# GEMM K-loops: loop-carried scalar pointer/counter updates and the exit compare moved from the head of the load segment into the preceding MFMA block (back-edge rotation)
# baseline (speedup 1.0000x reference)
; #define PG8_STAGE(bufoff, gbase, voff) do { _Pragma("unroll") for (int _i = 0; _i < 2; ++_i) \
;         __builtin_amdgcn_global_load_lds((const unsigned*)((const char*)(gbase) + (voff)[_i]), (LAS unsigned*)(lds + (bufoff) + ldsw + _i * 8192), 16, 0, 0); } while (0)
; #define PG8_LDA(dst, b, h) do { _Pragma("unroll") for (int m = 0; m < 4; ++m) _Pragma("unroll") for (int k = 0; k < 2; ++k) dst[m][k] = *(const LAS bf16x8*)(lds + PG8_SA(b, h) + aoff + m * 2048 + k * 1024); } while (0)
; #define PG8_LDB(dst, b, h) do { _Pragma("unroll") for (int n = 0; n < 2; ++n) _Pragma("unroll") for (int k = 0; k < 2; ++k) dst[n][k] = *(const LAS bf16x8*)(lds + PG8_SB(b, h) + boff + n * 2048 + k * 1024); } while (0)
; #define PG8_MMA(ai, bj, At, Bt) do { __builtin_amdgcn_s_setprio(1); _Pragma("unroll") for (int m = 0; m < 4; ++m) _Pragma("unroll") for (int n = 0; n < 2; ++n) _Pragma("unroll") for (int k = 0; k < 2; ++k) \
;         acc[ai][bj][m][n] = __builtin_amdgcn_mfma_f32_16x16x32_bf16(Bt[n][k], At[m][k], acc[ai][bj][m][n], 0, 0, 0); __builtin_amdgcn_s_setprio(0); } while (0)
; #define PG8_WAIT_V(n) asm volatile("s_waitcnt vmcnt(" #n ")" ::: "memory")
; #define PG8_BAR __builtin_amdgcn_s_barrier()
; template <class Epi, class Sched, bool ALIGN_EPI = true, bool SP2 = true>
; __device__ __forceinline__ void gemm_phase(LAS unsigned char* lds, const bf16_t* Ag, const bf16_t* Btg, const int K, const int lda, const int ldb, const Sched& S, const Epi& E) {
;     ...
;         for (int t = 0; t < nt; t += 2) {
;             const bool last = (t == nt - 2);
;             const char* a1 = cA + (size_t)(t + 1) * kstep;
;             const char* a2 = last ? nA : cA + (size_t)(t + 2) * kstep; const char* b2 = last ? nB : cB + (size_t)(t + 2) * kstep;
;             const char* a3 = a2 + kstep; const char* b3 = b2 + kstep;
;             if constexpr (SP2) {
;             PG8_LDB(B0, 0, 0); PG8_LDB(B1, 0, 1); PG8_SCHED; PG8_LDA(At, 0, 0); PG8_STAGE(PG8_SA(1, 1), a1 + hstepA, voffA);
;             PG8_WAIT_V(8); PG8_WAIT_L(0); PG8_BAR; PG8_MMA(0, 0, At, B0); PG8_MMA(0, 1, At, B1); PG8_BAR; PG8_SCHED;
;             PG8_LDA(At, 0, 1); PG8_STAGE(PG8_SB(0, 0), b2, voffB); PG8_STAGE(PG8_SB(0, 1), b2 + hstepB, voffB); PG8_STAGE(PG8_SA(0, 0), a2, voffA);
;             PG8_WAIT_V(8); PG8_WAIT_L(0); PG8_BAR; PG8_MMA(1, 0, At, B0); PG8_MMA(1, 1, At, B1); PG8_BAR; PG8_SCHED;
.LBB0_119:
	ds_read_b128 v[152:155], v149
	ds_read_b128 v[156:159], v149 offset:1024
	ds_read_b128 v[160:163], v149 offset:2048
	ds_read_b128 v[164:167], v149 offset:3072
	ds_read_b128 v[168:171], v150
	ds_read_b128 v[172:175], v150 offset:1024
	ds_read_b128 v[178:181], v150 offset:2048
	ds_read_b128 v[182:185], v150 offset:3072
	s_add_u32 s10, s34, 0xfff80080
	s_addc_u32 s11, s35, -1
	s_cmp_eq_u32 s60, 28
	s_cselect_b32 s51, s8, s11
	s_cselect_b32 s50, s9, s10
	s_cselect_b32 s39, s33, s59
	s_cselect_b32 s38, s6, s7
	v_lshl_add_u64 v[146:147], s[34:35], 0, v[138:139]
	s_add_i32 m0, s46, 0xc000
	ds_read_b128 v[186:189], v151
	ds_read_b128 v[190:193], v151 offset:1024
	ds_read_b128 v[194:197], v151 offset:2048
	ds_read_b128 v[198:201], v151 offset:3072
	ds_read_b128 v[202:205], v151 offset:4096
	ds_read_b128 v[206:209], v151 offset:5120
	ds_read_b128 v[210:213], v151 offset:6144
	ds_read_b128 v[214:217], v151 offset:7168
	global_load_lds_dwordx4 v[146:147], off
	v_lshl_add_u64 v[146:147], s[34:35], 0, v[140:141]
	s_add_i32 m0, s46, 0xe000
	s_nop 0
	global_load_lds_dwordx4 v[146:147], off
	s_waitcnt vmcnt(8)
	s_waitcnt lgkmcnt(0)
	s_barrier
	s_setprio 1
	s_waitcnt lgkmcnt(0)
	v_mfma_f32_16x16x32_bf16 v[124:127], v[152:155], v[186:189], v[124:127]
	v_mfma_f32_16x16x32_bf16 v[116:119], v[160:163], v[186:189], v[116:119]
	v_mfma_f32_16x16x32_bf16 v[108:111], v[152:155], v[194:197], v[108:111]
	v_mfma_f32_16x16x32_bf16 v[100:103], v[160:163], v[194:197], v[100:103]
	v_mfma_f32_16x16x32_bf16 v[92:95], v[152:155], v[202:205], v[92:95]
	v_mfma_f32_16x16x32_bf16 v[84:87], v[160:163], v[202:205], v[84:87]
	v_mfma_f32_16x16x32_bf16 v[76:79], v[152:155], v[210:213], v[76:79]
	v_mfma_f32_16x16x32_bf16 v[68:71], v[160:163], v[210:213], v[68:71]
	v_mfma_f32_16x16x32_bf16 v[124:127], v[156:159], v[190:193], v[124:127]
	v_mfma_f32_16x16x32_bf16 v[116:119], v[164:167], v[190:193], v[116:119]
	v_mfma_f32_16x16x32_bf16 v[108:111], v[156:159], v[198:201], v[108:111]
	v_mfma_f32_16x16x32_bf16 v[100:103], v[164:167], v[198:201], v[100:103]
	v_mfma_f32_16x16x32_bf16 v[92:95], v[156:159], v[206:209], v[92:95]
	v_mfma_f32_16x16x32_bf16 v[84:87], v[164:167], v[206:209], v[84:87]
	v_mfma_f32_16x16x32_bf16 v[76:79], v[156:159], v[214:217], v[76:79]
	v_mfma_f32_16x16x32_bf16 v[68:71], v[164:167], v[214:217], v[68:71]
	s_setprio 0
	s_setprio 1
	v_mfma_f32_16x16x32_bf16 v[120:123], v[168:171], v[186:189], v[120:123]
	v_mfma_f32_16x16x32_bf16 v[112:115], v[178:181], v[186:189], v[112:115]
	v_mfma_f32_16x16x32_bf16 v[104:107], v[168:171], v[194:197], v[104:107]
	v_mfma_f32_16x16x32_bf16 v[96:99], v[178:181], v[194:197], v[96:99]
	v_mfma_f32_16x16x32_bf16 v[88:91], v[168:171], v[202:205], v[88:91]
	v_mfma_f32_16x16x32_bf16 v[80:83], v[178:181], v[202:205], v[80:83]
	v_mfma_f32_16x16x32_bf16 v[72:75], v[168:171], v[210:213], v[72:75]
	v_mfma_f32_16x16x32_bf16 v[64:67], v[178:181], v[210:213], v[64:67]
	v_mfma_f32_16x16x32_bf16 v[120:123], v[172:175], v[190:193], v[120:123]
	v_mfma_f32_16x16x32_bf16 v[112:115], v[182:185], v[190:193], v[112:115]
	v_mfma_f32_16x16x32_bf16 v[104:107], v[172:175], v[198:201], v[104:107]
	v_mfma_f32_16x16x32_bf16 v[96:99], v[182:185], v[198:201], v[96:99]
	v_mfma_f32_16x16x32_bf16 v[88:91], v[172:175], v[206:209], v[88:91]
	v_mfma_f32_16x16x32_bf16 v[80:83], v[182:185], v[206:209], v[80:83]
	s_setprio 2
	s_barrier
	v_mfma_f32_16x16x32_bf16 v[72:75], v[172:175], v[214:217], v[72:75]
	v_mfma_f32_16x16x32_bf16 v[64:67], v[182:185], v[214:217], v[64:67]
	s_setprio 0
	s_add_i32 s10, s57, s37
	v_lshl_add_u64 v[146:147], s[38:39], 0, v[132:133]
	s_mov_b32 m0, s10
	ds_read_b128 v[186:189], v151 offset:16384
	ds_read_b128 v[190:193], v151 offset:17408
	ds_read_b128 v[194:197], v151 offset:18432
	ds_read_b128 v[198:201], v151 offset:19456
	ds_read_b128 v[202:205], v151 offset:20480
	ds_read_b128 v[206:209], v151 offset:21504
	ds_read_b128 v[210:213], v151 offset:22528
	ds_read_b128 v[214:217], v151 offset:23552
	global_load_lds_dwordx4 v[146:147], off
	s_add_i32 m0, s10, 0x2000
	s_add_u32 s62, s38, 0x80000
	v_lshl_add_u64 v[218:219], s[38:39], 0, v[128:129]
	s_addc_u32 s63, s39, 0
	s_add_i32 s10, s58, s37
	global_load_lds_dwordx4 v[218:219], off
	v_lshl_add_u64 v[220:221], s[62:63], 0, v[132:133]
	s_mov_b32 m0, s10
	v_lshl_add_u64 v[222:223], s[50:51], 0, v[130:131]
	global_load_lds_dwordx4 v[220:221], off
	v_lshl_add_u64 v[220:221], s[62:63], 0, v[128:129]
	s_add_i32 m0, s10, 0x2000
	s_nop 0
	global_load_lds_dwordx4 v[220:221], off
	v_lshl_add_u64 v[220:221], s[50:51], 0, v[134:135]
	s_mov_b32 m0, s46
	s_nop 0
	global_load_lds_dwordx4 v[220:221], off
	s_mov_b32 m0, s47
	s_nop 0
	global_load_lds_dwordx4 v[222:223], off
	s_waitcnt vmcnt(8)
	s_waitcnt lgkmcnt(0)
	s_barrier
; #define PG8_STAGE(bufoff, gbase, voff) do { _Pragma("unroll") for (int _i = 0; _i < 2; ++_i) \
;         __builtin_amdgcn_global_load_lds((const unsigned*)((const char*)(gbase) + (voff)[_i]), (LAS unsigned*)(lds + (bufoff) + ldsw + _i * 8192), 16, 0, 0); } while (0)
; #define PG8_LDA(dst, b, h) do { _Pragma("unroll") for (int m = 0; m < 4; ++m) _Pragma("unroll") for (int k = 0; k < 2; ++k) dst[m][k] = *(const LAS bf16x8*)(lds + PG8_SA(b, h) + aoff + m * 2048 + k * 1024); } while (0)
; #define PG8_LDB(dst, b, h) do { _Pragma("unroll") for (int n = 0; n < 2; ++n) _Pragma("unroll") for (int k = 0; k < 2; ++k) dst[n][k] = *(const LAS bf16x8*)(lds + PG8_SB(b, h) + boff + n * 2048 + k * 1024); } while (0)
; #define PG8_MMA(ai, bj, At, Bt) do { __builtin_amdgcn_s_setprio(1); _Pragma("unroll") for (int m = 0; m < 4; ++m) _Pragma("unroll") for (int n = 0; n < 2; ++n) _Pragma("unroll") for (int k = 0; k < 2; ++k) \
;         acc[ai][bj][m][n] = __builtin_amdgcn_mfma_f32_16x16x32_bf16(Bt[n][k], At[m][k], acc[ai][bj][m][n], 0, 0, 0); __builtin_amdgcn_s_setprio(0); } while (0)
; #define PG8_WAIT_V(n) asm volatile("s_waitcnt vmcnt(" #n ")" ::: "memory")
; #define PG8_WAIT_L(n) asm volatile("s_waitcnt lgkmcnt(" #n ")" ::: "memory")
; #define PG8_BAR __builtin_amdgcn_s_barrier()
; #define PG8_SCHED __builtin_amdgcn_sched_barrier(0)
; template <class Epi, class Sched, bool ALIGN_EPI = true, bool SP2 = true>
; __device__ __forceinline__ void gemm_phase(LAS unsigned char* lds, const bf16_t* Ag, const bf16_t* Btg, const int K, const int lda, const int ldb, const Sched& S, const Epi& E) {
;     ...
;             PG8_WAIT_V(8); PG8_WAIT_L(0); PG8_BAR; PG8_MMA(1, 0, At, B0); PG8_MMA(1, 1, At, B1); PG8_BAR; PG8_SCHED;
;             PG8_LDB(B0, 1, 0); PG8_LDB(B1, 1, 1); PG8_SCHED; PG8_LDA(At, 1, 0); PG8_STAGE(PG8_SA(0, 1), a2 + hstepA, voffA);
;             PG8_WAIT_V(8); PG8_WAIT_L(0); PG8_BAR; PG8_MMA(0, 0, At, B0); PG8_MMA(0, 1, At, B1); PG8_BAR; PG8_SCHED;
	s_setprio 1
	s_waitcnt lgkmcnt(0)
	v_mfma_f32_16x16x32_bf16 v[60:63], v[152:155], v[186:189], v[60:63]
	v_mfma_f32_16x16x32_bf16 v[52:55], v[160:163], v[186:189], v[52:55]
	v_mfma_f32_16x16x32_bf16 v[44:47], v[152:155], v[194:197], v[44:47]
	v_mfma_f32_16x16x32_bf16 v[36:39], v[160:163], v[194:197], v[36:39]
	v_mfma_f32_16x16x32_bf16 v[28:31], v[152:155], v[202:205], v[28:31]
	v_mfma_f32_16x16x32_bf16 v[20:23], v[160:163], v[202:205], v[20:23]
	v_mfma_f32_16x16x32_bf16 v[12:15], v[152:155], v[210:213], v[12:15]
	v_mfma_f32_16x16x32_bf16 v[4:7], v[160:163], v[210:213], v[4:7]
	v_mfma_f32_16x16x32_bf16 v[60:63], v[156:159], v[190:193], v[60:63]
	v_mfma_f32_16x16x32_bf16 v[52:55], v[164:167], v[190:193], v[52:55]
	v_mfma_f32_16x16x32_bf16 v[44:47], v[156:159], v[198:201], v[44:47]
	v_mfma_f32_16x16x32_bf16 v[36:39], v[164:167], v[198:201], v[36:39]
	v_mfma_f32_16x16x32_bf16 v[28:31], v[156:159], v[206:209], v[28:31]
	v_mfma_f32_16x16x32_bf16 v[20:23], v[164:167], v[206:209], v[20:23]
	v_mfma_f32_16x16x32_bf16 v[12:15], v[156:159], v[214:217], v[12:15]
	v_mfma_f32_16x16x32_bf16 v[4:7], v[164:167], v[214:217], v[4:7]
	s_setprio 0
	s_setprio 1
	v_mfma_f32_16x16x32_bf16 v[56:59], v[168:171], v[186:189], v[56:59]
	v_mfma_f32_16x16x32_bf16 v[48:51], v[178:181], v[186:189], v[48:51]
	v_mfma_f32_16x16x32_bf16 v[40:43], v[168:171], v[194:197], v[40:43]
	v_mfma_f32_16x16x32_bf16 v[32:35], v[178:181], v[194:197], v[32:35]
	v_mfma_f32_16x16x32_bf16 v[24:27], v[168:171], v[202:205], v[24:27]
	v_mfma_f32_16x16x32_bf16 v[16:19], v[178:181], v[202:205], v[16:19]
	v_mfma_f32_16x16x32_bf16 v[8:11], v[168:171], v[210:213], v[8:11]
	v_mfma_f32_16x16x32_bf16 v[0:3], v[178:181], v[210:213], v[0:3]
	v_mfma_f32_16x16x32_bf16 v[56:59], v[172:175], v[190:193], v[56:59]
	v_mfma_f32_16x16x32_bf16 v[48:51], v[182:185], v[190:193], v[48:51]
	v_mfma_f32_16x16x32_bf16 v[40:43], v[172:175], v[198:201], v[40:43]
	v_mfma_f32_16x16x32_bf16 v[32:35], v[182:185], v[198:201], v[32:35]
	v_mfma_f32_16x16x32_bf16 v[24:27], v[172:175], v[206:209], v[24:27]
	v_mfma_f32_16x16x32_bf16 v[16:19], v[182:185], v[206:209], v[16:19]
	s_setprio 2
	s_barrier
	v_mfma_f32_16x16x32_bf16 v[8:11], v[172:175], v[214:217], v[8:11]
	v_mfma_f32_16x16x32_bf16 v[0:3], v[182:185], v[214:217], v[0:3]
	s_setprio 0
	s_add_i32 s10, 0, 0x18000
	s_add_i32 s11, 0, 0x1c000
	v_add_u32_e32 v164, s10, v148
	v_add_u32_e32 v182, s11, v148
	ds_read_b128 v[152:155], v164
	ds_read_b128 v[156:159], v164 offset:1024
	ds_read_b128 v[160:163], v164 offset:2048
	ds_read_b128 v[164:167], v164 offset:3072
	ds_read_b128 v[168:171], v182
	ds_read_b128 v[172:175], v182 offset:1024
	ds_read_b128 v[178:181], v182 offset:2048
	ds_read_b128 v[182:185], v182 offset:3072
	s_add_u32 s50, s50, 0x80000
	s_addc_u32 s51, s51, 0
	s_mov_b32 m0, s52
	v_lshl_add_u64 v[224:225], s[50:51], 0, v[134:135]
	ds_read_b128 v[186:189], v151 offset:32768
	ds_read_b128 v[190:193], v151 offset:33792
	ds_read_b128 v[194:197], v151 offset:34816
	ds_read_b128 v[198:201], v151 offset:35840
	ds_read_b128 v[202:205], v151 offset:36864
	ds_read_b128 v[206:209], v151 offset:37888
	ds_read_b128 v[210:213], v151 offset:38912
	ds_read_b128 v[214:217], v151 offset:39936
	global_load_lds_dwordx4 v[224:225], off
	v_lshl_add_u64 v[224:225], s[50:51], 0, v[130:131]
	s_mov_b32 m0, s53
	s_nop 0
	global_load_lds_dwordx4 v[224:225], off
	s_waitcnt vmcnt(8)
	s_waitcnt lgkmcnt(0)
	s_barrier
	s_setprio 1
	s_waitcnt lgkmcnt(0)
	v_mfma_f32_16x16x32_bf16 v[124:127], v[152:155], v[186:189], v[124:127]
	v_mfma_f32_16x16x32_bf16 v[116:119], v[160:163], v[186:189], v[116:119]
	v_mfma_f32_16x16x32_bf16 v[108:111], v[152:155], v[194:197], v[108:111]
	v_mfma_f32_16x16x32_bf16 v[100:103], v[160:163], v[194:197], v[100:103]
	v_mfma_f32_16x16x32_bf16 v[92:95], v[152:155], v[202:205], v[92:95]
	v_mfma_f32_16x16x32_bf16 v[84:87], v[160:163], v[202:205], v[84:87]
	v_mfma_f32_16x16x32_bf16 v[76:79], v[152:155], v[210:213], v[76:79]
	v_mfma_f32_16x16x32_bf16 v[68:71], v[160:163], v[210:213], v[68:71]
	v_mfma_f32_16x16x32_bf16 v[124:127], v[156:159], v[190:193], v[124:127]
	v_mfma_f32_16x16x32_bf16 v[116:119], v[164:167], v[190:193], v[116:119]
	v_mfma_f32_16x16x32_bf16 v[108:111], v[156:159], v[198:201], v[108:111]
	v_mfma_f32_16x16x32_bf16 v[100:103], v[164:167], v[198:201], v[100:103]
	v_mfma_f32_16x16x32_bf16 v[92:95], v[156:159], v[206:209], v[92:95]
	v_mfma_f32_16x16x32_bf16 v[84:87], v[164:167], v[206:209], v[84:87]
	v_mfma_f32_16x16x32_bf16 v[76:79], v[156:159], v[214:217], v[76:79]
	v_mfma_f32_16x16x32_bf16 v[68:71], v[164:167], v[214:217], v[68:71]
	s_setprio 0
	s_setprio 1
	v_mfma_f32_16x16x32_bf16 v[120:123], v[168:171], v[186:189], v[120:123]
	v_mfma_f32_16x16x32_bf16 v[112:115], v[178:181], v[186:189], v[112:115]
	v_mfma_f32_16x16x32_bf16 v[104:107], v[168:171], v[194:197], v[104:107]
	v_mfma_f32_16x16x32_bf16 v[96:99], v[178:181], v[194:197], v[96:99]
	v_mfma_f32_16x16x32_bf16 v[88:91], v[168:171], v[202:205], v[88:91]
	v_mfma_f32_16x16x32_bf16 v[80:83], v[178:181], v[202:205], v[80:83]
	v_mfma_f32_16x16x32_bf16 v[72:75], v[168:171], v[210:213], v[72:75]
	v_mfma_f32_16x16x32_bf16 v[64:67], v[178:181], v[210:213], v[64:67]
	v_mfma_f32_16x16x32_bf16 v[120:123], v[172:175], v[190:193], v[120:123]
	v_mfma_f32_16x16x32_bf16 v[112:115], v[182:185], v[190:193], v[112:115]
	v_mfma_f32_16x16x32_bf16 v[104:107], v[172:175], v[198:201], v[104:107]
	v_mfma_f32_16x16x32_bf16 v[96:99], v[182:185], v[198:201], v[96:99]
	v_mfma_f32_16x16x32_bf16 v[88:91], v[172:175], v[206:209], v[88:91]
	v_mfma_f32_16x16x32_bf16 v[80:83], v[182:185], v[206:209], v[80:83]
	s_setprio 2
	s_barrier
; #define PG8_STAGE(bufoff, gbase, voff) do { _Pragma("unroll") for (int _i = 0; _i < 2; ++_i) \
;         __builtin_amdgcn_global_load_lds((const unsigned*)((const char*)(gbase) + (voff)[_i]), (LAS unsigned*)(lds + (bufoff) + ldsw + _i * 8192), 16, 0, 0); } while (0)
; #define PG8_LDA(dst, b, h) do { _Pragma("unroll") for (int m = 0; m < 4; ++m) _Pragma("unroll") for (int k = 0; k < 2; ++k) dst[m][k] = *(const LAS bf16x8*)(lds + PG8_SA(b, h) + aoff + m * 2048 + k * 1024); } while (0)
; #define PG8_MMA(ai, bj, At, Bt) do { __builtin_amdgcn_s_setprio(1); _Pragma("unroll") for (int m = 0; m < 4; ++m) _Pragma("unroll") for (int n = 0; n < 2; ++n) _Pragma("unroll") for (int k = 0; k < 2; ++k) \
;         acc[ai][bj][m][n] = __builtin_amdgcn_mfma_f32_16x16x32_bf16(Bt[n][k], At[m][k], acc[ai][bj][m][n], 0, 0, 0); __builtin_amdgcn_s_setprio(0); } while (0)
; #define PG8_WAIT_V(n) asm volatile("s_waitcnt vmcnt(" #n ")" ::: "memory")
; #define PG8_WAIT_L(n) asm volatile("s_waitcnt lgkmcnt(" #n ")" ::: "memory")
; #define PG8_BAR __builtin_amdgcn_s_barrier()
; #define PG8_SCHED __builtin_amdgcn_sched_barrier(0)
; template <class Epi, class Sched, bool ALIGN_EPI = true, bool SP2 = true>
; __device__ __forceinline__ void gemm_phase(LAS unsigned char* lds, const bf16_t* Ag, const bf16_t* Btg, const int K, const int lda, const int ldb, const Sched& S, const Epi& E) {
;     ...
;         for (int t = 0; t < nt; t += 2) {
;     ...
;             PG8_WAIT_V(8); PG8_WAIT_L(0); PG8_BAR; PG8_MMA(0, 0, At, B0); PG8_MMA(0, 1, At, B1); PG8_BAR; PG8_SCHED;
;             PG8_LDA(At, 1, 1); PG8_STAGE(PG8_SB(1, 0), b3, voffB); PG8_STAGE(PG8_SB(1, 1), b3 + hstepB, voffB); PG8_STAGE(PG8_SA(1, 0), a3, voffA);
;             PG8_WAIT_V(8); PG8_WAIT_L(0); PG8_BAR; PG8_MMA(1, 0, At, B0); PG8_MMA(1, 1, At, B1); PG8_BAR; PG8_SCHED;
	v_mfma_f32_16x16x32_bf16 v[72:75], v[172:175], v[214:217], v[72:75]
	v_mfma_f32_16x16x32_bf16 v[64:67], v[182:185], v[214:217], v[64:67]
	s_setprio 0
	s_add_i32 s10, s10, s37
	v_lshl_add_u64 v[146:147], v[146:147], 0, s[16:17]
	s_mov_b32 m0, s10
	ds_read_b128 v[186:189], v151 offset:49152
	ds_read_b128 v[190:193], v151 offset:50176
	ds_read_b128 v[194:197], v151 offset:51200
	ds_read_b128 v[198:201], v151 offset:52224
	ds_read_b128 v[202:205], v151 offset:53248
	ds_read_b128 v[206:209], v151 offset:54272
	ds_read_b128 v[210:213], v151 offset:55296
	ds_read_b128 v[214:217], v151 offset:56320
	global_load_lds_dwordx4 v[146:147], off
	s_add_i32 m0, s10, 0x2000
	s_add_u32 s38, s38, 0x80080
	v_lshl_add_u64 v[146:147], v[218:219], 0, s[16:17]
	s_addc_u32 s39, s39, 0
	s_add_i32 s10, s11, s37
	global_load_lds_dwordx4 v[146:147], off
	v_lshl_add_u64 v[146:147], s[38:39], 0, v[132:133]
	s_mov_b32 m0, s10
	s_nop 0
	global_load_lds_dwordx4 v[146:147], off
	v_lshl_add_u64 v[146:147], s[38:39], 0, v[128:129]
	s_add_i32 m0, s10, 0x2000
	s_nop 0
	global_load_lds_dwordx4 v[146:147], off
	v_lshl_add_u64 v[146:147], v[220:221], 0, s[16:17]
	s_mov_b32 m0, s54
	s_nop 0
	global_load_lds_dwordx4 v[146:147], off
	v_lshl_add_u64 v[146:147], v[222:223], 0, s[16:17]
	s_mov_b32 m0, s55
	s_nop 0
	global_load_lds_dwordx4 v[146:147], off
	s_waitcnt vmcnt(8)
	s_waitcnt lgkmcnt(0)
	s_barrier
	s_setprio 1
	s_waitcnt lgkmcnt(0)
	v_mfma_f32_16x16x32_bf16 v[60:63], v[152:155], v[186:189], v[60:63]
	s_add_i32 s60, s60, 2
	s_add_u32 s34, s34, 0x100
	s_addc_u32 s35, s35, 0
	s_add_u32 s7, s7, 0x100
	s_addc_u32 s59, s59, 0
	s_cmp_gt_u32 s60, 29
	v_mfma_f32_16x16x32_bf16 v[52:55], v[160:163], v[186:189], v[52:55]
	v_mfma_f32_16x16x32_bf16 v[44:47], v[152:155], v[194:197], v[44:47]
	v_mfma_f32_16x16x32_bf16 v[36:39], v[160:163], v[194:197], v[36:39]
	v_mfma_f32_16x16x32_bf16 v[28:31], v[152:155], v[202:205], v[28:31]
	v_mfma_f32_16x16x32_bf16 v[20:23], v[160:163], v[202:205], v[20:23]
	v_mfma_f32_16x16x32_bf16 v[12:15], v[152:155], v[210:213], v[12:15]
	v_mfma_f32_16x16x32_bf16 v[4:7], v[160:163], v[210:213], v[4:7]
	v_mfma_f32_16x16x32_bf16 v[60:63], v[156:159], v[190:193], v[60:63]
	v_mfma_f32_16x16x32_bf16 v[52:55], v[164:167], v[190:193], v[52:55]
	v_mfma_f32_16x16x32_bf16 v[44:47], v[156:159], v[198:201], v[44:47]
	v_mfma_f32_16x16x32_bf16 v[36:39], v[164:167], v[198:201], v[36:39]
	v_mfma_f32_16x16x32_bf16 v[28:31], v[156:159], v[206:209], v[28:31]
	v_mfma_f32_16x16x32_bf16 v[20:23], v[164:167], v[206:209], v[20:23]
	v_mfma_f32_16x16x32_bf16 v[12:15], v[156:159], v[214:217], v[12:15]
	v_mfma_f32_16x16x32_bf16 v[4:7], v[164:167], v[214:217], v[4:7]
	s_setprio 0
	s_setprio 1
	v_mfma_f32_16x16x32_bf16 v[56:59], v[168:171], v[186:189], v[56:59]
	v_mfma_f32_16x16x32_bf16 v[48:51], v[178:181], v[186:189], v[48:51]
	v_mfma_f32_16x16x32_bf16 v[40:43], v[168:171], v[194:197], v[40:43]
	v_mfma_f32_16x16x32_bf16 v[32:35], v[178:181], v[194:197], v[32:35]
	v_mfma_f32_16x16x32_bf16 v[24:27], v[168:171], v[202:205], v[24:27]
	v_mfma_f32_16x16x32_bf16 v[16:19], v[178:181], v[202:205], v[16:19]
	v_mfma_f32_16x16x32_bf16 v[8:11], v[168:171], v[210:213], v[8:11]
	v_mfma_f32_16x16x32_bf16 v[0:3], v[178:181], v[210:213], v[0:3]
	v_mfma_f32_16x16x32_bf16 v[56:59], v[172:175], v[190:193], v[56:59]
	v_mfma_f32_16x16x32_bf16 v[48:51], v[182:185], v[190:193], v[48:51]
	v_mfma_f32_16x16x32_bf16 v[40:43], v[172:175], v[198:201], v[40:43]
	v_mfma_f32_16x16x32_bf16 v[32:35], v[182:185], v[198:201], v[32:35]
	v_mfma_f32_16x16x32_bf16 v[24:27], v[172:175], v[206:209], v[24:27]
	v_mfma_f32_16x16x32_bf16 v[16:19], v[182:185], v[206:209], v[16:19]
	s_setprio 2
	s_barrier
	v_mfma_f32_16x16x32_bf16 v[8:11], v[172:175], v[214:217], v[8:11]
	v_mfma_f32_16x16x32_bf16 v[0:3], v[182:185], v[214:217], v[0:3]
	s_setprio 0
	s_cbranch_scc0 .LBB0_119
	s_and_b64 vcc, exec, s[18:19]
	s_cbranch_vccz .LBB0_122
	s_barrier

; #define PG8_STAGE(bufoff, gbase, voff) do { _Pragma("unroll") for (int _i = 0; _i < 2; ++_i) \
;         __builtin_amdgcn_global_load_lds((const unsigned*)((const char*)(gbase) + (voff)[_i]), (LAS unsigned*)(lds + (bufoff) + ldsw + _i * 8192), 16, 0, 0); } while (0)
; #define PG8_LDA(dst, b, h) do { _Pragma("unroll") for (int m = 0; m < 4; ++m) _Pragma("unroll") for (int k = 0; k < 2; ++k) dst[m][k] = *(const LAS bf16x8*)(lds + PG8_SA(b, h) + aoff + m * 2048 + k * 1024); } while (0)
; #define PG8_LDB(dst, b, h) do { _Pragma("unroll") for (int n = 0; n < 2; ++n) _Pragma("unroll") for (int k = 0; k < 2; ++k) dst[n][k] = *(const LAS bf16x8*)(lds + PG8_SB(b, h) + boff + n * 2048 + k * 1024); } while (0)
; #define PG8_MMA(ai, bj, At, Bt) do { __builtin_amdgcn_s_setprio(1); _Pragma("unroll") for (int m = 0; m < 4; ++m) _Pragma("unroll") for (int n = 0; n < 2; ++n) _Pragma("unroll") for (int k = 0; k < 2; ++k) \
;         acc[ai][bj][m][n] = __builtin_amdgcn_mfma_f32_16x16x32_bf16(Bt[n][k], At[m][k], acc[ai][bj][m][n], 0, 0, 0); __builtin_amdgcn_s_setprio(0); } while (0)
; #define PG8_WAIT_V(n) asm volatile("s_waitcnt vmcnt(" #n ")" ::: "memory")
; #define PG8_BAR __builtin_amdgcn_s_barrier()
; template <class Epi, class Sched, bool ALIGN_EPI = true, bool SP2 = true>
; __device__ __forceinline__ void gemm_phase(LAS unsigned char* lds, const bf16_t* Ag, const bf16_t* Btg, const int K, const int lda, const int ldb, const Sched& S, const Epi& E) {
;     ...
;         for (int t = 0; t < nt; t += 2) {
;             const bool last = (t == nt - 2);
;             const char* a1 = cA + (size_t)(t + 1) * kstep;
;             const char* a2 = last ? nA : cA + (size_t)(t + 2) * kstep; const char* b2 = last ? nB : cB + (size_t)(t + 2) * kstep;
;             const char* a3 = a2 + kstep; const char* b3 = b2 + kstep;
;             if constexpr (SP2) {
;             PG8_LDB(B0, 0, 0); PG8_LDB(B1, 0, 1); PG8_SCHED; PG8_LDA(At, 0, 0); PG8_STAGE(PG8_SA(1, 1), a1 + hstepA, voffA);
;             PG8_WAIT_V(8); PG8_WAIT_L(0); PG8_BAR; PG8_MMA(0, 0, At, B0); PG8_MMA(0, 1, At, B1); PG8_BAR; PG8_SCHED;
;             PG8_LDA(At, 0, 1); PG8_STAGE(PG8_SB(0, 0), b2, voffB); PG8_STAGE(PG8_SB(0, 1), b2 + hstepB, voffB); PG8_STAGE(PG8_SA(0, 0), a2, voffA);
;             PG8_WAIT_V(8); PG8_WAIT_L(0); PG8_BAR; PG8_MMA(1, 0, At, B0); PG8_MMA(1, 1, At, B1); PG8_BAR; PG8_SCHED;
.LBB0_199:
	ds_read_b128 v[146:149], v151
	ds_read_b128 v[154:157], v151 offset:1024
	ds_read_b128 v[158:161], v151 offset:2048
	ds_read_b128 v[162:165], v151 offset:3072
	ds_read_b128 v[166:169], v152
	ds_read_b128 v[170:173], v152 offset:1024
	ds_read_b128 v[178:181], v152 offset:2048
	ds_read_b128 v[182:185], v152 offset:3072
	s_add_u32 s1, s84, 0xffea0080
	s_addc_u32 s10, s85, -1
	s_cmpk_eq_i32 s0, 0x54
	s_cselect_b32 s71, vcc_lo, s10
	s_cselect_b32 s70, vcc_hi, s1
	s_cselect_b32 s67, s6, s73
	s_cselect_b32 s66, s7, s72
	v_lshl_add_u64 v[174:175], s[84:85], 0, v[138:139]
	s_add_i32 m0, s40, 0xc000
	ds_read_b128 v[186:189], v153
	ds_read_b128 v[190:193], v153 offset:1024
	ds_read_b128 v[194:197], v153 offset:2048
	ds_read_b128 v[198:201], v153 offset:3072
	ds_read_b128 v[202:205], v153 offset:4096
	ds_read_b128 v[206:209], v153 offset:5120
	ds_read_b128 v[210:213], v153 offset:6144
	ds_read_b128 v[214:217], v153 offset:7168
	global_load_lds_dwordx4 v[174:175], off
	v_lshl_add_u64 v[174:175], s[84:85], 0, v[140:141]
	s_add_i32 m0, s40, 0xe000
	s_nop 0
	global_load_lds_dwordx4 v[174:175], off
	s_waitcnt vmcnt(8)
	s_waitcnt lgkmcnt(0)
	s_barrier
	s_setprio 1
	s_waitcnt lgkmcnt(0)
	v_mfma_f32_16x16x32_bf16 v[124:127], v[146:149], v[186:189], v[124:127]
	v_mfma_f32_16x16x32_bf16 v[120:123], v[158:161], v[186:189], v[120:123]
	v_mfma_f32_16x16x32_bf16 v[116:119], v[146:149], v[194:197], v[116:119]
	v_mfma_f32_16x16x32_bf16 v[104:107], v[158:161], v[194:197], v[104:107]
	v_mfma_f32_16x16x32_bf16 v[100:103], v[146:149], v[202:205], v[100:103]
	v_mfma_f32_16x16x32_bf16 v[88:91], v[158:161], v[202:205], v[88:91]
	v_mfma_f32_16x16x32_bf16 v[84:87], v[146:149], v[210:213], v[84:87]
	v_mfma_f32_16x16x32_bf16 v[72:75], v[158:161], v[210:213], v[72:75]
	v_mfma_f32_16x16x32_bf16 v[124:127], v[154:157], v[190:193], v[124:127]
	v_mfma_f32_16x16x32_bf16 v[120:123], v[162:165], v[190:193], v[120:123]
	v_mfma_f32_16x16x32_bf16 v[116:119], v[154:157], v[198:201], v[116:119]
	v_mfma_f32_16x16x32_bf16 v[104:107], v[162:165], v[198:201], v[104:107]
	v_mfma_f32_16x16x32_bf16 v[100:103], v[154:157], v[206:209], v[100:103]
	v_mfma_f32_16x16x32_bf16 v[88:91], v[162:165], v[206:209], v[88:91]
	v_mfma_f32_16x16x32_bf16 v[84:87], v[154:157], v[214:217], v[84:87]
	v_mfma_f32_16x16x32_bf16 v[72:75], v[162:165], v[214:217], v[72:75]
	s_setprio 0
	s_setprio 1
	v_mfma_f32_16x16x32_bf16 v[112:115], v[166:169], v[186:189], v[112:115]
	v_mfma_f32_16x16x32_bf16 v[108:111], v[178:181], v[186:189], v[108:111]
	v_mfma_f32_16x16x32_bf16 v[96:99], v[166:169], v[194:197], v[96:99]
	v_mfma_f32_16x16x32_bf16 v[92:95], v[178:181], v[194:197], v[92:95]
	v_mfma_f32_16x16x32_bf16 v[80:83], v[166:169], v[202:205], v[80:83]
	v_mfma_f32_16x16x32_bf16 v[76:79], v[178:181], v[202:205], v[76:79]
	v_mfma_f32_16x16x32_bf16 v[68:71], v[166:169], v[210:213], v[68:71]
	v_mfma_f32_16x16x32_bf16 v[64:67], v[178:181], v[210:213], v[64:67]
	v_mfma_f32_16x16x32_bf16 v[112:115], v[170:173], v[190:193], v[112:115]
	v_mfma_f32_16x16x32_bf16 v[108:111], v[182:185], v[190:193], v[108:111]
	v_mfma_f32_16x16x32_bf16 v[96:99], v[170:173], v[198:201], v[96:99]
	v_mfma_f32_16x16x32_bf16 v[92:95], v[182:185], v[198:201], v[92:95]
	v_mfma_f32_16x16x32_bf16 v[80:83], v[170:173], v[206:209], v[80:83]
	v_mfma_f32_16x16x32_bf16 v[76:79], v[182:185], v[206:209], v[76:79]
	s_setprio 2
	s_barrier
	v_mfma_f32_16x16x32_bf16 v[68:71], v[170:173], v[214:217], v[68:71]
	v_mfma_f32_16x16x32_bf16 v[64:67], v[182:185], v[214:217], v[64:67]
	s_setprio 0
	s_add_i32 s1, s79, s37
	v_lshl_add_u64 v[174:175], s[66:67], 0, v[130:131]
	s_mov_b32 m0, s1
	ds_read_b128 v[186:189], v153 offset:16384
	ds_read_b128 v[190:193], v153 offset:17408
	ds_read_b128 v[194:197], v153 offset:18432
	ds_read_b128 v[198:201], v153 offset:19456
	ds_read_b128 v[202:205], v153 offset:20480
	ds_read_b128 v[206:209], v153 offset:21504
	ds_read_b128 v[210:213], v153 offset:22528
	ds_read_b128 v[214:217], v153 offset:23552
	global_load_lds_dwordx4 v[174:175], off
	s_add_i32 m0, s1, 0x2000
	s_add_u32 s10, s66, 0x160000
	v_lshl_add_u64 v[218:219], s[66:67], 0, v[134:135]
	s_addc_u32 s11, s67, 0
	s_add_i32 s1, s82, s37
	global_load_lds_dwordx4 v[218:219], off
	v_lshl_add_u64 v[220:221], s[10:11], 0, v[130:131]
	s_mov_b32 m0, s1
	v_lshl_add_u64 v[222:223], s[70:71], 0, v[132:133]
	global_load_lds_dwordx4 v[220:221], off
	v_lshl_add_u64 v[220:221], s[10:11], 0, v[134:135]
	s_add_i32 m0, s1, 0x2000
	s_nop 0
	global_load_lds_dwordx4 v[220:221], off
	v_lshl_add_u64 v[220:221], s[70:71], 0, v[128:129]
	s_mov_b32 m0, s40
	s_nop 0
	global_load_lds_dwordx4 v[220:221], off
	s_mov_b32 m0, s41
	s_nop 0
	global_load_lds_dwordx4 v[222:223], off
	s_waitcnt vmcnt(8)
	s_waitcnt lgkmcnt(0)
	s_barrier
; #define PG8_STAGE(bufoff, gbase, voff) do { _Pragma("unroll") for (int _i = 0; _i < 2; ++_i) \
;         __builtin_amdgcn_global_load_lds((const unsigned*)((const char*)(gbase) + (voff)[_i]), (LAS unsigned*)(lds + (bufoff) + ldsw + _i * 8192), 16, 0, 0); } while (0)
; #define PG8_LDA(dst, b, h) do { _Pragma("unroll") for (int m = 0; m < 4; ++m) _Pragma("unroll") for (int k = 0; k < 2; ++k) dst[m][k] = *(const LAS bf16x8*)(lds + PG8_SA(b, h) + aoff + m * 2048 + k * 1024); } while (0)
; #define PG8_LDB(dst, b, h) do { _Pragma("unroll") for (int n = 0; n < 2; ++n) _Pragma("unroll") for (int k = 0; k < 2; ++k) dst[n][k] = *(const LAS bf16x8*)(lds + PG8_SB(b, h) + boff + n * 2048 + k * 1024); } while (0)
; #define PG8_MMA(ai, bj, At, Bt) do { __builtin_amdgcn_s_setprio(1); _Pragma("unroll") for (int m = 0; m < 4; ++m) _Pragma("unroll") for (int n = 0; n < 2; ++n) _Pragma("unroll") for (int k = 0; k < 2; ++k) \
;         acc[ai][bj][m][n] = __builtin_amdgcn_mfma_f32_16x16x32_bf16(Bt[n][k], At[m][k], acc[ai][bj][m][n], 0, 0, 0); __builtin_amdgcn_s_setprio(0); } while (0)
; #define PG8_WAIT_V(n) asm volatile("s_waitcnt vmcnt(" #n ")" ::: "memory")
; #define PG8_WAIT_L(n) asm volatile("s_waitcnt lgkmcnt(" #n ")" ::: "memory")
; #define PG8_BAR __builtin_amdgcn_s_barrier()
; #define PG8_SCHED __builtin_amdgcn_sched_barrier(0)
; template <class Epi, class Sched, bool ALIGN_EPI = true, bool SP2 = true>
; __device__ __forceinline__ void gemm_phase(LAS unsigned char* lds, const bf16_t* Ag, const bf16_t* Btg, const int K, const int lda, const int ldb, const Sched& S, const Epi& E) {
;     ...
;             PG8_WAIT_V(8); PG8_WAIT_L(0); PG8_BAR; PG8_MMA(1, 0, At, B0); PG8_MMA(1, 1, At, B1); PG8_BAR; PG8_SCHED;
;             PG8_LDB(B0, 1, 0); PG8_LDB(B1, 1, 1); PG8_SCHED; PG8_LDA(At, 1, 0); PG8_STAGE(PG8_SA(0, 1), a2 + hstepA, voffA);
;             PG8_WAIT_V(8); PG8_WAIT_L(0); PG8_BAR; PG8_MMA(0, 0, At, B0); PG8_MMA(0, 1, At, B1); PG8_BAR; PG8_SCHED;
	s_setprio 1
	s_waitcnt lgkmcnt(0)
	v_mfma_f32_16x16x32_bf16 v[60:63], v[146:149], v[186:189], v[60:63]
	v_mfma_f32_16x16x32_bf16 v[56:59], v[158:161], v[186:189], v[56:59]
	v_mfma_f32_16x16x32_bf16 v[52:55], v[146:149], v[194:197], v[52:55]
	v_mfma_f32_16x16x32_bf16 v[40:43], v[158:161], v[194:197], v[40:43]
	v_mfma_f32_16x16x32_bf16 v[36:39], v[146:149], v[202:205], v[36:39]
	v_mfma_f32_16x16x32_bf16 v[24:27], v[158:161], v[202:205], v[24:27]
	v_mfma_f32_16x16x32_bf16 v[16:19], v[146:149], v[210:213], v[16:19]
	v_mfma_f32_16x16x32_bf16 v[8:11], v[158:161], v[210:213], v[8:11]
	v_mfma_f32_16x16x32_bf16 v[60:63], v[154:157], v[190:193], v[60:63]
	v_mfma_f32_16x16x32_bf16 v[56:59], v[162:165], v[190:193], v[56:59]
	v_mfma_f32_16x16x32_bf16 v[52:55], v[154:157], v[198:201], v[52:55]
	v_mfma_f32_16x16x32_bf16 v[40:43], v[162:165], v[198:201], v[40:43]
	v_mfma_f32_16x16x32_bf16 v[36:39], v[154:157], v[206:209], v[36:39]
	v_mfma_f32_16x16x32_bf16 v[24:27], v[162:165], v[206:209], v[24:27]
	v_mfma_f32_16x16x32_bf16 v[16:19], v[154:157], v[214:217], v[16:19]
	v_mfma_f32_16x16x32_bf16 v[8:11], v[162:165], v[214:217], v[8:11]
	s_setprio 0
	s_setprio 1
	v_mfma_f32_16x16x32_bf16 v[48:51], v[166:169], v[186:189], v[48:51]
	v_mfma_f32_16x16x32_bf16 v[44:47], v[178:181], v[186:189], v[44:47]
	v_mfma_f32_16x16x32_bf16 v[32:35], v[166:169], v[194:197], v[32:35]
	v_mfma_f32_16x16x32_bf16 v[28:31], v[178:181], v[194:197], v[28:31]
	v_mfma_f32_16x16x32_bf16 v[20:23], v[166:169], v[202:205], v[20:23]
	v_mfma_f32_16x16x32_bf16 v[12:15], v[178:181], v[202:205], v[12:15]
	v_mfma_f32_16x16x32_bf16 v[4:7], v[166:169], v[210:213], v[4:7]
	v_mfma_f32_16x16x32_bf16 v[0:3], v[178:181], v[210:213], v[0:3]
	v_mfma_f32_16x16x32_bf16 v[48:51], v[170:173], v[190:193], v[48:51]
	v_mfma_f32_16x16x32_bf16 v[44:47], v[182:185], v[190:193], v[44:47]
	v_mfma_f32_16x16x32_bf16 v[32:35], v[170:173], v[198:201], v[32:35]
	v_mfma_f32_16x16x32_bf16 v[28:31], v[182:185], v[198:201], v[28:31]
	v_mfma_f32_16x16x32_bf16 v[20:23], v[170:173], v[206:209], v[20:23]
	v_mfma_f32_16x16x32_bf16 v[12:15], v[182:185], v[206:209], v[12:15]
	s_setprio 2
	s_barrier
	v_mfma_f32_16x16x32_bf16 v[4:7], v[170:173], v[214:217], v[4:7]
	v_mfma_f32_16x16x32_bf16 v[0:3], v[182:185], v[214:217], v[0:3]
	s_setprio 0
	s_add_i32 s1, 0, 0x18000
	s_add_i32 s12, 0, 0x1c000
	v_add_u32_e32 v162, s1, v150
	v_add_u32_e32 v182, s12, v150
	ds_read_b128 v[146:149], v162
	ds_read_b128 v[154:157], v162 offset:1024
	ds_read_b128 v[158:161], v162 offset:2048
	ds_read_b128 v[162:165], v162 offset:3072
	ds_read_b128 v[166:169], v182
	ds_read_b128 v[170:173], v182 offset:1024
	ds_read_b128 v[178:181], v182 offset:2048
	ds_read_b128 v[182:185], v182 offset:3072
	s_add_u32 s10, s70, 0x160000
	s_addc_u32 s11, s71, 0
	s_mov_b32 m0, s46
	v_lshl_add_u64 v[224:225], s[10:11], 0, v[128:129]
	ds_read_b128 v[186:189], v153 offset:32768
	ds_read_b128 v[190:193], v153 offset:33792
	ds_read_b128 v[194:197], v153 offset:34816
	ds_read_b128 v[198:201], v153 offset:35840
	ds_read_b128 v[202:205], v153 offset:36864
	ds_read_b128 v[206:209], v153 offset:37888
	ds_read_b128 v[210:213], v153 offset:38912
	ds_read_b128 v[214:217], v153 offset:39936
	global_load_lds_dwordx4 v[224:225], off
	v_lshl_add_u64 v[224:225], s[10:11], 0, v[132:133]
	s_mov_b32 m0, s47
	s_nop 0
	global_load_lds_dwordx4 v[224:225], off
	s_waitcnt vmcnt(8)
	s_waitcnt lgkmcnt(0)
	s_barrier
	s_setprio 1
	s_waitcnt lgkmcnt(0)
	v_mfma_f32_16x16x32_bf16 v[124:127], v[146:149], v[186:189], v[124:127]
	v_mfma_f32_16x16x32_bf16 v[120:123], v[158:161], v[186:189], v[120:123]
	v_mfma_f32_16x16x32_bf16 v[116:119], v[146:149], v[194:197], v[116:119]
	v_mfma_f32_16x16x32_bf16 v[104:107], v[158:161], v[194:197], v[104:107]
	v_mfma_f32_16x16x32_bf16 v[100:103], v[146:149], v[202:205], v[100:103]
	v_mfma_f32_16x16x32_bf16 v[88:91], v[158:161], v[202:205], v[88:91]
	v_mfma_f32_16x16x32_bf16 v[84:87], v[146:149], v[210:213], v[84:87]
	v_mfma_f32_16x16x32_bf16 v[72:75], v[158:161], v[210:213], v[72:75]
	v_mfma_f32_16x16x32_bf16 v[124:127], v[154:157], v[190:193], v[124:127]
	v_mfma_f32_16x16x32_bf16 v[120:123], v[162:165], v[190:193], v[120:123]
	v_mfma_f32_16x16x32_bf16 v[116:119], v[154:157], v[198:201], v[116:119]
	v_mfma_f32_16x16x32_bf16 v[104:107], v[162:165], v[198:201], v[104:107]
	v_mfma_f32_16x16x32_bf16 v[100:103], v[154:157], v[206:209], v[100:103]
	v_mfma_f32_16x16x32_bf16 v[88:91], v[162:165], v[206:209], v[88:91]
	v_mfma_f32_16x16x32_bf16 v[84:87], v[154:157], v[214:217], v[84:87]
	v_mfma_f32_16x16x32_bf16 v[72:75], v[162:165], v[214:217], v[72:75]
	s_setprio 0
	s_setprio 1
	v_mfma_f32_16x16x32_bf16 v[112:115], v[166:169], v[186:189], v[112:115]
	v_mfma_f32_16x16x32_bf16 v[108:111], v[178:181], v[186:189], v[108:111]
	v_mfma_f32_16x16x32_bf16 v[96:99], v[166:169], v[194:197], v[96:99]
	v_mfma_f32_16x16x32_bf16 v[92:95], v[178:181], v[194:197], v[92:95]
	v_mfma_f32_16x16x32_bf16 v[80:83], v[166:169], v[202:205], v[80:83]
	v_mfma_f32_16x16x32_bf16 v[76:79], v[178:181], v[202:205], v[76:79]
	v_mfma_f32_16x16x32_bf16 v[68:71], v[166:169], v[210:213], v[68:71]
	v_mfma_f32_16x16x32_bf16 v[64:67], v[178:181], v[210:213], v[64:67]
	v_mfma_f32_16x16x32_bf16 v[112:115], v[170:173], v[190:193], v[112:115]
	v_mfma_f32_16x16x32_bf16 v[108:111], v[182:185], v[190:193], v[108:111]
	v_mfma_f32_16x16x32_bf16 v[96:99], v[170:173], v[198:201], v[96:99]
	v_mfma_f32_16x16x32_bf16 v[92:95], v[182:185], v[198:201], v[92:95]
	v_mfma_f32_16x16x32_bf16 v[80:83], v[170:173], v[206:209], v[80:83]
	v_mfma_f32_16x16x32_bf16 v[76:79], v[182:185], v[206:209], v[76:79]
	s_setprio 2
	s_barrier
; #define PG8_STAGE(bufoff, gbase, voff) do { _Pragma("unroll") for (int _i = 0; _i < 2; ++_i) \
;         __builtin_amdgcn_global_load_lds((const unsigned*)((const char*)(gbase) + (voff)[_i]), (LAS unsigned*)(lds + (bufoff) + ldsw + _i * 8192), 16, 0, 0); } while (0)
; #define PG8_LDA(dst, b, h) do { _Pragma("unroll") for (int m = 0; m < 4; ++m) _Pragma("unroll") for (int k = 0; k < 2; ++k) dst[m][k] = *(const LAS bf16x8*)(lds + PG8_SA(b, h) + aoff + m * 2048 + k * 1024); } while (0)
; #define PG8_MMA(ai, bj, At, Bt) do { __builtin_amdgcn_s_setprio(1); _Pragma("unroll") for (int m = 0; m < 4; ++m) _Pragma("unroll") for (int n = 0; n < 2; ++n) _Pragma("unroll") for (int k = 0; k < 2; ++k) \
;         acc[ai][bj][m][n] = __builtin_amdgcn_mfma_f32_16x16x32_bf16(Bt[n][k], At[m][k], acc[ai][bj][m][n], 0, 0, 0); __builtin_amdgcn_s_setprio(0); } while (0)
; #define PG8_WAIT_V(n) asm volatile("s_waitcnt vmcnt(" #n ")" ::: "memory")
; #define PG8_WAIT_L(n) asm volatile("s_waitcnt lgkmcnt(" #n ")" ::: "memory")
; #define PG8_BAR __builtin_amdgcn_s_barrier()
; #define PG8_SCHED __builtin_amdgcn_sched_barrier(0)
; template <class Epi, class Sched, bool ALIGN_EPI = true, bool SP2 = true>
; __device__ __forceinline__ void gemm_phase(LAS unsigned char* lds, const bf16_t* Ag, const bf16_t* Btg, const int K, const int lda, const int ldb, const Sched& S, const Epi& E) {
;     ...
;         for (int t = 0; t < nt; t += 2) {
;     ...
;             PG8_WAIT_V(8); PG8_WAIT_L(0); PG8_BAR; PG8_MMA(0, 0, At, B0); PG8_MMA(0, 1, At, B1); PG8_BAR; PG8_SCHED;
;             PG8_LDA(At, 1, 1); PG8_STAGE(PG8_SB(1, 0), b3, voffB); PG8_STAGE(PG8_SB(1, 1), b3 + hstepB, voffB); PG8_STAGE(PG8_SA(1, 0), a3, voffA);
;             PG8_WAIT_V(8); PG8_WAIT_L(0); PG8_BAR; PG8_MMA(1, 0, At, B0); PG8_MMA(1, 1, At, B1); PG8_BAR; PG8_SCHED;
	v_mfma_f32_16x16x32_bf16 v[68:71], v[170:173], v[214:217], v[68:71]
	v_mfma_f32_16x16x32_bf16 v[64:67], v[182:185], v[214:217], v[64:67]
	s_setprio 0
	s_add_i32 s1, s1, s37
	v_lshl_add_u64 v[174:175], v[174:175], 0, s[14:15]
	s_mov_b32 m0, s1
	ds_read_b128 v[186:189], v153 offset:49152
	ds_read_b128 v[190:193], v153 offset:50176
	ds_read_b128 v[194:197], v153 offset:51200
	ds_read_b128 v[198:201], v153 offset:52224
	ds_read_b128 v[202:205], v153 offset:53248
	ds_read_b128 v[206:209], v153 offset:54272
	ds_read_b128 v[210:213], v153 offset:55296
	ds_read_b128 v[214:217], v153 offset:56320
	global_load_lds_dwordx4 v[174:175], off
	s_add_i32 m0, s1, 0x2000
	s_add_u32 s10, s66, 0x160080
	v_lshl_add_u64 v[174:175], v[218:219], 0, s[14:15]
	s_addc_u32 s11, s67, 0
	s_add_i32 s1, s12, s37
	global_load_lds_dwordx4 v[174:175], off
	v_lshl_add_u64 v[174:175], s[10:11], 0, v[130:131]
	s_mov_b32 m0, s1
	s_nop 0
	global_load_lds_dwordx4 v[174:175], off
	v_lshl_add_u64 v[174:175], s[10:11], 0, v[134:135]
	s_add_i32 m0, s1, 0x2000
	s_nop 0
	global_load_lds_dwordx4 v[174:175], off
	v_lshl_add_u64 v[174:175], v[220:221], 0, s[14:15]
	s_mov_b32 m0, s75
	s_nop 0
	global_load_lds_dwordx4 v[174:175], off
	v_lshl_add_u64 v[174:175], v[222:223], 0, s[14:15]
	s_mov_b32 m0, s76
	s_nop 0
	global_load_lds_dwordx4 v[174:175], off
	s_waitcnt vmcnt(8)
	s_waitcnt lgkmcnt(0)
	s_barrier
	s_setprio 1
	s_waitcnt lgkmcnt(0)
	v_mfma_f32_16x16x32_bf16 v[60:63], v[146:149], v[186:189], v[60:63]
	s_add_i32 s0, s0, 2
	s_add_u32 s84, s84, 0x100
	s_addc_u32 s85, s85, 0
	s_add_u32 s72, s72, 0x100
	s_addc_u32 s73, s73, 0
	s_cmpk_gt_u32 s0, 0x55
	v_mfma_f32_16x16x32_bf16 v[56:59], v[158:161], v[186:189], v[56:59]
	v_mfma_f32_16x16x32_bf16 v[52:55], v[146:149], v[194:197], v[52:55]
	v_mfma_f32_16x16x32_bf16 v[40:43], v[158:161], v[194:197], v[40:43]
	v_mfma_f32_16x16x32_bf16 v[36:39], v[146:149], v[202:205], v[36:39]
	v_mfma_f32_16x16x32_bf16 v[24:27], v[158:161], v[202:205], v[24:27]
	v_mfma_f32_16x16x32_bf16 v[16:19], v[146:149], v[210:213], v[16:19]
	v_mfma_f32_16x16x32_bf16 v[8:11], v[158:161], v[210:213], v[8:11]
	v_mfma_f32_16x16x32_bf16 v[60:63], v[154:157], v[190:193], v[60:63]
	v_mfma_f32_16x16x32_bf16 v[56:59], v[162:165], v[190:193], v[56:59]
	v_mfma_f32_16x16x32_bf16 v[52:55], v[154:157], v[198:201], v[52:55]
	v_mfma_f32_16x16x32_bf16 v[40:43], v[162:165], v[198:201], v[40:43]
	v_mfma_f32_16x16x32_bf16 v[36:39], v[154:157], v[206:209], v[36:39]
	v_mfma_f32_16x16x32_bf16 v[24:27], v[162:165], v[206:209], v[24:27]
	v_mfma_f32_16x16x32_bf16 v[16:19], v[154:157], v[214:217], v[16:19]
	v_mfma_f32_16x16x32_bf16 v[8:11], v[162:165], v[214:217], v[8:11]
	s_setprio 0
	s_setprio 1
	v_mfma_f32_16x16x32_bf16 v[48:51], v[166:169], v[186:189], v[48:51]
	v_mfma_f32_16x16x32_bf16 v[44:47], v[178:181], v[186:189], v[44:47]
	v_mfma_f32_16x16x32_bf16 v[32:35], v[166:169], v[194:197], v[32:35]
	v_mfma_f32_16x16x32_bf16 v[28:31], v[178:181], v[194:197], v[28:31]
	v_mfma_f32_16x16x32_bf16 v[20:23], v[166:169], v[202:205], v[20:23]
	v_mfma_f32_16x16x32_bf16 v[12:15], v[178:181], v[202:205], v[12:15]
	v_mfma_f32_16x16x32_bf16 v[4:7], v[166:169], v[210:213], v[4:7]
	v_mfma_f32_16x16x32_bf16 v[0:3], v[178:181], v[210:213], v[0:3]
	v_mfma_f32_16x16x32_bf16 v[48:51], v[170:173], v[190:193], v[48:51]
	v_mfma_f32_16x16x32_bf16 v[44:47], v[182:185], v[190:193], v[44:47]
	v_mfma_f32_16x16x32_bf16 v[32:35], v[170:173], v[198:201], v[32:35]
	v_mfma_f32_16x16x32_bf16 v[28:31], v[182:185], v[198:201], v[28:31]
	v_mfma_f32_16x16x32_bf16 v[20:23], v[170:173], v[206:209], v[20:23]
	v_mfma_f32_16x16x32_bf16 v[12:15], v[182:185], v[206:209], v[12:15]
	s_setprio 2
	s_barrier
	v_mfma_f32_16x16x32_bf16 v[4:7], v[170:173], v[214:217], v[4:7]
	v_mfma_f32_16x16x32_bf16 v[0:3], v[182:185], v[214:217], v[0:3]
	s_setprio 0
	s_cbranch_scc0 .LBB0_199
	s_and_b64 vcc, exec, s[48:49]
	s_cbranch_vccz .LBB0_202
	s_barrier

; #define PG8_STAGE(bufoff, gbase, voff) do { _Pragma("unroll") for (int _i = 0; _i < 2; ++_i) \
;         __builtin_amdgcn_global_load_lds((const unsigned*)((const char*)(gbase) + (voff)[_i]), (LAS unsigned*)(lds + (bufoff) + ldsw + _i * 8192), 16, 0, 0); } while (0)
; #define PG8_LDA(dst, b, h) do { _Pragma("unroll") for (int m = 0; m < 4; ++m) _Pragma("unroll") for (int k = 0; k < 2; ++k) dst[m][k] = *(const LAS bf16x8*)(lds + PG8_SA(b, h) + aoff + m * 2048 + k * 1024); } while (0)
; #define PG8_LDB(dst, b, h) do { _Pragma("unroll") for (int n = 0; n < 2; ++n) _Pragma("unroll") for (int k = 0; k < 2; ++k) dst[n][k] = *(const LAS bf16x8*)(lds + PG8_SB(b, h) + boff + n * 2048 + k * 1024); } while (0)
; #define PG8_MMA(ai, bj, At, Bt) do { __builtin_amdgcn_s_setprio(1); _Pragma("unroll") for (int m = 0; m < 4; ++m) _Pragma("unroll") for (int n = 0; n < 2; ++n) _Pragma("unroll") for (int k = 0; k < 2; ++k) \
;         acc[ai][bj][m][n] = __builtin_amdgcn_mfma_f32_16x16x32_bf16(Bt[n][k], At[m][k], acc[ai][bj][m][n], 0, 0, 0); __builtin_amdgcn_s_setprio(0); } while (0)
; #define PG8_WAIT_V(n) asm volatile("s_waitcnt vmcnt(" #n ")" ::: "memory")
; #define PG8_BAR __builtin_amdgcn_s_barrier()
; template <class Epi, class Sched, bool ALIGN_EPI = true, bool SP2 = true>
; __device__ __forceinline__ void gemm_phase(LAS unsigned char* lds, const bf16_t* Ag, const bf16_t* Btg, const int K, const int lda, const int ldb, const Sched& S, const Epi& E) {
;     ...
;         for (int t = 0; t < nt; t += 2) {
;             const bool last = (t == nt - 2);
;             const char* a1 = cA + (size_t)(t + 1) * kstep;
;             const char* a2 = last ? nA : cA + (size_t)(t + 2) * kstep; const char* b2 = last ? nB : cB + (size_t)(t + 2) * kstep;
;             const char* a3 = a2 + kstep; const char* b3 = b2 + kstep;
;             if constexpr (SP2) {
;             PG8_LDB(B0, 0, 0); PG8_LDB(B1, 0, 1); PG8_SCHED; PG8_LDA(At, 0, 0); PG8_STAGE(PG8_SA(1, 1), a1 + hstepA, voffA);
;             PG8_WAIT_V(8); PG8_WAIT_L(0); PG8_BAR; PG8_MMA(0, 0, At, B0); PG8_MMA(0, 1, At, B1); PG8_BAR; PG8_SCHED;
;             PG8_LDA(At, 0, 1); PG8_STAGE(PG8_SB(0, 0), b2, voffB); PG8_STAGE(PG8_SB(0, 1), b2 + hstepB, voffB); PG8_STAGE(PG8_SA(0, 0), a2, voffA);
;             PG8_WAIT_V(8); PG8_WAIT_L(0); PG8_BAR; PG8_MMA(1, 0, At, B0); PG8_MMA(1, 1, At, B1); PG8_BAR; PG8_SCHED;
.LBB0_278:
	ds_read_b128 v[152:155], v137
	ds_read_b128 v[156:159], v137 offset:1024
	ds_read_b128 v[160:163], v137 offset:2048
	ds_read_b128 v[164:167], v137 offset:3072
	ds_read_b128 v[168:171], v150
	ds_read_b128 v[172:175], v150 offset:1024
	ds_read_b128 v[180:183], v150 offset:2048
	ds_read_b128 v[184:187], v150 offset:3072
	s_add_u32 s34, s30, 0xfff80080
	s_addc_u32 s35, s31, -1
	s_cmp_eq_u32 s59, 28
	s_cselect_b32 s39, s55, s35
	s_cselect_b32 s38, s56, s34
	s_cselect_b32 s35, s6, s58
	s_cselect_b32 s34, s7, s57
	v_lshl_add_u64 v[220:221], s[30:31], 0, v[140:141]
	s_add_i32 m0, s33, 0xc000
	ds_read_b128 v[188:191], v151
	ds_read_b128 v[192:195], v151 offset:1024
	ds_read_b128 v[196:199], v151 offset:2048
	ds_read_b128 v[200:203], v151 offset:3072
	ds_read_b128 v[204:207], v151 offset:4096
	ds_read_b128 v[208:211], v151 offset:5120
	ds_read_b128 v[212:215], v151 offset:6144
	ds_read_b128 v[216:219], v151 offset:7168
	global_load_lds_dwordx4 v[220:221], off
	v_lshl_add_u64 v[220:221], s[30:31], 0, v[142:143]
	s_add_i32 m0, s33, 0xe000
	s_nop 0
	global_load_lds_dwordx4 v[220:221], off
	s_waitcnt vmcnt(8)
	s_waitcnt lgkmcnt(0)
	s_barrier
	s_setprio 1
	s_waitcnt lgkmcnt(0)
	v_mfma_f32_16x16x32_bf16 v[124:127], v[152:155], v[188:191], v[124:127]
	v_mfma_f32_16x16x32_bf16 v[120:123], v[160:163], v[188:191], v[120:123]
	v_mfma_f32_16x16x32_bf16 v[116:119], v[152:155], v[196:199], v[116:119]
	v_mfma_f32_16x16x32_bf16 v[112:115], v[160:163], v[196:199], v[112:115]
	v_mfma_f32_16x16x32_bf16 v[100:103], v[152:155], v[204:207], v[100:103]
	v_mfma_f32_16x16x32_bf16 v[96:99], v[160:163], v[204:207], v[96:99]
	v_mfma_f32_16x16x32_bf16 v[84:87], v[152:155], v[212:215], v[84:87]
	v_mfma_f32_16x16x32_bf16 v[80:83], v[160:163], v[212:215], v[80:83]
	v_mfma_f32_16x16x32_bf16 v[124:127], v[156:159], v[192:195], v[124:127]
	v_mfma_f32_16x16x32_bf16 v[120:123], v[164:167], v[192:195], v[120:123]
	v_mfma_f32_16x16x32_bf16 v[116:119], v[156:159], v[200:203], v[116:119]
	v_mfma_f32_16x16x32_bf16 v[112:115], v[164:167], v[200:203], v[112:115]
	v_mfma_f32_16x16x32_bf16 v[100:103], v[156:159], v[208:211], v[100:103]
	v_mfma_f32_16x16x32_bf16 v[96:99], v[164:167], v[208:211], v[96:99]
	v_mfma_f32_16x16x32_bf16 v[84:87], v[156:159], v[216:219], v[84:87]
	v_mfma_f32_16x16x32_bf16 v[80:83], v[164:167], v[216:219], v[80:83]
	s_setprio 0
	s_setprio 1
	v_mfma_f32_16x16x32_bf16 v[108:111], v[168:171], v[188:191], v[108:111]
	v_mfma_f32_16x16x32_bf16 v[104:107], v[180:183], v[188:191], v[104:107]
	v_mfma_f32_16x16x32_bf16 v[92:95], v[168:171], v[196:199], v[92:95]
	v_mfma_f32_16x16x32_bf16 v[88:91], v[180:183], v[196:199], v[88:91]
	v_mfma_f32_16x16x32_bf16 v[76:79], v[168:171], v[204:207], v[76:79]
	v_mfma_f32_16x16x32_bf16 v[72:75], v[180:183], v[204:207], v[72:75]
	v_mfma_f32_16x16x32_bf16 v[68:71], v[168:171], v[212:215], v[68:71]
	v_mfma_f32_16x16x32_bf16 v[64:67], v[180:183], v[212:215], v[64:67]
	v_mfma_f32_16x16x32_bf16 v[108:111], v[172:175], v[192:195], v[108:111]
	v_mfma_f32_16x16x32_bf16 v[104:107], v[184:187], v[192:195], v[104:107]
	v_mfma_f32_16x16x32_bf16 v[92:95], v[172:175], v[200:203], v[92:95]
	v_mfma_f32_16x16x32_bf16 v[88:91], v[184:187], v[200:203], v[88:91]
	v_mfma_f32_16x16x32_bf16 v[76:79], v[172:175], v[208:211], v[76:79]
	v_mfma_f32_16x16x32_bf16 v[72:75], v[184:187], v[208:211], v[72:75]
	s_setprio 2
	s_barrier
	v_mfma_f32_16x16x32_bf16 v[68:71], v[172:175], v[216:219], v[68:71]
	v_mfma_f32_16x16x32_bf16 v[64:67], v[184:187], v[216:219], v[64:67]
	s_setprio 0
	s_add_i32 s60, s0, s9
	v_lshl_add_u64 v[220:221], s[34:35], 0, v[130:131]
	s_mov_b32 m0, s60
	ds_read_b128 v[188:191], v151 offset:16384
	ds_read_b128 v[192:195], v151 offset:17408
	ds_read_b128 v[196:199], v151 offset:18432
	ds_read_b128 v[200:203], v151 offset:19456
	ds_read_b128 v[204:207], v151 offset:20480
	ds_read_b128 v[208:211], v151 offset:21504
	ds_read_b128 v[212:215], v151 offset:22528
	ds_read_b128 v[216:219], v151 offset:23552
	global_load_lds_dwordx4 v[220:221], off
	s_add_i32 m0, s60, 0x2000
	s_add_u32 s60, s34, 0x80000
	v_lshl_add_u64 v[222:223], s[34:35], 0, v[134:135]
	s_addc_u32 s61, s35, 0
	s_add_i32 s62, s54, s9
	global_load_lds_dwordx4 v[222:223], off
	v_lshl_add_u64 v[224:225], s[60:61], 0, v[130:131]
	s_mov_b32 m0, s62
	v_lshl_add_u64 v[226:227], s[38:39], 0, v[132:133]
	global_load_lds_dwordx4 v[224:225], off
	v_lshl_add_u64 v[224:225], s[60:61], 0, v[134:135]
	s_add_i32 m0, s62, 0x2000
	s_nop 0
	global_load_lds_dwordx4 v[224:225], off
	v_lshl_add_u64 v[224:225], s[38:39], 0, v[128:129]
	s_mov_b32 m0, s33
	s_nop 0
	global_load_lds_dwordx4 v[224:225], off
	s_mov_b32 m0, s41
	s_nop 0
	global_load_lds_dwordx4 v[226:227], off
	s_waitcnt vmcnt(8)
	s_waitcnt lgkmcnt(0)
	s_barrier
; #define PG8_STAGE(bufoff, gbase, voff) do { _Pragma("unroll") for (int _i = 0; _i < 2; ++_i) \
;         __builtin_amdgcn_global_load_lds((const unsigned*)((const char*)(gbase) + (voff)[_i]), (LAS unsigned*)(lds + (bufoff) + ldsw + _i * 8192), 16, 0, 0); } while (0)
; #define PG8_LDA(dst, b, h) do { _Pragma("unroll") for (int m = 0; m < 4; ++m) _Pragma("unroll") for (int k = 0; k < 2; ++k) dst[m][k] = *(const LAS bf16x8*)(lds + PG8_SA(b, h) + aoff + m * 2048 + k * 1024); } while (0)
; #define PG8_LDB(dst, b, h) do { _Pragma("unroll") for (int n = 0; n < 2; ++n) _Pragma("unroll") for (int k = 0; k < 2; ++k) dst[n][k] = *(const LAS bf16x8*)(lds + PG8_SB(b, h) + boff + n * 2048 + k * 1024); } while (0)
; #define PG8_MMA(ai, bj, At, Bt) do { __builtin_amdgcn_s_setprio(1); _Pragma("unroll") for (int m = 0; m < 4; ++m) _Pragma("unroll") for (int n = 0; n < 2; ++n) _Pragma("unroll") for (int k = 0; k < 2; ++k) \
;         acc[ai][bj][m][n] = __builtin_amdgcn_mfma_f32_16x16x32_bf16(Bt[n][k], At[m][k], acc[ai][bj][m][n], 0, 0, 0); __builtin_amdgcn_s_setprio(0); } while (0)
; #define PG8_WAIT_V(n) asm volatile("s_waitcnt vmcnt(" #n ")" ::: "memory")
; #define PG8_WAIT_L(n) asm volatile("s_waitcnt lgkmcnt(" #n ")" ::: "memory")
; #define PG8_BAR __builtin_amdgcn_s_barrier()
; #define PG8_SCHED __builtin_amdgcn_sched_barrier(0)
; template <class Epi, class Sched, bool ALIGN_EPI = true, bool SP2 = true>
; __device__ __forceinline__ void gemm_phase(LAS unsigned char* lds, const bf16_t* Ag, const bf16_t* Btg, const int K, const int lda, const int ldb, const Sched& S, const Epi& E) {
;     ...
;             PG8_WAIT_V(8); PG8_WAIT_L(0); PG8_BAR; PG8_MMA(1, 0, At, B0); PG8_MMA(1, 1, At, B1); PG8_BAR; PG8_SCHED;
;             PG8_LDB(B0, 1, 0); PG8_LDB(B1, 1, 1); PG8_SCHED; PG8_LDA(At, 1, 0); PG8_STAGE(PG8_SA(0, 1), a2 + hstepA, voffA);
;             PG8_WAIT_V(8); PG8_WAIT_L(0); PG8_BAR; PG8_MMA(0, 0, At, B0); PG8_MMA(0, 1, At, B1); PG8_BAR; PG8_SCHED;
	s_setprio 1
	s_waitcnt lgkmcnt(0)
	v_mfma_f32_16x16x32_bf16 v[60:63], v[152:155], v[188:191], v[60:63]
	v_mfma_f32_16x16x32_bf16 v[56:59], v[160:163], v[188:191], v[56:59]
	v_mfma_f32_16x16x32_bf16 v[52:55], v[152:155], v[196:199], v[52:55]
	v_mfma_f32_16x16x32_bf16 v[48:51], v[160:163], v[196:199], v[48:51]
	v_mfma_f32_16x16x32_bf16 v[36:39], v[152:155], v[204:207], v[36:39]
	v_mfma_f32_16x16x32_bf16 v[32:35], v[160:163], v[204:207], v[32:35]
	v_mfma_f32_16x16x32_bf16 v[20:23], v[152:155], v[212:215], v[20:23]
	v_mfma_f32_16x16x32_bf16 v[16:19], v[160:163], v[212:215], v[16:19]
	v_mfma_f32_16x16x32_bf16 v[60:63], v[156:159], v[192:195], v[60:63]
	v_mfma_f32_16x16x32_bf16 v[56:59], v[164:167], v[192:195], v[56:59]
	v_mfma_f32_16x16x32_bf16 v[52:55], v[156:159], v[200:203], v[52:55]
	v_mfma_f32_16x16x32_bf16 v[48:51], v[164:167], v[200:203], v[48:51]
	v_mfma_f32_16x16x32_bf16 v[36:39], v[156:159], v[208:211], v[36:39]
	v_mfma_f32_16x16x32_bf16 v[32:35], v[164:167], v[208:211], v[32:35]
	v_mfma_f32_16x16x32_bf16 v[20:23], v[156:159], v[216:219], v[20:23]
	v_mfma_f32_16x16x32_bf16 v[16:19], v[164:167], v[216:219], v[16:19]
	s_setprio 0
	s_setprio 1
	v_mfma_f32_16x16x32_bf16 v[44:47], v[168:171], v[188:191], v[44:47]
	v_mfma_f32_16x16x32_bf16 v[40:43], v[180:183], v[188:191], v[40:43]
	v_mfma_f32_16x16x32_bf16 v[28:31], v[168:171], v[196:199], v[28:31]
	v_mfma_f32_16x16x32_bf16 v[24:27], v[180:183], v[196:199], v[24:27]
	v_mfma_f32_16x16x32_bf16 v[12:15], v[168:171], v[204:207], v[12:15]
	v_mfma_f32_16x16x32_bf16 v[8:11], v[180:183], v[204:207], v[8:11]
	v_mfma_f32_16x16x32_bf16 v[4:7], v[168:171], v[212:215], v[4:7]
	v_mfma_f32_16x16x32_bf16 v[0:3], v[180:183], v[212:215], v[0:3]
	v_mfma_f32_16x16x32_bf16 v[44:47], v[172:175], v[192:195], v[44:47]
	v_mfma_f32_16x16x32_bf16 v[40:43], v[184:187], v[192:195], v[40:43]
	v_mfma_f32_16x16x32_bf16 v[28:31], v[172:175], v[200:203], v[28:31]
	v_mfma_f32_16x16x32_bf16 v[24:27], v[184:187], v[200:203], v[24:27]
	v_mfma_f32_16x16x32_bf16 v[12:15], v[172:175], v[208:211], v[12:15]
	v_mfma_f32_16x16x32_bf16 v[8:11], v[184:187], v[208:211], v[8:11]
	s_setprio 2
	s_barrier
	v_mfma_f32_16x16x32_bf16 v[4:7], v[172:175], v[216:219], v[4:7]
	v_mfma_f32_16x16x32_bf16 v[0:3], v[184:187], v[216:219], v[0:3]
	s_setprio 0
	s_add_i32 s60, 0, 0x18000
	s_add_i32 s61, 0, 0x1c000
	v_add_u32_e32 v164, s60, v149
	v_add_u32_e32 v184, s61, v149
	ds_read_b128 v[152:155], v164
	ds_read_b128 v[156:159], v164 offset:1024
	ds_read_b128 v[160:163], v164 offset:2048
	ds_read_b128 v[164:167], v164 offset:3072
	ds_read_b128 v[168:171], v184
	ds_read_b128 v[172:175], v184 offset:1024
	ds_read_b128 v[180:183], v184 offset:2048
	ds_read_b128 v[184:187], v184 offset:3072
	s_add_u32 s38, s38, 0x80000
	s_addc_u32 s39, s39, 0
	s_mov_b32 m0, s46
	v_lshl_add_u64 v[228:229], s[38:39], 0, v[128:129]
	ds_read_b128 v[188:191], v151 offset:32768
	ds_read_b128 v[192:195], v151 offset:33792
	ds_read_b128 v[196:199], v151 offset:34816
	ds_read_b128 v[200:203], v151 offset:35840
	ds_read_b128 v[204:207], v151 offset:36864
	ds_read_b128 v[208:211], v151 offset:37888
	ds_read_b128 v[212:215], v151 offset:38912
	ds_read_b128 v[216:219], v151 offset:39936
	global_load_lds_dwordx4 v[228:229], off
	v_lshl_add_u64 v[228:229], s[38:39], 0, v[132:133]
	s_mov_b32 m0, s47
	s_nop 0
	global_load_lds_dwordx4 v[228:229], off
	s_waitcnt vmcnt(8)
	s_waitcnt lgkmcnt(0)
	s_barrier
	s_setprio 1
	s_waitcnt lgkmcnt(0)
	v_mfma_f32_16x16x32_bf16 v[124:127], v[152:155], v[188:191], v[124:127]
	v_mfma_f32_16x16x32_bf16 v[120:123], v[160:163], v[188:191], v[120:123]
	v_mfma_f32_16x16x32_bf16 v[116:119], v[152:155], v[196:199], v[116:119]
	v_mfma_f32_16x16x32_bf16 v[112:115], v[160:163], v[196:199], v[112:115]
	v_mfma_f32_16x16x32_bf16 v[100:103], v[152:155], v[204:207], v[100:103]
	v_mfma_f32_16x16x32_bf16 v[96:99], v[160:163], v[204:207], v[96:99]
	v_mfma_f32_16x16x32_bf16 v[84:87], v[152:155], v[212:215], v[84:87]
	v_mfma_f32_16x16x32_bf16 v[80:83], v[160:163], v[212:215], v[80:83]
	v_mfma_f32_16x16x32_bf16 v[124:127], v[156:159], v[192:195], v[124:127]
	v_mfma_f32_16x16x32_bf16 v[120:123], v[164:167], v[192:195], v[120:123]
	v_mfma_f32_16x16x32_bf16 v[116:119], v[156:159], v[200:203], v[116:119]
	v_mfma_f32_16x16x32_bf16 v[112:115], v[164:167], v[200:203], v[112:115]
	v_mfma_f32_16x16x32_bf16 v[100:103], v[156:159], v[208:211], v[100:103]
	v_mfma_f32_16x16x32_bf16 v[96:99], v[164:167], v[208:211], v[96:99]
	v_mfma_f32_16x16x32_bf16 v[84:87], v[156:159], v[216:219], v[84:87]
	v_mfma_f32_16x16x32_bf16 v[80:83], v[164:167], v[216:219], v[80:83]
	s_setprio 0
	s_setprio 1
	v_mfma_f32_16x16x32_bf16 v[108:111], v[168:171], v[188:191], v[108:111]
	v_mfma_f32_16x16x32_bf16 v[104:107], v[180:183], v[188:191], v[104:107]
	v_mfma_f32_16x16x32_bf16 v[92:95], v[168:171], v[196:199], v[92:95]
	v_mfma_f32_16x16x32_bf16 v[88:91], v[180:183], v[196:199], v[88:91]
	v_mfma_f32_16x16x32_bf16 v[76:79], v[168:171], v[204:207], v[76:79]
	v_mfma_f32_16x16x32_bf16 v[72:75], v[180:183], v[204:207], v[72:75]
	v_mfma_f32_16x16x32_bf16 v[68:71], v[168:171], v[212:215], v[68:71]
	v_mfma_f32_16x16x32_bf16 v[64:67], v[180:183], v[212:215], v[64:67]
	v_mfma_f32_16x16x32_bf16 v[108:111], v[172:175], v[192:195], v[108:111]
	v_mfma_f32_16x16x32_bf16 v[104:107], v[184:187], v[192:195], v[104:107]
	v_mfma_f32_16x16x32_bf16 v[92:95], v[172:175], v[200:203], v[92:95]
	v_mfma_f32_16x16x32_bf16 v[88:91], v[184:187], v[200:203], v[88:91]
	v_mfma_f32_16x16x32_bf16 v[76:79], v[172:175], v[208:211], v[76:79]
	v_mfma_f32_16x16x32_bf16 v[72:75], v[184:187], v[208:211], v[72:75]
	s_setprio 2
	s_barrier
; #define PG8_STAGE(bufoff, gbase, voff) do { _Pragma("unroll") for (int _i = 0; _i < 2; ++_i) \
;         __builtin_amdgcn_global_load_lds((const unsigned*)((const char*)(gbase) + (voff)[_i]), (LAS unsigned*)(lds + (bufoff) + ldsw + _i * 8192), 16, 0, 0); } while (0)
; #define PG8_LDA(dst, b, h) do { _Pragma("unroll") for (int m = 0; m < 4; ++m) _Pragma("unroll") for (int k = 0; k < 2; ++k) dst[m][k] = *(const LAS bf16x8*)(lds + PG8_SA(b, h) + aoff + m * 2048 + k * 1024); } while (0)
; #define PG8_MMA(ai, bj, At, Bt) do { __builtin_amdgcn_s_setprio(1); _Pragma("unroll") for (int m = 0; m < 4; ++m) _Pragma("unroll") for (int n = 0; n < 2; ++n) _Pragma("unroll") for (int k = 0; k < 2; ++k) \
;         acc[ai][bj][m][n] = __builtin_amdgcn_mfma_f32_16x16x32_bf16(Bt[n][k], At[m][k], acc[ai][bj][m][n], 0, 0, 0); __builtin_amdgcn_s_setprio(0); } while (0)
; #define PG8_WAIT_V(n) asm volatile("s_waitcnt vmcnt(" #n ")" ::: "memory")
; #define PG8_WAIT_L(n) asm volatile("s_waitcnt lgkmcnt(" #n ")" ::: "memory")
; #define PG8_BAR __builtin_amdgcn_s_barrier()
; #define PG8_SCHED __builtin_amdgcn_sched_barrier(0)
; template <class Epi, class Sched, bool ALIGN_EPI = true, bool SP2 = true>
; __device__ __forceinline__ void gemm_phase(LAS unsigned char* lds, const bf16_t* Ag, const bf16_t* Btg, const int K, const int lda, const int ldb, const Sched& S, const Epi& E) {
;     ...
;         for (int t = 0; t < nt; t += 2) {
;     ...
;             PG8_WAIT_V(8); PG8_WAIT_L(0); PG8_BAR; PG8_MMA(0, 0, At, B0); PG8_MMA(0, 1, At, B1); PG8_BAR; PG8_SCHED;
;             PG8_LDA(At, 1, 1); PG8_STAGE(PG8_SB(1, 0), b3, voffB); PG8_STAGE(PG8_SB(1, 1), b3 + hstepB, voffB); PG8_STAGE(PG8_SA(1, 0), a3, voffA);
;             PG8_WAIT_V(8); PG8_WAIT_L(0); PG8_BAR; PG8_MMA(1, 0, At, B0); PG8_MMA(1, 1, At, B1); PG8_BAR; PG8_SCHED;
	v_mfma_f32_16x16x32_bf16 v[68:71], v[172:175], v[216:219], v[68:71]
	v_mfma_f32_16x16x32_bf16 v[64:67], v[184:187], v[216:219], v[64:67]
	s_setprio 0
	s_add_i32 s38, s60, s9
	v_lshl_add_u64 v[220:221], v[220:221], 0, s[12:13]
	s_mov_b32 m0, s38
	ds_read_b128 v[188:191], v151 offset:49152
	ds_read_b128 v[192:195], v151 offset:50176
	ds_read_b128 v[196:199], v151 offset:51200
	ds_read_b128 v[200:203], v151 offset:52224
	ds_read_b128 v[204:207], v151 offset:53248
	ds_read_b128 v[208:211], v151 offset:54272
	ds_read_b128 v[212:215], v151 offset:55296
	ds_read_b128 v[216:219], v151 offset:56320
	global_load_lds_dwordx4 v[220:221], off
	s_add_i32 m0, s38, 0x2000
	s_add_u32 s34, s34, 0x80080
	v_lshl_add_u64 v[220:221], v[222:223], 0, s[12:13]
	s_addc_u32 s35, s35, 0
	s_add_i32 s38, s61, s9
	global_load_lds_dwordx4 v[220:221], off
	v_lshl_add_u64 v[220:221], s[34:35], 0, v[130:131]
	s_mov_b32 m0, s38
	s_nop 0
	global_load_lds_dwordx4 v[220:221], off
	v_lshl_add_u64 v[220:221], s[34:35], 0, v[134:135]
	s_add_i32 m0, s38, 0x2000
	s_nop 0
	global_load_lds_dwordx4 v[220:221], off
	v_lshl_add_u64 v[220:221], v[224:225], 0, s[12:13]
	s_mov_b32 m0, s50
	s_nop 0
	global_load_lds_dwordx4 v[220:221], off
	v_lshl_add_u64 v[220:221], v[226:227], 0, s[12:13]
	s_mov_b32 m0, s51
	s_nop 0
	global_load_lds_dwordx4 v[220:221], off
	s_waitcnt vmcnt(8)
	s_waitcnt lgkmcnt(0)
	s_barrier
	s_setprio 1
	s_waitcnt lgkmcnt(0)
	v_mfma_f32_16x16x32_bf16 v[60:63], v[152:155], v[188:191], v[60:63]
	s_add_i32 s59, s59, 2
	s_add_u32 s30, s30, 0x100
	s_addc_u32 s31, s31, 0
	s_add_u32 s57, s57, 0x100
	s_addc_u32 s58, s58, 0
	s_cmp_gt_u32 s59, 29
	v_mfma_f32_16x16x32_bf16 v[56:59], v[160:163], v[188:191], v[56:59]
	v_mfma_f32_16x16x32_bf16 v[52:55], v[152:155], v[196:199], v[52:55]
	v_mfma_f32_16x16x32_bf16 v[48:51], v[160:163], v[196:199], v[48:51]
	v_mfma_f32_16x16x32_bf16 v[36:39], v[152:155], v[204:207], v[36:39]
	v_mfma_f32_16x16x32_bf16 v[32:35], v[160:163], v[204:207], v[32:35]
	v_mfma_f32_16x16x32_bf16 v[20:23], v[152:155], v[212:215], v[20:23]
	v_mfma_f32_16x16x32_bf16 v[16:19], v[160:163], v[212:215], v[16:19]
	v_mfma_f32_16x16x32_bf16 v[60:63], v[156:159], v[192:195], v[60:63]
	v_mfma_f32_16x16x32_bf16 v[56:59], v[164:167], v[192:195], v[56:59]
	v_mfma_f32_16x16x32_bf16 v[52:55], v[156:159], v[200:203], v[52:55]
	v_mfma_f32_16x16x32_bf16 v[48:51], v[164:167], v[200:203], v[48:51]
	v_mfma_f32_16x16x32_bf16 v[36:39], v[156:159], v[208:211], v[36:39]
	v_mfma_f32_16x16x32_bf16 v[32:35], v[164:167], v[208:211], v[32:35]
	v_mfma_f32_16x16x32_bf16 v[20:23], v[156:159], v[216:219], v[20:23]
	v_mfma_f32_16x16x32_bf16 v[16:19], v[164:167], v[216:219], v[16:19]
	s_setprio 0
	s_setprio 1
	v_mfma_f32_16x16x32_bf16 v[44:47], v[168:171], v[188:191], v[44:47]
	v_mfma_f32_16x16x32_bf16 v[40:43], v[180:183], v[188:191], v[40:43]
	v_mfma_f32_16x16x32_bf16 v[28:31], v[168:171], v[196:199], v[28:31]
	v_mfma_f32_16x16x32_bf16 v[24:27], v[180:183], v[196:199], v[24:27]
	v_mfma_f32_16x16x32_bf16 v[12:15], v[168:171], v[204:207], v[12:15]
	v_mfma_f32_16x16x32_bf16 v[8:11], v[180:183], v[204:207], v[8:11]
	v_mfma_f32_16x16x32_bf16 v[4:7], v[168:171], v[212:215], v[4:7]
	v_mfma_f32_16x16x32_bf16 v[0:3], v[180:183], v[212:215], v[0:3]
	v_mfma_f32_16x16x32_bf16 v[44:47], v[172:175], v[192:195], v[44:47]
	v_mfma_f32_16x16x32_bf16 v[40:43], v[184:187], v[192:195], v[40:43]
	v_mfma_f32_16x16x32_bf16 v[28:31], v[172:175], v[200:203], v[28:31]
	v_mfma_f32_16x16x32_bf16 v[24:27], v[184:187], v[200:203], v[24:27]
	v_mfma_f32_16x16x32_bf16 v[12:15], v[172:175], v[208:211], v[12:15]
	v_mfma_f32_16x16x32_bf16 v[8:11], v[184:187], v[208:211], v[8:11]
	s_setprio 2
	s_barrier
	v_mfma_f32_16x16x32_bf16 v[4:7], v[172:175], v[216:219], v[4:7]
	v_mfma_f32_16x16x32_bf16 v[0:3], v[184:187], v[216:219], v[0:3]
	s_setprio 0
	s_cbranch_scc0 .LBB0_278
	s_and_b64 vcc, exec, s[14:15]
	s_cbranch_vccz .LBB0_281
	s_barrier

; #define PG8_STAGE(bufoff, gbase, voff) do { _Pragma("unroll") for (int _i = 0; _i < 2; ++_i) \
;         __builtin_amdgcn_global_load_lds((const unsigned*)((const char*)(gbase) + (voff)[_i]), (LAS unsigned*)(lds + (bufoff) + ldsw + _i * 8192), 16, 0, 0); } while (0)
; #define PG8_LDA(dst, b, h) do { _Pragma("unroll") for (int m = 0; m < 4; ++m) _Pragma("unroll") for (int k = 0; k < 2; ++k) dst[m][k] = *(const LAS bf16x8*)(lds + PG8_SA(b, h) + aoff + m * 2048 + k * 1024); } while (0)
; #define PG8_LDB(dst, b, h) do { _Pragma("unroll") for (int n = 0; n < 2; ++n) _Pragma("unroll") for (int k = 0; k < 2; ++k) dst[n][k] = *(const LAS bf16x8*)(lds + PG8_SB(b, h) + boff + n * 2048 + k * 1024); } while (0)
; #define PG8_MMA(ai, bj, At, Bt) do { __builtin_amdgcn_s_setprio(1); _Pragma("unroll") for (int m = 0; m < 4; ++m) _Pragma("unroll") for (int n = 0; n < 2; ++n) _Pragma("unroll") for (int k = 0; k < 2; ++k) \
;         acc[ai][bj][m][n] = __builtin_amdgcn_mfma_f32_16x16x32_bf16(Bt[n][k], At[m][k], acc[ai][bj][m][n], 0, 0, 0); __builtin_amdgcn_s_setprio(0); } while (0)
; #define PG8_WAIT_V(n) asm volatile("s_waitcnt vmcnt(" #n ")" ::: "memory")
; #define PG8_BAR __builtin_amdgcn_s_barrier()
; template <class Epi, class Sched, bool ALIGN_EPI = true, bool SP2 = true>
; __device__ __forceinline__ void gemm_phase(LAS unsigned char* lds, const bf16_t* Ag, const bf16_t* Btg, const int K, const int lda, const int ldb, const Sched& S, const Epi& E) {
;     ...
;         for (int t = 0; t < nt; t += 2) {
;             const bool last = (t == nt - 2);
;             const char* a1 = cA + (size_t)(t + 1) * kstep;
;             const char* a2 = last ? nA : cA + (size_t)(t + 2) * kstep; const char* b2 = last ? nB : cB + (size_t)(t + 2) * kstep;
;             const char* a3 = a2 + kstep; const char* b3 = b2 + kstep;
;             if constexpr (SP2) {
;             PG8_LDB(B0, 0, 0); PG8_LDB(B1, 0, 1); PG8_SCHED; PG8_LDA(At, 0, 0); PG8_STAGE(PG8_SA(1, 1), a1 + hstepA, voffA);
;             PG8_WAIT_V(8); PG8_WAIT_L(0); PG8_BAR; PG8_MMA(0, 0, At, B0); PG8_MMA(0, 1, At, B1); PG8_BAR; PG8_SCHED;
;             PG8_LDA(At, 0, 1); PG8_STAGE(PG8_SB(0, 0), b2, voffB); PG8_STAGE(PG8_SB(0, 1), b2 + hstepB, voffB); PG8_STAGE(PG8_SA(0, 0), a2, voffA);
;             PG8_WAIT_V(8); PG8_WAIT_L(0); PG8_BAR; PG8_MMA(1, 0, At, B0); PG8_MMA(1, 1, At, B1); PG8_BAR; PG8_SCHED;
.LBB0_302:
	ds_read_b128 v[146:149], v143
	ds_read_b128 v[150:153], v143 offset:1024
	ds_read_b128 v[154:157], v143 offset:2048
	ds_read_b128 v[158:161], v143 offset:3072
	ds_read_b128 v[162:165], v144
	ds_read_b128 v[166:169], v144 offset:1024
	ds_read_b128 v[170:173], v144 offset:2048
	ds_read_b128 v[180:183], v144 offset:3072
	s_add_u32 s30, s28, 0xfff80080
	s_addc_u32 s31, s29, -1
	s_cmp_eq_u32 s62, 28
	s_cselect_b32 s35, s56, s31
	s_cselect_b32 s34, s57, s30
	s_cselect_b32 s31, s58, s61
	s_cselect_b32 s30, s59, s60
	v_lshl_add_u64 v[174:175], s[28:29], 0, v[138:139]
	s_add_i32 m0, s41, 0xc000
	ds_read_b128 v[184:187], v145
	ds_read_b128 v[188:191], v145 offset:1024
	ds_read_b128 v[192:195], v145 offset:2048
	ds_read_b128 v[196:199], v145 offset:3072
	ds_read_b128 v[200:203], v145 offset:4096
	ds_read_b128 v[204:207], v145 offset:5120
	ds_read_b128 v[208:211], v145 offset:6144
	ds_read_b128 v[212:215], v145 offset:7168
	global_load_lds_dwordx4 v[174:175], off
	v_lshl_add_u64 v[174:175], s[28:29], 0, v[140:141]
	s_add_i32 m0, s41, 0xe000
	s_nop 0
	global_load_lds_dwordx4 v[174:175], off
	s_waitcnt vmcnt(8)
	s_waitcnt lgkmcnt(0)
	s_barrier
	s_setprio 1
	s_waitcnt lgkmcnt(0)
	v_mfma_f32_16x16x32_bf16 v[124:127], v[146:149], v[184:187], v[124:127]
	v_mfma_f32_16x16x32_bf16 v[120:123], v[154:157], v[184:187], v[120:123]
	v_mfma_f32_16x16x32_bf16 v[116:119], v[146:149], v[192:195], v[116:119]
	v_mfma_f32_16x16x32_bf16 v[112:115], v[154:157], v[192:195], v[112:115]
	v_mfma_f32_16x16x32_bf16 v[100:103], v[146:149], v[200:203], v[100:103]
	v_mfma_f32_16x16x32_bf16 v[96:99], v[154:157], v[200:203], v[96:99]
	v_mfma_f32_16x16x32_bf16 v[84:87], v[146:149], v[208:211], v[84:87]
	v_mfma_f32_16x16x32_bf16 v[80:83], v[154:157], v[208:211], v[80:83]
	v_mfma_f32_16x16x32_bf16 v[124:127], v[150:153], v[188:191], v[124:127]
	v_mfma_f32_16x16x32_bf16 v[120:123], v[158:161], v[188:191], v[120:123]
	v_mfma_f32_16x16x32_bf16 v[116:119], v[150:153], v[196:199], v[116:119]
	v_mfma_f32_16x16x32_bf16 v[112:115], v[158:161], v[196:199], v[112:115]
	v_mfma_f32_16x16x32_bf16 v[100:103], v[150:153], v[204:207], v[100:103]
	v_mfma_f32_16x16x32_bf16 v[96:99], v[158:161], v[204:207], v[96:99]
	v_mfma_f32_16x16x32_bf16 v[84:87], v[150:153], v[212:215], v[84:87]
	v_mfma_f32_16x16x32_bf16 v[80:83], v[158:161], v[212:215], v[80:83]
	s_setprio 0
	s_setprio 1
	v_mfma_f32_16x16x32_bf16 v[108:111], v[162:165], v[184:187], v[108:111]
	v_mfma_f32_16x16x32_bf16 v[104:107], v[170:173], v[184:187], v[104:107]
	v_mfma_f32_16x16x32_bf16 v[92:95], v[162:165], v[192:195], v[92:95]
	v_mfma_f32_16x16x32_bf16 v[88:91], v[170:173], v[192:195], v[88:91]
	v_mfma_f32_16x16x32_bf16 v[76:79], v[162:165], v[200:203], v[76:79]
	v_mfma_f32_16x16x32_bf16 v[72:75], v[170:173], v[200:203], v[72:75]
	v_mfma_f32_16x16x32_bf16 v[68:71], v[162:165], v[208:211], v[68:71]
	v_mfma_f32_16x16x32_bf16 v[64:67], v[170:173], v[208:211], v[64:67]
	v_mfma_f32_16x16x32_bf16 v[108:111], v[166:169], v[188:191], v[108:111]
	v_mfma_f32_16x16x32_bf16 v[104:107], v[180:183], v[188:191], v[104:107]
	v_mfma_f32_16x16x32_bf16 v[92:95], v[166:169], v[196:199], v[92:95]
	v_mfma_f32_16x16x32_bf16 v[88:91], v[180:183], v[196:199], v[88:91]
	v_mfma_f32_16x16x32_bf16 v[76:79], v[166:169], v[204:207], v[76:79]
	v_mfma_f32_16x16x32_bf16 v[72:75], v[180:183], v[204:207], v[72:75]
	s_setprio 2
	s_barrier
	v_mfma_f32_16x16x32_bf16 v[68:71], v[166:169], v[212:215], v[68:71]
	v_mfma_f32_16x16x32_bf16 v[64:67], v[180:183], v[212:215], v[64:67]
	s_setprio 0
	s_add_i32 s63, s0, s39
	v_lshl_add_u64 v[174:175], s[30:31], 0, v[130:131]
	s_mov_b32 m0, s63
	ds_read_b128 v[184:187], v145 offset:16384
	ds_read_b128 v[188:191], v145 offset:17408
	ds_read_b128 v[192:195], v145 offset:18432
	ds_read_b128 v[196:199], v145 offset:19456
	ds_read_b128 v[200:203], v145 offset:20480
	ds_read_b128 v[204:207], v145 offset:21504
	ds_read_b128 v[208:211], v145 offset:22528
	ds_read_b128 v[212:215], v145 offset:23552
	global_load_lds_dwordx4 v[174:175], off
	s_add_i32 m0, s63, 0x2000
	s_add_u32 s64, s30, 0x80000
	v_lshl_add_u64 v[216:217], s[30:31], 0, v[134:135]
	s_addc_u32 s65, s31, 0
	s_add_i32 s63, s55, s39
	global_load_lds_dwordx4 v[216:217], off
	v_lshl_add_u64 v[218:219], s[64:65], 0, v[130:131]
	s_mov_b32 m0, s63
	v_lshl_add_u64 v[220:221], s[34:35], 0, v[132:133]
	global_load_lds_dwordx4 v[218:219], off
	v_lshl_add_u64 v[218:219], s[64:65], 0, v[134:135]
	s_add_i32 m0, s63, 0x2000
	s_nop 0
	global_load_lds_dwordx4 v[218:219], off
	v_lshl_add_u64 v[218:219], s[34:35], 0, v[128:129]
	s_mov_b32 m0, s41
	s_nop 0
	global_load_lds_dwordx4 v[218:219], off
	s_mov_b32 m0, s46
	s_nop 0
	global_load_lds_dwordx4 v[220:221], off
	s_waitcnt vmcnt(8)
	s_waitcnt lgkmcnt(0)
	s_barrier
; #define PG8_STAGE(bufoff, gbase, voff) do { _Pragma("unroll") for (int _i = 0; _i < 2; ++_i) \
;         __builtin_amdgcn_global_load_lds((const unsigned*)((const char*)(gbase) + (voff)[_i]), (LAS unsigned*)(lds + (bufoff) + ldsw + _i * 8192), 16, 0, 0); } while (0)
; #define PG8_LDA(dst, b, h) do { _Pragma("unroll") for (int m = 0; m < 4; ++m) _Pragma("unroll") for (int k = 0; k < 2; ++k) dst[m][k] = *(const LAS bf16x8*)(lds + PG8_SA(b, h) + aoff + m * 2048 + k * 1024); } while (0)
; #define PG8_LDB(dst, b, h) do { _Pragma("unroll") for (int n = 0; n < 2; ++n) _Pragma("unroll") for (int k = 0; k < 2; ++k) dst[n][k] = *(const LAS bf16x8*)(lds + PG8_SB(b, h) + boff + n * 2048 + k * 1024); } while (0)
; #define PG8_MMA(ai, bj, At, Bt) do { __builtin_amdgcn_s_setprio(1); _Pragma("unroll") for (int m = 0; m < 4; ++m) _Pragma("unroll") for (int n = 0; n < 2; ++n) _Pragma("unroll") for (int k = 0; k < 2; ++k) \
;         acc[ai][bj][m][n] = __builtin_amdgcn_mfma_f32_16x16x32_bf16(Bt[n][k], At[m][k], acc[ai][bj][m][n], 0, 0, 0); __builtin_amdgcn_s_setprio(0); } while (0)
; #define PG8_WAIT_V(n) asm volatile("s_waitcnt vmcnt(" #n ")" ::: "memory")
; #define PG8_WAIT_L(n) asm volatile("s_waitcnt lgkmcnt(" #n ")" ::: "memory")
; #define PG8_BAR __builtin_amdgcn_s_barrier()
; #define PG8_SCHED __builtin_amdgcn_sched_barrier(0)
; template <class Epi, class Sched, bool ALIGN_EPI = true, bool SP2 = true>
; __device__ __forceinline__ void gemm_phase(LAS unsigned char* lds, const bf16_t* Ag, const bf16_t* Btg, const int K, const int lda, const int ldb, const Sched& S, const Epi& E) {
;     ...
;             PG8_WAIT_V(8); PG8_WAIT_L(0); PG8_BAR; PG8_MMA(1, 0, At, B0); PG8_MMA(1, 1, At, B1); PG8_BAR; PG8_SCHED;
;             PG8_LDB(B0, 1, 0); PG8_LDB(B1, 1, 1); PG8_SCHED; PG8_LDA(At, 1, 0); PG8_STAGE(PG8_SA(0, 1), a2 + hstepA, voffA);
;             PG8_WAIT_V(8); PG8_WAIT_L(0); PG8_BAR; PG8_MMA(0, 0, At, B0); PG8_MMA(0, 1, At, B1); PG8_BAR; PG8_SCHED;
	s_setprio 1
	s_waitcnt lgkmcnt(0)
	v_mfma_f32_16x16x32_bf16 v[60:63], v[146:149], v[184:187], v[60:63]
	v_mfma_f32_16x16x32_bf16 v[56:59], v[154:157], v[184:187], v[56:59]
	v_mfma_f32_16x16x32_bf16 v[52:55], v[146:149], v[192:195], v[52:55]
	v_mfma_f32_16x16x32_bf16 v[48:51], v[154:157], v[192:195], v[48:51]
	v_mfma_f32_16x16x32_bf16 v[36:39], v[146:149], v[200:203], v[36:39]
	v_mfma_f32_16x16x32_bf16 v[32:35], v[154:157], v[200:203], v[32:35]
	v_mfma_f32_16x16x32_bf16 v[20:23], v[146:149], v[208:211], v[20:23]
	v_mfma_f32_16x16x32_bf16 v[16:19], v[154:157], v[208:211], v[16:19]
	v_mfma_f32_16x16x32_bf16 v[60:63], v[150:153], v[188:191], v[60:63]
	v_mfma_f32_16x16x32_bf16 v[56:59], v[158:161], v[188:191], v[56:59]
	v_mfma_f32_16x16x32_bf16 v[52:55], v[150:153], v[196:199], v[52:55]
	v_mfma_f32_16x16x32_bf16 v[48:51], v[158:161], v[196:199], v[48:51]
	v_mfma_f32_16x16x32_bf16 v[36:39], v[150:153], v[204:207], v[36:39]
	v_mfma_f32_16x16x32_bf16 v[32:35], v[158:161], v[204:207], v[32:35]
	v_mfma_f32_16x16x32_bf16 v[20:23], v[150:153], v[212:215], v[20:23]
	v_mfma_f32_16x16x32_bf16 v[16:19], v[158:161], v[212:215], v[16:19]
	s_setprio 0
	s_setprio 1
	v_mfma_f32_16x16x32_bf16 v[44:47], v[162:165], v[184:187], v[44:47]
	v_mfma_f32_16x16x32_bf16 v[40:43], v[170:173], v[184:187], v[40:43]
	v_mfma_f32_16x16x32_bf16 v[28:31], v[162:165], v[192:195], v[28:31]
	v_mfma_f32_16x16x32_bf16 v[24:27], v[170:173], v[192:195], v[24:27]
	v_mfma_f32_16x16x32_bf16 v[12:15], v[162:165], v[200:203], v[12:15]
	v_mfma_f32_16x16x32_bf16 v[8:11], v[170:173], v[200:203], v[8:11]
	v_mfma_f32_16x16x32_bf16 v[4:7], v[162:165], v[208:211], v[4:7]
	v_mfma_f32_16x16x32_bf16 v[0:3], v[170:173], v[208:211], v[0:3]
	v_mfma_f32_16x16x32_bf16 v[44:47], v[166:169], v[188:191], v[44:47]
	v_mfma_f32_16x16x32_bf16 v[40:43], v[180:183], v[188:191], v[40:43]
	v_mfma_f32_16x16x32_bf16 v[28:31], v[166:169], v[196:199], v[28:31]
	v_mfma_f32_16x16x32_bf16 v[24:27], v[180:183], v[196:199], v[24:27]
	v_mfma_f32_16x16x32_bf16 v[12:15], v[166:169], v[204:207], v[12:15]
	v_mfma_f32_16x16x32_bf16 v[8:11], v[180:183], v[204:207], v[8:11]
	s_setprio 2
	s_barrier
	v_mfma_f32_16x16x32_bf16 v[4:7], v[166:169], v[212:215], v[4:7]
	v_mfma_f32_16x16x32_bf16 v[0:3], v[180:183], v[212:215], v[0:3]
	s_setprio 0
	s_add_i32 s63, 0, 0x18000
	s_add_i32 s64, 0, 0x1c000
	v_add_u32_e32 v158, s63, v142
	v_add_u32_e32 v180, s64, v142
	ds_read_b128 v[146:149], v158
	ds_read_b128 v[150:153], v158 offset:1024
	ds_read_b128 v[154:157], v158 offset:2048
	ds_read_b128 v[158:161], v158 offset:3072
	ds_read_b128 v[162:165], v180
	ds_read_b128 v[166:169], v180 offset:1024
	ds_read_b128 v[170:173], v180 offset:2048
	ds_read_b128 v[180:183], v180 offset:3072
	s_add_u32 s34, s34, 0x80000
	s_addc_u32 s35, s35, 0
	s_mov_b32 m0, s47
	v_lshl_add_u64 v[222:223], s[34:35], 0, v[128:129]
	ds_read_b128 v[184:187], v145 offset:32768
	ds_read_b128 v[188:191], v145 offset:33792
	ds_read_b128 v[192:195], v145 offset:34816
	ds_read_b128 v[196:199], v145 offset:35840
	ds_read_b128 v[200:203], v145 offset:36864
	ds_read_b128 v[204:207], v145 offset:37888
	ds_read_b128 v[208:211], v145 offset:38912
	ds_read_b128 v[212:215], v145 offset:39936
	global_load_lds_dwordx4 v[222:223], off
	v_lshl_add_u64 v[222:223], s[34:35], 0, v[132:133]
	s_mov_b32 m0, s50
	s_nop 0
	global_load_lds_dwordx4 v[222:223], off
	s_waitcnt vmcnt(8)
	s_waitcnt lgkmcnt(0)
	s_barrier
	s_setprio 1
	s_waitcnt lgkmcnt(0)
	v_mfma_f32_16x16x32_bf16 v[124:127], v[146:149], v[184:187], v[124:127]
	v_mfma_f32_16x16x32_bf16 v[120:123], v[154:157], v[184:187], v[120:123]
	v_mfma_f32_16x16x32_bf16 v[116:119], v[146:149], v[192:195], v[116:119]
	v_mfma_f32_16x16x32_bf16 v[112:115], v[154:157], v[192:195], v[112:115]
	v_mfma_f32_16x16x32_bf16 v[100:103], v[146:149], v[200:203], v[100:103]
	v_mfma_f32_16x16x32_bf16 v[96:99], v[154:157], v[200:203], v[96:99]
	v_mfma_f32_16x16x32_bf16 v[84:87], v[146:149], v[208:211], v[84:87]
	v_mfma_f32_16x16x32_bf16 v[80:83], v[154:157], v[208:211], v[80:83]
	v_mfma_f32_16x16x32_bf16 v[124:127], v[150:153], v[188:191], v[124:127]
	v_mfma_f32_16x16x32_bf16 v[120:123], v[158:161], v[188:191], v[120:123]
	v_mfma_f32_16x16x32_bf16 v[116:119], v[150:153], v[196:199], v[116:119]
	v_mfma_f32_16x16x32_bf16 v[112:115], v[158:161], v[196:199], v[112:115]
	v_mfma_f32_16x16x32_bf16 v[100:103], v[150:153], v[204:207], v[100:103]
	v_mfma_f32_16x16x32_bf16 v[96:99], v[158:161], v[204:207], v[96:99]
	v_mfma_f32_16x16x32_bf16 v[84:87], v[150:153], v[212:215], v[84:87]
	v_mfma_f32_16x16x32_bf16 v[80:83], v[158:161], v[212:215], v[80:83]
	s_setprio 0
	s_setprio 1
	v_mfma_f32_16x16x32_bf16 v[108:111], v[162:165], v[184:187], v[108:111]
	v_mfma_f32_16x16x32_bf16 v[104:107], v[170:173], v[184:187], v[104:107]
	v_mfma_f32_16x16x32_bf16 v[92:95], v[162:165], v[192:195], v[92:95]
	v_mfma_f32_16x16x32_bf16 v[88:91], v[170:173], v[192:195], v[88:91]
	v_mfma_f32_16x16x32_bf16 v[76:79], v[162:165], v[200:203], v[76:79]
	v_mfma_f32_16x16x32_bf16 v[72:75], v[170:173], v[200:203], v[72:75]
	v_mfma_f32_16x16x32_bf16 v[68:71], v[162:165], v[208:211], v[68:71]
	v_mfma_f32_16x16x32_bf16 v[64:67], v[170:173], v[208:211], v[64:67]
	v_mfma_f32_16x16x32_bf16 v[108:111], v[166:169], v[188:191], v[108:111]
	v_mfma_f32_16x16x32_bf16 v[104:107], v[180:183], v[188:191], v[104:107]
	v_mfma_f32_16x16x32_bf16 v[92:95], v[166:169], v[196:199], v[92:95]
	v_mfma_f32_16x16x32_bf16 v[88:91], v[180:183], v[196:199], v[88:91]
	v_mfma_f32_16x16x32_bf16 v[76:79], v[166:169], v[204:207], v[76:79]
	v_mfma_f32_16x16x32_bf16 v[72:75], v[180:183], v[204:207], v[72:75]
	s_setprio 2
	s_barrier
; #define PG8_STAGE(bufoff, gbase, voff) do { _Pragma("unroll") for (int _i = 0; _i < 2; ++_i) \
;         __builtin_amdgcn_global_load_lds((const unsigned*)((const char*)(gbase) + (voff)[_i]), (LAS unsigned*)(lds + (bufoff) + ldsw + _i * 8192), 16, 0, 0); } while (0)
; #define PG8_LDA(dst, b, h) do { _Pragma("unroll") for (int m = 0; m < 4; ++m) _Pragma("unroll") for (int k = 0; k < 2; ++k) dst[m][k] = *(const LAS bf16x8*)(lds + PG8_SA(b, h) + aoff + m * 2048 + k * 1024); } while (0)
; #define PG8_MMA(ai, bj, At, Bt) do { __builtin_amdgcn_s_setprio(1); _Pragma("unroll") for (int m = 0; m < 4; ++m) _Pragma("unroll") for (int n = 0; n < 2; ++n) _Pragma("unroll") for (int k = 0; k < 2; ++k) \
;         acc[ai][bj][m][n] = __builtin_amdgcn_mfma_f32_16x16x32_bf16(Bt[n][k], At[m][k], acc[ai][bj][m][n], 0, 0, 0); __builtin_amdgcn_s_setprio(0); } while (0)
; #define PG8_WAIT_V(n) asm volatile("s_waitcnt vmcnt(" #n ")" ::: "memory")
; #define PG8_WAIT_L(n) asm volatile("s_waitcnt lgkmcnt(" #n ")" ::: "memory")
; #define PG8_BAR __builtin_amdgcn_s_barrier()
; #define PG8_SCHED __builtin_amdgcn_sched_barrier(0)
; template <class Epi, class Sched, bool ALIGN_EPI = true, bool SP2 = true>
; __device__ __forceinline__ void gemm_phase(LAS unsigned char* lds, const bf16_t* Ag, const bf16_t* Btg, const int K, const int lda, const int ldb, const Sched& S, const Epi& E) {
;     ...
;         for (int t = 0; t < nt; t += 2) {
;     ...
;             PG8_WAIT_V(8); PG8_WAIT_L(0); PG8_BAR; PG8_MMA(0, 0, At, B0); PG8_MMA(0, 1, At, B1); PG8_BAR; PG8_SCHED;
;             PG8_LDA(At, 1, 1); PG8_STAGE(PG8_SB(1, 0), b3, voffB); PG8_STAGE(PG8_SB(1, 1), b3 + hstepB, voffB); PG8_STAGE(PG8_SA(1, 0), a3, voffA);
;             PG8_WAIT_V(8); PG8_WAIT_L(0); PG8_BAR; PG8_MMA(1, 0, At, B0); PG8_MMA(1, 1, At, B1); PG8_BAR; PG8_SCHED;
	v_mfma_f32_16x16x32_bf16 v[68:71], v[166:169], v[212:215], v[68:71]
	v_mfma_f32_16x16x32_bf16 v[64:67], v[180:183], v[212:215], v[64:67]
	s_setprio 0
	s_add_i32 s34, s63, s39
	v_lshl_add_u64 v[174:175], v[174:175], 0, s[10:11]
	s_mov_b32 m0, s34
	ds_read_b128 v[184:187], v145 offset:49152
	ds_read_b128 v[188:191], v145 offset:50176
	ds_read_b128 v[192:195], v145 offset:51200
	ds_read_b128 v[196:199], v145 offset:52224
	ds_read_b128 v[200:203], v145 offset:53248
	ds_read_b128 v[204:207], v145 offset:54272
	ds_read_b128 v[208:211], v145 offset:55296
	ds_read_b128 v[212:215], v145 offset:56320
	global_load_lds_dwordx4 v[174:175], off
	s_add_i32 m0, s34, 0x2000
	s_add_u32 s30, s30, 0x80080
	v_lshl_add_u64 v[174:175], v[216:217], 0, s[10:11]
	s_addc_u32 s31, s31, 0
	s_add_i32 s34, s64, s39
	global_load_lds_dwordx4 v[174:175], off
	v_lshl_add_u64 v[174:175], s[30:31], 0, v[130:131]
	s_mov_b32 m0, s34
	s_nop 0
	global_load_lds_dwordx4 v[174:175], off
	v_lshl_add_u64 v[174:175], s[30:31], 0, v[134:135]
	s_add_i32 m0, s34, 0x2000
	s_nop 0
	global_load_lds_dwordx4 v[174:175], off
	v_lshl_add_u64 v[174:175], v[218:219], 0, s[10:11]
	s_mov_b32 m0, s51
	s_nop 0
	global_load_lds_dwordx4 v[174:175], off
	v_lshl_add_u64 v[174:175], v[220:221], 0, s[10:11]
	s_mov_b32 m0, s52
	s_nop 0
	global_load_lds_dwordx4 v[174:175], off
	s_waitcnt vmcnt(8)
	s_waitcnt lgkmcnt(0)
	s_barrier
	s_setprio 1
	s_waitcnt lgkmcnt(0)
	v_mfma_f32_16x16x32_bf16 v[60:63], v[146:149], v[184:187], v[60:63]
	s_add_i32 s62, s62, 2
	s_add_u32 s28, s28, 0x100
	s_addc_u32 s29, s29, 0
	s_add_u32 s60, s60, 0x100
	s_addc_u32 s61, s61, 0
	s_cmp_gt_u32 s62, 29
	v_mfma_f32_16x16x32_bf16 v[56:59], v[154:157], v[184:187], v[56:59]
	v_mfma_f32_16x16x32_bf16 v[52:55], v[146:149], v[192:195], v[52:55]
	v_mfma_f32_16x16x32_bf16 v[48:51], v[154:157], v[192:195], v[48:51]
	v_mfma_f32_16x16x32_bf16 v[36:39], v[146:149], v[200:203], v[36:39]
	v_mfma_f32_16x16x32_bf16 v[32:35], v[154:157], v[200:203], v[32:35]
	v_mfma_f32_16x16x32_bf16 v[20:23], v[146:149], v[208:211], v[20:23]
	v_mfma_f32_16x16x32_bf16 v[16:19], v[154:157], v[208:211], v[16:19]
	v_mfma_f32_16x16x32_bf16 v[60:63], v[150:153], v[188:191], v[60:63]
	v_mfma_f32_16x16x32_bf16 v[56:59], v[158:161], v[188:191], v[56:59]
	v_mfma_f32_16x16x32_bf16 v[52:55], v[150:153], v[196:199], v[52:55]
	v_mfma_f32_16x16x32_bf16 v[48:51], v[158:161], v[196:199], v[48:51]
	v_mfma_f32_16x16x32_bf16 v[36:39], v[150:153], v[204:207], v[36:39]
	v_mfma_f32_16x16x32_bf16 v[32:35], v[158:161], v[204:207], v[32:35]
	v_mfma_f32_16x16x32_bf16 v[20:23], v[150:153], v[212:215], v[20:23]
	v_mfma_f32_16x16x32_bf16 v[16:19], v[158:161], v[212:215], v[16:19]
	s_setprio 0
	s_setprio 1
	v_mfma_f32_16x16x32_bf16 v[44:47], v[162:165], v[184:187], v[44:47]
	v_mfma_f32_16x16x32_bf16 v[40:43], v[170:173], v[184:187], v[40:43]
	v_mfma_f32_16x16x32_bf16 v[28:31], v[162:165], v[192:195], v[28:31]
	v_mfma_f32_16x16x32_bf16 v[24:27], v[170:173], v[192:195], v[24:27]
	v_mfma_f32_16x16x32_bf16 v[12:15], v[162:165], v[200:203], v[12:15]
	v_mfma_f32_16x16x32_bf16 v[8:11], v[170:173], v[200:203], v[8:11]
	v_mfma_f32_16x16x32_bf16 v[4:7], v[162:165], v[208:211], v[4:7]
	v_mfma_f32_16x16x32_bf16 v[0:3], v[170:173], v[208:211], v[0:3]
	v_mfma_f32_16x16x32_bf16 v[44:47], v[166:169], v[188:191], v[44:47]
	v_mfma_f32_16x16x32_bf16 v[40:43], v[180:183], v[188:191], v[40:43]
	v_mfma_f32_16x16x32_bf16 v[28:31], v[166:169], v[196:199], v[28:31]
	v_mfma_f32_16x16x32_bf16 v[24:27], v[180:183], v[196:199], v[24:27]
	v_mfma_f32_16x16x32_bf16 v[12:15], v[166:169], v[204:207], v[12:15]
	v_mfma_f32_16x16x32_bf16 v[8:11], v[180:183], v[204:207], v[8:11]
	s_setprio 2
	s_barrier
	v_mfma_f32_16x16x32_bf16 v[4:7], v[166:169], v[212:215], v[4:7]
	v_mfma_f32_16x16x32_bf16 v[0:3], v[180:183], v[212:215], v[0:3]
	s_setprio 0
	s_cbranch_scc0 .LBB0_302
	s_and_b64 vcc, exec, s[12:13]
	s_cbranch_vccz .LBB0_305
	s_barrier

; #define PG8_STAGE(bufoff, gbase, voff) do { _Pragma("unroll") for (int _i = 0; _i < 2; ++_i) \
;         __builtin_amdgcn_global_load_lds((const unsigned*)((const char*)(gbase) + (voff)[_i]), (LAS unsigned*)(lds + (bufoff) + ldsw + _i * 8192), 16, 0, 0); } while (0)
; #define PG8_LDA(dst, b, h) do { _Pragma("unroll") for (int m = 0; m < 4; ++m) _Pragma("unroll") for (int k = 0; k < 2; ++k) dst[m][k] = *(const LAS bf16x8*)(lds + PG8_SA(b, h) + aoff + m * 2048 + k * 1024); } while (0)
; #define PG8_LDB(dst, b, h) do { _Pragma("unroll") for (int n = 0; n < 2; ++n) _Pragma("unroll") for (int k = 0; k < 2; ++k) dst[n][k] = *(const LAS bf16x8*)(lds + PG8_SB(b, h) + boff + n * 2048 + k * 1024); } while (0)
; #define PG8_MMA(ai, bj, At, Bt) do { __builtin_amdgcn_s_setprio(1); _Pragma("unroll") for (int m = 0; m < 4; ++m) _Pragma("unroll") for (int n = 0; n < 2; ++n) _Pragma("unroll") for (int k = 0; k < 2; ++k) \
;         acc[ai][bj][m][n] = __builtin_amdgcn_mfma_f32_16x16x32_bf16(Bt[n][k], At[m][k], acc[ai][bj][m][n], 0, 0, 0); __builtin_amdgcn_s_setprio(0); } while (0)
; #define PG8_WAIT_V(n) asm volatile("s_waitcnt vmcnt(" #n ")" ::: "memory")
; #define PG8_BAR __builtin_amdgcn_s_barrier()
; template <class Epi, class Sched, bool ALIGN_EPI = true, bool SP2 = true>
; __device__ __forceinline__ void gemm_phase(LAS unsigned char* lds, const bf16_t* Ag, const bf16_t* Btg, const int K, const int lda, const int ldb, const Sched& S, const Epi& E) {
;     ...
;         for (int t = 0; t < nt; t += 2) {
;             const bool last = (t == nt - 2);
;             const char* a1 = cA + (size_t)(t + 1) * kstep;
;             const char* a2 = last ? nA : cA + (size_t)(t + 2) * kstep; const char* b2 = last ? nB : cB + (size_t)(t + 2) * kstep;
;             const char* a3 = a2 + kstep; const char* b3 = b2 + kstep;
;             if constexpr (SP2) {
;             PG8_LDB(B0, 0, 0); PG8_LDB(B1, 0, 1); PG8_SCHED; PG8_LDA(At, 0, 0); PG8_STAGE(PG8_SA(1, 1), a1 + hstepA, voffA);
;             PG8_WAIT_V(8); PG8_WAIT_L(0); PG8_BAR; PG8_MMA(0, 0, At, B0); PG8_MMA(0, 1, At, B1); PG8_BAR; PG8_SCHED;
;             PG8_LDA(At, 0, 1); PG8_STAGE(PG8_SB(0, 0), b2, voffB); PG8_STAGE(PG8_SB(0, 1), b2 + hstepB, voffB); PG8_STAGE(PG8_SA(0, 0), a2, voffA);
;             PG8_WAIT_V(8); PG8_WAIT_L(0); PG8_BAR; PG8_MMA(1, 0, At, B0); PG8_MMA(1, 1, At, B1); PG8_BAR; PG8_SCHED;
.LBB0_387:
	ds_read_b128 v[80:83], v182
	ds_read_b128 v[84:87], v182 offset:1024
	ds_read_b128 v[136:139], v182 offset:2048
	ds_read_b128 v[140:143], v182 offset:3072
	ds_read_b128 v[164:167], v183
	ds_read_b128 v[168:171], v183 offset:1024
	ds_read_b128 v[172:175], v183 offset:2048
	ds_read_b128 v[186:189], v183 offset:3072
	s_add_u32 s6, s4, 0xfff80080
	s_addc_u32 s7, s5, -1
	s_cmp_eq_u32 s38, 28
	s_cselect_b32 s35, s1, s7
	s_cselect_b32 s34, s9, s6
	s_cselect_b32 s7, s15, s33
	s_cselect_b32 s6, s21, s23
	v_lshl_add_u64 v[222:223], s[4:5], 0, v[156:157]
	s_add_i32 m0, s54, 0xc000
	ds_read_b128 v[190:193], v184
	ds_read_b128 v[194:197], v184 offset:1024
	ds_read_b128 v[198:201], v184 offset:2048
	ds_read_b128 v[202:205], v184 offset:3072
	ds_read_b128 v[206:209], v184 offset:4096
	ds_read_b128 v[210:213], v184 offset:5120
	ds_read_b128 v[214:217], v184 offset:6144
	ds_read_b128 v[218:221], v184 offset:7168
	global_load_lds_dwordx4 v[222:223], off
	v_lshl_add_u64 v[222:223], s[4:5], 0, v[158:159]
	s_add_i32 m0, s54, 0xe000
	s_nop 0
	global_load_lds_dwordx4 v[222:223], off
	s_waitcnt vmcnt(8)
	s_waitcnt lgkmcnt(0)
	s_barrier
	s_setprio 1
	s_waitcnt lgkmcnt(0)
	v_mfma_f32_16x16x32_bf16 v[132:135], v[80:83], v[190:193], v[132:135]
	v_mfma_f32_16x16x32_bf16 v[128:131], v[136:139], v[190:193], v[128:131]
	v_mfma_f32_16x16x32_bf16 v[124:127], v[80:83], v[198:201], v[124:127]
	v_mfma_f32_16x16x32_bf16 v[120:123], v[136:139], v[198:201], v[120:123]
	v_mfma_f32_16x16x32_bf16 v[116:119], v[80:83], v[206:209], v[116:119]
	v_mfma_f32_16x16x32_bf16 v[112:115], v[136:139], v[206:209], v[112:115]
	v_mfma_f32_16x16x32_bf16 v[108:111], v[80:83], v[214:217], v[108:111]
	v_mfma_f32_16x16x32_bf16 v[104:107], v[136:139], v[214:217], v[104:107]
	v_mfma_f32_16x16x32_bf16 v[132:135], v[84:87], v[194:197], v[132:135]
	v_mfma_f32_16x16x32_bf16 v[128:131], v[140:143], v[194:197], v[128:131]
	v_mfma_f32_16x16x32_bf16 v[124:127], v[84:87], v[202:205], v[124:127]
	v_mfma_f32_16x16x32_bf16 v[120:123], v[140:143], v[202:205], v[120:123]
	v_mfma_f32_16x16x32_bf16 v[116:119], v[84:87], v[210:213], v[116:119]
	v_mfma_f32_16x16x32_bf16 v[112:115], v[140:143], v[210:213], v[112:115]
	v_mfma_f32_16x16x32_bf16 v[108:111], v[84:87], v[218:221], v[108:111]
	v_mfma_f32_16x16x32_bf16 v[104:107], v[140:143], v[218:221], v[104:107]
	s_setprio 0
	s_setprio 1
	v_mfma_f32_16x16x32_bf16 v[60:63], v[164:167], v[190:193], v[60:63]
	v_mfma_f32_16x16x32_bf16 v[56:59], v[172:175], v[190:193], v[56:59]
	v_mfma_f32_16x16x32_bf16 v[52:55], v[164:167], v[198:201], v[52:55]
	v_mfma_f32_16x16x32_bf16 v[48:51], v[172:175], v[198:201], v[48:51]
	v_mfma_f32_16x16x32_bf16 v[44:47], v[164:167], v[206:209], v[44:47]
	v_mfma_f32_16x16x32_bf16 v[40:43], v[172:175], v[206:209], v[40:43]
	v_mfma_f32_16x16x32_bf16 v[36:39], v[164:167], v[214:217], v[36:39]
	v_mfma_f32_16x16x32_bf16 v[32:35], v[172:175], v[214:217], v[32:35]
	v_mfma_f32_16x16x32_bf16 v[60:63], v[168:171], v[194:197], v[60:63]
	v_mfma_f32_16x16x32_bf16 v[56:59], v[186:189], v[194:197], v[56:59]
	v_mfma_f32_16x16x32_bf16 v[52:55], v[168:171], v[202:205], v[52:55]
	v_mfma_f32_16x16x32_bf16 v[48:51], v[186:189], v[202:205], v[48:51]
	v_mfma_f32_16x16x32_bf16 v[44:47], v[168:171], v[210:213], v[44:47]
	v_mfma_f32_16x16x32_bf16 v[40:43], v[186:189], v[210:213], v[40:43]
	s_setprio 2
	s_barrier
	v_mfma_f32_16x16x32_bf16 v[36:39], v[168:171], v[218:221], v[36:39]
	v_mfma_f32_16x16x32_bf16 v[32:35], v[186:189], v[218:221], v[32:35]
	s_setprio 0
	s_add_i32 s39, s84, s37
	v_lshl_add_u64 v[222:223], s[6:7], 0, v[146:147]
	s_mov_b32 m0, s39
	ds_read_b128 v[190:193], v184 offset:16384
	ds_read_b128 v[194:197], v184 offset:17408
	ds_read_b128 v[198:201], v184 offset:18432
	ds_read_b128 v[202:205], v184 offset:19456
	ds_read_b128 v[206:209], v184 offset:20480
	ds_read_b128 v[210:213], v184 offset:21504
	ds_read_b128 v[214:217], v184 offset:22528
	ds_read_b128 v[218:221], v184 offset:23552
	global_load_lds_dwordx4 v[222:223], off
	s_add_i32 m0, s39, 0x2000
	s_add_u32 s46, s6, 0x80000
	v_lshl_add_u64 v[224:225], s[6:7], 0, v[150:151]
	s_addc_u32 s47, s7, 0
	s_add_i32 s39, s85, s37
	global_load_lds_dwordx4 v[224:225], off
	v_lshl_add_u64 v[226:227], s[46:47], 0, v[146:147]
	s_mov_b32 m0, s39
	v_lshl_add_u64 v[228:229], s[34:35], 0, v[148:149]
	global_load_lds_dwordx4 v[226:227], off
	v_lshl_add_u64 v[226:227], s[46:47], 0, v[150:151]
	s_add_i32 m0, s39, 0x2000
	s_nop 0
	global_load_lds_dwordx4 v[226:227], off
	v_lshl_add_u64 v[226:227], s[34:35], 0, v[144:145]
	s_mov_b32 m0, s54
	s_nop 0
	global_load_lds_dwordx4 v[226:227], off
	s_mov_b32 m0, s55
	s_nop 0
	global_load_lds_dwordx4 v[228:229], off
	s_waitcnt vmcnt(8)
	s_waitcnt lgkmcnt(0)
	s_barrier
; #define PG8_STAGE(bufoff, gbase, voff) do { _Pragma("unroll") for (int _i = 0; _i < 2; ++_i) \
;         __builtin_amdgcn_global_load_lds((const unsigned*)((const char*)(gbase) + (voff)[_i]), (LAS unsigned*)(lds + (bufoff) + ldsw + _i * 8192), 16, 0, 0); } while (0)
; #define PG8_LDA(dst, b, h) do { _Pragma("unroll") for (int m = 0; m < 4; ++m) _Pragma("unroll") for (int k = 0; k < 2; ++k) dst[m][k] = *(const LAS bf16x8*)(lds + PG8_SA(b, h) + aoff + m * 2048 + k * 1024); } while (0)
; #define PG8_LDB(dst, b, h) do { _Pragma("unroll") for (int n = 0; n < 2; ++n) _Pragma("unroll") for (int k = 0; k < 2; ++k) dst[n][k] = *(const LAS bf16x8*)(lds + PG8_SB(b, h) + boff + n * 2048 + k * 1024); } while (0)
; #define PG8_MMA(ai, bj, At, Bt) do { __builtin_amdgcn_s_setprio(1); _Pragma("unroll") for (int m = 0; m < 4; ++m) _Pragma("unroll") for (int n = 0; n < 2; ++n) _Pragma("unroll") for (int k = 0; k < 2; ++k) \
;         acc[ai][bj][m][n] = __builtin_amdgcn_mfma_f32_16x16x32_bf16(Bt[n][k], At[m][k], acc[ai][bj][m][n], 0, 0, 0); __builtin_amdgcn_s_setprio(0); } while (0)
; #define PG8_WAIT_V(n) asm volatile("s_waitcnt vmcnt(" #n ")" ::: "memory")
; #define PG8_WAIT_L(n) asm volatile("s_waitcnt lgkmcnt(" #n ")" ::: "memory")
; #define PG8_BAR __builtin_amdgcn_s_barrier()
; #define PG8_SCHED __builtin_amdgcn_sched_barrier(0)
; template <class Epi, class Sched, bool ALIGN_EPI = true, bool SP2 = true>
; __device__ __forceinline__ void gemm_phase(LAS unsigned char* lds, const bf16_t* Ag, const bf16_t* Btg, const int K, const int lda, const int ldb, const Sched& S, const Epi& E) {
;     ...
;             PG8_WAIT_V(8); PG8_WAIT_L(0); PG8_BAR; PG8_MMA(1, 0, At, B0); PG8_MMA(1, 1, At, B1); PG8_BAR; PG8_SCHED;
;             PG8_LDB(B0, 1, 0); PG8_LDB(B1, 1, 1); PG8_SCHED; PG8_LDA(At, 1, 0); PG8_STAGE(PG8_SA(0, 1), a2 + hstepA, voffA);
;             PG8_WAIT_V(8); PG8_WAIT_L(0); PG8_BAR; PG8_MMA(0, 0, At, B0); PG8_MMA(0, 1, At, B1); PG8_BAR; PG8_SCHED;
	s_setprio 1
	s_waitcnt lgkmcnt(0)
	v_mfma_f32_16x16x32_bf16 v[100:103], v[80:83], v[190:193], v[100:103]
	v_mfma_f32_16x16x32_bf16 v[96:99], v[136:139], v[190:193], v[96:99]
	v_mfma_f32_16x16x32_bf16 v[92:95], v[80:83], v[198:201], v[92:95]
	v_mfma_f32_16x16x32_bf16 v[88:91], v[136:139], v[198:201], v[88:91]
	v_mfma_f32_16x16x32_bf16 v[76:79], v[80:83], v[206:209], v[76:79]
	v_mfma_f32_16x16x32_bf16 v[72:75], v[136:139], v[206:209], v[72:75]
	v_mfma_f32_16x16x32_bf16 v[68:71], v[80:83], v[214:217], v[68:71]
	v_mfma_f32_16x16x32_bf16 v[64:67], v[136:139], v[214:217], v[64:67]
	v_mfma_f32_16x16x32_bf16 v[100:103], v[84:87], v[194:197], v[100:103]
	v_mfma_f32_16x16x32_bf16 v[96:99], v[140:143], v[194:197], v[96:99]
	v_mfma_f32_16x16x32_bf16 v[92:95], v[84:87], v[202:205], v[92:95]
	v_mfma_f32_16x16x32_bf16 v[88:91], v[140:143], v[202:205], v[88:91]
	v_mfma_f32_16x16x32_bf16 v[76:79], v[84:87], v[210:213], v[76:79]
	v_mfma_f32_16x16x32_bf16 v[72:75], v[140:143], v[210:213], v[72:75]
	v_mfma_f32_16x16x32_bf16 v[68:71], v[84:87], v[218:221], v[68:71]
	v_mfma_f32_16x16x32_bf16 v[64:67], v[140:143], v[218:221], v[64:67]
	s_setprio 0
	s_setprio 1
	v_mfma_f32_16x16x32_bf16 v[28:31], v[164:167], v[190:193], v[28:31]
	v_mfma_f32_16x16x32_bf16 v[24:27], v[172:175], v[190:193], v[24:27]
	v_mfma_f32_16x16x32_bf16 v[20:23], v[164:167], v[198:201], v[20:23]
	v_mfma_f32_16x16x32_bf16 v[16:19], v[172:175], v[198:201], v[16:19]
	v_mfma_f32_16x16x32_bf16 v[12:15], v[164:167], v[206:209], v[12:15]
	v_mfma_f32_16x16x32_bf16 v[8:11], v[172:175], v[206:209], v[8:11]
	v_mfma_f32_16x16x32_bf16 v[4:7], v[164:167], v[214:217], v[4:7]
	v_mfma_f32_16x16x32_bf16 v[0:3], v[172:175], v[214:217], v[0:3]
	v_mfma_f32_16x16x32_bf16 v[28:31], v[168:171], v[194:197], v[28:31]
	v_mfma_f32_16x16x32_bf16 v[24:27], v[186:189], v[194:197], v[24:27]
	v_mfma_f32_16x16x32_bf16 v[20:23], v[168:171], v[202:205], v[20:23]
	v_mfma_f32_16x16x32_bf16 v[16:19], v[186:189], v[202:205], v[16:19]
	v_mfma_f32_16x16x32_bf16 v[12:15], v[168:171], v[210:213], v[12:15]
	v_mfma_f32_16x16x32_bf16 v[8:11], v[186:189], v[210:213], v[8:11]
	s_setprio 2
	s_barrier
	v_mfma_f32_16x16x32_bf16 v[4:7], v[168:171], v[218:221], v[4:7]
	v_mfma_f32_16x16x32_bf16 v[0:3], v[186:189], v[218:221], v[0:3]
	s_setprio 0
	s_add_i32 s39, 0, 0x18000
	s_add_i32 s40, 0, 0x1c000
	v_add_u32_e32 v140, s39, v180
	v_add_u32_e32 v152, s40, v180
	ds_read_b128 v[80:83], v140
	ds_read_b128 v[84:87], v140 offset:1024
	ds_read_b128 v[136:139], v140 offset:2048
	ds_read_b128 v[140:143], v140 offset:3072
	ds_read_b128 v[164:167], v152
	ds_read_b128 v[168:171], v152 offset:1024
	ds_read_b128 v[172:175], v152 offset:2048
	ds_read_b128 v[186:189], v152 offset:3072
	s_add_u32 s34, s34, 0x80000
	s_addc_u32 s35, s35, 0
	s_mov_b32 m0, s58
	v_lshl_add_u64 v[230:231], s[34:35], 0, v[144:145]
	ds_read_b128 v[190:193], v184 offset:32768
	ds_read_b128 v[194:197], v184 offset:33792
	ds_read_b128 v[198:201], v184 offset:34816
	ds_read_b128 v[202:205], v184 offset:35840
	ds_read_b128 v[206:209], v184 offset:36864
	ds_read_b128 v[210:213], v184 offset:37888
	ds_read_b128 v[214:217], v184 offset:38912
	ds_read_b128 v[218:221], v184 offset:39936
	global_load_lds_dwordx4 v[230:231], off
	v_lshl_add_u64 v[230:231], s[34:35], 0, v[148:149]
	s_mov_b32 m0, s59
	s_nop 0
	global_load_lds_dwordx4 v[230:231], off
	s_waitcnt vmcnt(8)
	s_waitcnt lgkmcnt(0)
	s_barrier
	s_setprio 1
	s_waitcnt lgkmcnt(0)
	v_mfma_f32_16x16x32_bf16 v[132:135], v[80:83], v[190:193], v[132:135]
	v_mfma_f32_16x16x32_bf16 v[128:131], v[136:139], v[190:193], v[128:131]
	v_mfma_f32_16x16x32_bf16 v[124:127], v[80:83], v[198:201], v[124:127]
	v_mfma_f32_16x16x32_bf16 v[120:123], v[136:139], v[198:201], v[120:123]
	v_mfma_f32_16x16x32_bf16 v[116:119], v[80:83], v[206:209], v[116:119]
	v_mfma_f32_16x16x32_bf16 v[112:115], v[136:139], v[206:209], v[112:115]
	v_mfma_f32_16x16x32_bf16 v[108:111], v[80:83], v[214:217], v[108:111]
	v_mfma_f32_16x16x32_bf16 v[104:107], v[136:139], v[214:217], v[104:107]
	v_mfma_f32_16x16x32_bf16 v[132:135], v[84:87], v[194:197], v[132:135]
	v_mfma_f32_16x16x32_bf16 v[128:131], v[140:143], v[194:197], v[128:131]
	v_mfma_f32_16x16x32_bf16 v[124:127], v[84:87], v[202:205], v[124:127]
	v_mfma_f32_16x16x32_bf16 v[120:123], v[140:143], v[202:205], v[120:123]
	v_mfma_f32_16x16x32_bf16 v[116:119], v[84:87], v[210:213], v[116:119]
	v_mfma_f32_16x16x32_bf16 v[112:115], v[140:143], v[210:213], v[112:115]
	v_mfma_f32_16x16x32_bf16 v[108:111], v[84:87], v[218:221], v[108:111]
	v_mfma_f32_16x16x32_bf16 v[104:107], v[140:143], v[218:221], v[104:107]
	s_setprio 0
	s_setprio 1
	v_mfma_f32_16x16x32_bf16 v[60:63], v[164:167], v[190:193], v[60:63]
	v_mfma_f32_16x16x32_bf16 v[56:59], v[172:175], v[190:193], v[56:59]
	v_mfma_f32_16x16x32_bf16 v[52:55], v[164:167], v[198:201], v[52:55]
	v_mfma_f32_16x16x32_bf16 v[48:51], v[172:175], v[198:201], v[48:51]
	v_mfma_f32_16x16x32_bf16 v[44:47], v[164:167], v[206:209], v[44:47]
	v_mfma_f32_16x16x32_bf16 v[40:43], v[172:175], v[206:209], v[40:43]
	v_mfma_f32_16x16x32_bf16 v[36:39], v[164:167], v[214:217], v[36:39]
	v_mfma_f32_16x16x32_bf16 v[32:35], v[172:175], v[214:217], v[32:35]
	v_mfma_f32_16x16x32_bf16 v[60:63], v[168:171], v[194:197], v[60:63]
	v_mfma_f32_16x16x32_bf16 v[56:59], v[186:189], v[194:197], v[56:59]
	v_mfma_f32_16x16x32_bf16 v[52:55], v[168:171], v[202:205], v[52:55]
	v_mfma_f32_16x16x32_bf16 v[48:51], v[186:189], v[202:205], v[48:51]
	v_mfma_f32_16x16x32_bf16 v[44:47], v[168:171], v[210:213], v[44:47]
	v_mfma_f32_16x16x32_bf16 v[40:43], v[186:189], v[210:213], v[40:43]
	s_setprio 2
	s_barrier
; #define PG8_STAGE(bufoff, gbase, voff) do { _Pragma("unroll") for (int _i = 0; _i < 2; ++_i) \
;         __builtin_amdgcn_global_load_lds((const unsigned*)((const char*)(gbase) + (voff)[_i]), (LAS unsigned*)(lds + (bufoff) + ldsw + _i * 8192), 16, 0, 0); } while (0)
; #define PG8_LDA(dst, b, h) do { _Pragma("unroll") for (int m = 0; m < 4; ++m) _Pragma("unroll") for (int k = 0; k < 2; ++k) dst[m][k] = *(const LAS bf16x8*)(lds + PG8_SA(b, h) + aoff + m * 2048 + k * 1024); } while (0)
; #define PG8_MMA(ai, bj, At, Bt) do { __builtin_amdgcn_s_setprio(1); _Pragma("unroll") for (int m = 0; m < 4; ++m) _Pragma("unroll") for (int n = 0; n < 2; ++n) _Pragma("unroll") for (int k = 0; k < 2; ++k) \
;         acc[ai][bj][m][n] = __builtin_amdgcn_mfma_f32_16x16x32_bf16(Bt[n][k], At[m][k], acc[ai][bj][m][n], 0, 0, 0); __builtin_amdgcn_s_setprio(0); } while (0)
; #define PG8_WAIT_V(n) asm volatile("s_waitcnt vmcnt(" #n ")" ::: "memory")
; #define PG8_WAIT_L(n) asm volatile("s_waitcnt lgkmcnt(" #n ")" ::: "memory")
; #define PG8_BAR __builtin_amdgcn_s_barrier()
; #define PG8_SCHED __builtin_amdgcn_sched_barrier(0)
; template <class Epi, class Sched, bool ALIGN_EPI = true, bool SP2 = true>
; __device__ __forceinline__ void gemm_phase(LAS unsigned char* lds, const bf16_t* Ag, const bf16_t* Btg, const int K, const int lda, const int ldb, const Sched& S, const Epi& E) {
;     ...
;         for (int t = 0; t < nt; t += 2) {
;     ...
;             PG8_WAIT_V(8); PG8_WAIT_L(0); PG8_BAR; PG8_MMA(0, 0, At, B0); PG8_MMA(0, 1, At, B1); PG8_BAR; PG8_SCHED;
;             PG8_LDA(At, 1, 1); PG8_STAGE(PG8_SB(1, 0), b3, voffB); PG8_STAGE(PG8_SB(1, 1), b3 + hstepB, voffB); PG8_STAGE(PG8_SA(1, 0), a3, voffA);
;             PG8_WAIT_V(8); PG8_WAIT_L(0); PG8_BAR; PG8_MMA(1, 0, At, B0); PG8_MMA(1, 1, At, B1); PG8_BAR; PG8_SCHED;
	v_mfma_f32_16x16x32_bf16 v[36:39], v[168:171], v[218:221], v[36:39]
	v_mfma_f32_16x16x32_bf16 v[32:35], v[186:189], v[218:221], v[32:35]
	s_setprio 0
	s_add_i32 s34, s39, s37
	v_lshl_add_u64 v[222:223], v[222:223], 0, s[16:17]
	s_mov_b32 m0, s34
	ds_read_b128 v[190:193], v184 offset:49152
	ds_read_b128 v[194:197], v184 offset:50176
	ds_read_b128 v[198:201], v184 offset:51200
	ds_read_b128 v[202:205], v184 offset:52224
	ds_read_b128 v[206:209], v184 offset:53248
	ds_read_b128 v[210:213], v184 offset:54272
	ds_read_b128 v[214:217], v184 offset:55296
	ds_read_b128 v[218:221], v184 offset:56320
	global_load_lds_dwordx4 v[222:223], off
	s_add_i32 m0, s34, 0x2000
	s_add_u32 s6, s6, 0x80080
	v_lshl_add_u64 v[222:223], v[224:225], 0, s[16:17]
	s_addc_u32 s7, s7, 0
	s_add_i32 s34, s40, s37
	global_load_lds_dwordx4 v[222:223], off
	v_lshl_add_u64 v[222:223], s[6:7], 0, v[146:147]
	s_mov_b32 m0, s34
	s_nop 0
	global_load_lds_dwordx4 v[222:223], off
	v_lshl_add_u64 v[222:223], s[6:7], 0, v[150:151]
	s_add_i32 m0, s34, 0x2000
	s_nop 0
	global_load_lds_dwordx4 v[222:223], off
	v_lshl_add_u64 v[222:223], v[226:227], 0, s[16:17]
	s_mov_b32 m0, s61
	s_nop 0
	global_load_lds_dwordx4 v[222:223], off
	v_lshl_add_u64 v[222:223], v[228:229], 0, s[16:17]
	s_mov_b32 m0, s70
	s_nop 0
	global_load_lds_dwordx4 v[222:223], off
	s_waitcnt vmcnt(8)
	s_waitcnt lgkmcnt(0)
	s_barrier
	s_setprio 1
	s_waitcnt lgkmcnt(0)
	v_mfma_f32_16x16x32_bf16 v[100:103], v[80:83], v[190:193], v[100:103]
	s_add_i32 s38, s38, 2
	s_add_u32 s4, s4, 0x100
	s_addc_u32 s5, s5, 0
	s_add_u32 s23, s23, 0x100
	s_addc_u32 s33, s33, 0
	s_cmp_gt_u32 s38, 29
	v_mfma_f32_16x16x32_bf16 v[96:99], v[136:139], v[190:193], v[96:99]
	v_mfma_f32_16x16x32_bf16 v[92:95], v[80:83], v[198:201], v[92:95]
	v_mfma_f32_16x16x32_bf16 v[88:91], v[136:139], v[198:201], v[88:91]
	v_mfma_f32_16x16x32_bf16 v[76:79], v[80:83], v[206:209], v[76:79]
	v_mfma_f32_16x16x32_bf16 v[72:75], v[136:139], v[206:209], v[72:75]
	v_mfma_f32_16x16x32_bf16 v[68:71], v[80:83], v[214:217], v[68:71]
	v_mfma_f32_16x16x32_bf16 v[64:67], v[136:139], v[214:217], v[64:67]
	v_mfma_f32_16x16x32_bf16 v[100:103], v[84:87], v[194:197], v[100:103]
	v_mfma_f32_16x16x32_bf16 v[96:99], v[140:143], v[194:197], v[96:99]
	v_mfma_f32_16x16x32_bf16 v[92:95], v[84:87], v[202:205], v[92:95]
	v_mfma_f32_16x16x32_bf16 v[88:91], v[140:143], v[202:205], v[88:91]
	v_mfma_f32_16x16x32_bf16 v[76:79], v[84:87], v[210:213], v[76:79]
	v_mfma_f32_16x16x32_bf16 v[72:75], v[140:143], v[210:213], v[72:75]
	v_mfma_f32_16x16x32_bf16 v[68:71], v[84:87], v[218:221], v[68:71]
	v_mfma_f32_16x16x32_bf16 v[64:67], v[140:143], v[218:221], v[64:67]
	s_setprio 0
	s_setprio 1
	v_mfma_f32_16x16x32_bf16 v[28:31], v[164:167], v[190:193], v[28:31]
	v_mfma_f32_16x16x32_bf16 v[24:27], v[172:175], v[190:193], v[24:27]
	v_mfma_f32_16x16x32_bf16 v[20:23], v[164:167], v[198:201], v[20:23]
	v_mfma_f32_16x16x32_bf16 v[16:19], v[172:175], v[198:201], v[16:19]
	v_mfma_f32_16x16x32_bf16 v[12:15], v[164:167], v[206:209], v[12:15]
	v_mfma_f32_16x16x32_bf16 v[8:11], v[172:175], v[206:209], v[8:11]
	v_mfma_f32_16x16x32_bf16 v[4:7], v[164:167], v[214:217], v[4:7]
	v_mfma_f32_16x16x32_bf16 v[0:3], v[172:175], v[214:217], v[0:3]
	v_mfma_f32_16x16x32_bf16 v[28:31], v[168:171], v[194:197], v[28:31]
	v_mfma_f32_16x16x32_bf16 v[24:27], v[186:189], v[194:197], v[24:27]
	v_mfma_f32_16x16x32_bf16 v[20:23], v[168:171], v[202:205], v[20:23]
	v_mfma_f32_16x16x32_bf16 v[16:19], v[186:189], v[202:205], v[16:19]
	v_mfma_f32_16x16x32_bf16 v[12:15], v[168:171], v[210:213], v[12:15]
	v_mfma_f32_16x16x32_bf16 v[8:11], v[186:189], v[210:213], v[8:11]
	s_setprio 2
	s_barrier
	v_mfma_f32_16x16x32_bf16 v[4:7], v[168:171], v[218:221], v[4:7]
	v_mfma_f32_16x16x32_bf16 v[0:3], v[186:189], v[218:221], v[0:3]
	s_setprio 0
	s_cbranch_scc0 .LBB0_387
	s_and_b64 vcc, exec, s[18:19]
	s_cbranch_vccz .LBB0_390
	s_barrier

; #define PG8_STAGE(bufoff, gbase, voff) do { _Pragma("unroll") for (int _i = 0; _i < 2; ++_i) \
;         __builtin_amdgcn_global_load_lds((const unsigned*)((const char*)(gbase) + (voff)[_i]), (LAS unsigned*)(lds + (bufoff) + ldsw + _i * 8192), 16, 0, 0); } while (0)
; #define PG8_LDA(dst, b, h) do { _Pragma("unroll") for (int m = 0; m < 4; ++m) _Pragma("unroll") for (int k = 0; k < 2; ++k) dst[m][k] = *(const LAS bf16x8*)(lds + PG8_SA(b, h) + aoff + m * 2048 + k * 1024); } while (0)
; #define PG8_LDB(dst, b, h) do { _Pragma("unroll") for (int n = 0; n < 2; ++n) _Pragma("unroll") for (int k = 0; k < 2; ++k) dst[n][k] = *(const LAS bf16x8*)(lds + PG8_SB(b, h) + boff + n * 2048 + k * 1024); } while (0)
; #define PG8_MMA(ai, bj, At, Bt) do { __builtin_amdgcn_s_setprio(1); _Pragma("unroll") for (int m = 0; m < 4; ++m) _Pragma("unroll") for (int n = 0; n < 2; ++n) _Pragma("unroll") for (int k = 0; k < 2; ++k) \
;         acc[ai][bj][m][n] = __builtin_amdgcn_mfma_f32_16x16x32_bf16(Bt[n][k], At[m][k], acc[ai][bj][m][n], 0, 0, 0); __builtin_amdgcn_s_setprio(0); } while (0)
; #define PG8_WAIT_V(n) asm volatile("s_waitcnt vmcnt(" #n ")" ::: "memory")
; #define PG8_BAR __builtin_amdgcn_s_barrier()
; template <class Epi, class Sched, bool ALIGN_EPI = true, bool SP2 = true>
; __device__ __forceinline__ void gemm_phase(LAS unsigned char* lds, const bf16_t* Ag, const bf16_t* Btg, const int K, const int lda, const int ldb, const Sched& S, const Epi& E) {
;     ...
;         for (int t = 0; t < nt; t += 2) {
;             const bool last = (t == nt - 2);
;             const char* a1 = cA + (size_t)(t + 1) * kstep;
;             const char* a2 = last ? nA : cA + (size_t)(t + 2) * kstep; const char* b2 = last ? nB : cB + (size_t)(t + 2) * kstep;
;             const char* a3 = a2 + kstep; const char* b3 = b2 + kstep;
;             if constexpr (SP2) {
;             PG8_LDB(B0, 0, 0); PG8_LDB(B1, 0, 1); PG8_SCHED; PG8_LDA(At, 0, 0); PG8_STAGE(PG8_SA(1, 1), a1 + hstepA, voffA);
;             PG8_WAIT_V(8); PG8_WAIT_L(0); PG8_BAR; PG8_MMA(0, 0, At, B0); PG8_MMA(0, 1, At, B1); PG8_BAR; PG8_SCHED;
;             PG8_LDA(At, 0, 1); PG8_STAGE(PG8_SB(0, 0), b2, voffB); PG8_STAGE(PG8_SB(0, 1), b2 + hstepB, voffB); PG8_STAGE(PG8_SA(0, 0), a2, voffA);
;             PG8_WAIT_V(8); PG8_WAIT_L(0); PG8_BAR; PG8_MMA(1, 0, At, B0); PG8_MMA(1, 1, At, B1); PG8_BAR; PG8_SCHED;
.LBB0_787:
	ds_read_b128 v[108:111], v170
	ds_read_b128 v[112:115], v170 offset:1024
	ds_read_b128 v[154:157], v170 offset:2048
	ds_read_b128 v[158:161], v170 offset:3072
	ds_read_b128 v[162:165], v171
	ds_read_b128 v[180:183], v171 offset:1024
	ds_read_b128 v[184:187], v171 offset:2048
	ds_read_b128 v[188:191], v171 offset:3072
	s_add_u32 s26, s24, 0xfff80080
	s_addc_u32 s27, s25, -1
	s_cmp_eq_u32 s53, 28
	s_cselect_b32 s29, s11, s27
	s_cselect_b32 s28, s13, s26
	s_cselect_b32 s27, s33, s52
	s_cselect_b32 s26, s50, s51
	v_lshl_add_u64 v[174:175], s[24:25], 0, v[146:147]
	s_add_i32 m0, s37, 0xc000
	ds_read_b128 v[192:195], v172
	ds_read_b128 v[196:199], v172 offset:1024
	ds_read_b128 v[200:203], v172 offset:2048
	ds_read_b128 v[204:207], v172 offset:3072
	ds_read_b128 v[208:211], v172 offset:4096
	ds_read_b128 v[212:215], v172 offset:5120
	ds_read_b128 v[216:219], v172 offset:6144
	ds_read_b128 v[220:223], v172 offset:7168
	global_load_lds_dwordx4 v[174:175], off
	v_lshl_add_u64 v[174:175], s[24:25], 0, v[148:149]
	s_add_i32 m0, s37, 0xe000
	s_nop 0
	global_load_lds_dwordx4 v[174:175], off
	s_waitcnt vmcnt(8)
	s_waitcnt lgkmcnt(0)
	s_barrier
	s_setprio 1
	s_waitcnt lgkmcnt(0)
	v_mfma_f32_16x16x32_bf16 v[132:135], v[108:111], v[192:195], v[132:135]
	v_mfma_f32_16x16x32_bf16 v[128:131], v[154:157], v[192:195], v[128:131]
	v_mfma_f32_16x16x32_bf16 v[124:127], v[108:111], v[200:203], v[124:127]
	v_mfma_f32_16x16x32_bf16 v[120:123], v[154:157], v[200:203], v[120:123]
	v_mfma_f32_16x16x32_bf16 v[116:119], v[108:111], v[208:211], v[116:119]
	v_mfma_f32_16x16x32_bf16 v[104:107], v[154:157], v[208:211], v[104:107]
	v_mfma_f32_16x16x32_bf16 v[100:103], v[108:111], v[216:219], v[100:103]
	v_mfma_f32_16x16x32_bf16 v[96:99], v[154:157], v[216:219], v[96:99]
	v_mfma_f32_16x16x32_bf16 v[132:135], v[112:115], v[196:199], v[132:135]
	v_mfma_f32_16x16x32_bf16 v[128:131], v[158:161], v[196:199], v[128:131]
	v_mfma_f32_16x16x32_bf16 v[124:127], v[112:115], v[204:207], v[124:127]
	v_mfma_f32_16x16x32_bf16 v[120:123], v[158:161], v[204:207], v[120:123]
	v_mfma_f32_16x16x32_bf16 v[116:119], v[112:115], v[212:215], v[116:119]
	v_mfma_f32_16x16x32_bf16 v[104:107], v[158:161], v[212:215], v[104:107]
	v_mfma_f32_16x16x32_bf16 v[100:103], v[112:115], v[220:223], v[100:103]
	v_mfma_f32_16x16x32_bf16 v[96:99], v[158:161], v[220:223], v[96:99]
	s_setprio 0
	s_setprio 1
	v_mfma_f32_16x16x32_bf16 v[60:63], v[162:165], v[192:195], v[60:63]
	v_mfma_f32_16x16x32_bf16 v[56:59], v[184:187], v[192:195], v[56:59]
	v_mfma_f32_16x16x32_bf16 v[52:55], v[162:165], v[200:203], v[52:55]
	v_mfma_f32_16x16x32_bf16 v[48:51], v[184:187], v[200:203], v[48:51]
	v_mfma_f32_16x16x32_bf16 v[44:47], v[162:165], v[208:211], v[44:47]
	v_mfma_f32_16x16x32_bf16 v[40:43], v[184:187], v[208:211], v[40:43]
	v_mfma_f32_16x16x32_bf16 v[36:39], v[162:165], v[216:219], v[36:39]
	v_mfma_f32_16x16x32_bf16 v[32:35], v[184:187], v[216:219], v[32:35]
	v_mfma_f32_16x16x32_bf16 v[60:63], v[180:183], v[196:199], v[60:63]
	v_mfma_f32_16x16x32_bf16 v[56:59], v[188:191], v[196:199], v[56:59]
	v_mfma_f32_16x16x32_bf16 v[52:55], v[180:183], v[204:207], v[52:55]
	v_mfma_f32_16x16x32_bf16 v[48:51], v[188:191], v[204:207], v[48:51]
	v_mfma_f32_16x16x32_bf16 v[44:47], v[180:183], v[212:215], v[44:47]
	v_mfma_f32_16x16x32_bf16 v[40:43], v[188:191], v[212:215], v[40:43]
	s_setprio 2
	s_barrier
	v_mfma_f32_16x16x32_bf16 v[36:39], v[180:183], v[220:223], v[36:39]
	v_mfma_f32_16x16x32_bf16 v[32:35], v[188:191], v[220:223], v[32:35]
	s_setprio 0
	s_add_i32 s54, s46, s35
	v_lshl_add_u64 v[174:175], s[26:27], 0, v[138:139]
	s_mov_b32 m0, s54
	ds_read_b128 v[192:195], v172 offset:16384
	ds_read_b128 v[196:199], v172 offset:17408
	ds_read_b128 v[200:203], v172 offset:18432
	ds_read_b128 v[204:207], v172 offset:19456
	ds_read_b128 v[208:211], v172 offset:20480
	ds_read_b128 v[212:215], v172 offset:21504
	ds_read_b128 v[216:219], v172 offset:22528
	ds_read_b128 v[220:223], v172 offset:23552
	global_load_lds_dwordx4 v[174:175], off
	s_add_i32 m0, s54, 0x2000
	s_add_u32 s54, s26, 0x80000
	v_lshl_add_u64 v[224:225], s[26:27], 0, v[142:143]
	s_addc_u32 s55, s27, 0
	s_add_i32 s58, s47, s35
	global_load_lds_dwordx4 v[224:225], off
	v_lshl_add_u64 v[226:227], s[54:55], 0, v[138:139]
	s_mov_b32 m0, s58
	v_lshl_add_u64 v[228:229], s[28:29], 0, v[140:141]
	global_load_lds_dwordx4 v[226:227], off
	v_lshl_add_u64 v[226:227], s[54:55], 0, v[142:143]
	s_add_i32 m0, s58, 0x2000
	s_nop 0
	global_load_lds_dwordx4 v[226:227], off
	v_lshl_add_u64 v[226:227], s[28:29], 0, v[136:137]
	s_mov_b32 m0, s37
	s_nop 0
	global_load_lds_dwordx4 v[226:227], off
	s_mov_b32 m0, s38
	s_nop 0
	global_load_lds_dwordx4 v[228:229], off
	s_waitcnt vmcnt(8)
	s_waitcnt lgkmcnt(0)
	s_barrier
; #define PG8_STAGE(bufoff, gbase, voff) do { _Pragma("unroll") for (int _i = 0; _i < 2; ++_i) \
;         __builtin_amdgcn_global_load_lds((const unsigned*)((const char*)(gbase) + (voff)[_i]), (LAS unsigned*)(lds + (bufoff) + ldsw + _i * 8192), 16, 0, 0); } while (0)
; #define PG8_LDA(dst, b, h) do { _Pragma("unroll") for (int m = 0; m < 4; ++m) _Pragma("unroll") for (int k = 0; k < 2; ++k) dst[m][k] = *(const LAS bf16x8*)(lds + PG8_SA(b, h) + aoff + m * 2048 + k * 1024); } while (0)
; #define PG8_LDB(dst, b, h) do { _Pragma("unroll") for (int n = 0; n < 2; ++n) _Pragma("unroll") for (int k = 0; k < 2; ++k) dst[n][k] = *(const LAS bf16x8*)(lds + PG8_SB(b, h) + boff + n * 2048 + k * 1024); } while (0)
; #define PG8_MMA(ai, bj, At, Bt) do { __builtin_amdgcn_s_setprio(1); _Pragma("unroll") for (int m = 0; m < 4; ++m) _Pragma("unroll") for (int n = 0; n < 2; ++n) _Pragma("unroll") for (int k = 0; k < 2; ++k) \
;         acc[ai][bj][m][n] = __builtin_amdgcn_mfma_f32_16x16x32_bf16(Bt[n][k], At[m][k], acc[ai][bj][m][n], 0, 0, 0); __builtin_amdgcn_s_setprio(0); } while (0)
; #define PG8_WAIT_V(n) asm volatile("s_waitcnt vmcnt(" #n ")" ::: "memory")
; #define PG8_WAIT_L(n) asm volatile("s_waitcnt lgkmcnt(" #n ")" ::: "memory")
; #define PG8_BAR __builtin_amdgcn_s_barrier()
; #define PG8_SCHED __builtin_amdgcn_sched_barrier(0)
; template <class Epi, class Sched, bool ALIGN_EPI = true, bool SP2 = true>
; __device__ __forceinline__ void gemm_phase(LAS unsigned char* lds, const bf16_t* Ag, const bf16_t* Btg, const int K, const int lda, const int ldb, const Sched& S, const Epi& E) {
;     ...
;             PG8_WAIT_V(8); PG8_WAIT_L(0); PG8_BAR; PG8_MMA(1, 0, At, B0); PG8_MMA(1, 1, At, B1); PG8_BAR; PG8_SCHED;
;             PG8_LDB(B0, 1, 0); PG8_LDB(B1, 1, 1); PG8_SCHED; PG8_LDA(At, 1, 0); PG8_STAGE(PG8_SA(0, 1), a2 + hstepA, voffA);
;             PG8_WAIT_V(8); PG8_WAIT_L(0); PG8_BAR; PG8_MMA(0, 0, At, B0); PG8_MMA(0, 1, At, B1); PG8_BAR; PG8_SCHED;
	s_setprio 1
	s_waitcnt lgkmcnt(0)
	v_mfma_f32_16x16x32_bf16 v[92:95], v[108:111], v[192:195], v[92:95]
	v_mfma_f32_16x16x32_bf16 v[88:91], v[154:157], v[192:195], v[88:91]
	v_mfma_f32_16x16x32_bf16 v[84:87], v[108:111], v[200:203], v[84:87]
	v_mfma_f32_16x16x32_bf16 v[80:83], v[154:157], v[200:203], v[80:83]
	v_mfma_f32_16x16x32_bf16 v[76:79], v[108:111], v[208:211], v[76:79]
	v_mfma_f32_16x16x32_bf16 v[72:75], v[154:157], v[208:211], v[72:75]
	v_mfma_f32_16x16x32_bf16 v[68:71], v[108:111], v[216:219], v[68:71]
	v_mfma_f32_16x16x32_bf16 v[64:67], v[154:157], v[216:219], v[64:67]
	v_mfma_f32_16x16x32_bf16 v[92:95], v[112:115], v[196:199], v[92:95]
	v_mfma_f32_16x16x32_bf16 v[88:91], v[158:161], v[196:199], v[88:91]
	v_mfma_f32_16x16x32_bf16 v[84:87], v[112:115], v[204:207], v[84:87]
	v_mfma_f32_16x16x32_bf16 v[80:83], v[158:161], v[204:207], v[80:83]
	v_mfma_f32_16x16x32_bf16 v[76:79], v[112:115], v[212:215], v[76:79]
	v_mfma_f32_16x16x32_bf16 v[72:75], v[158:161], v[212:215], v[72:75]
	v_mfma_f32_16x16x32_bf16 v[68:71], v[112:115], v[220:223], v[68:71]
	v_mfma_f32_16x16x32_bf16 v[64:67], v[158:161], v[220:223], v[64:67]
	s_setprio 0
	s_setprio 1
	v_mfma_f32_16x16x32_bf16 v[28:31], v[162:165], v[192:195], v[28:31]
	v_mfma_f32_16x16x32_bf16 v[24:27], v[184:187], v[192:195], v[24:27]
	v_mfma_f32_16x16x32_bf16 v[20:23], v[162:165], v[200:203], v[20:23]
	v_mfma_f32_16x16x32_bf16 v[16:19], v[184:187], v[200:203], v[16:19]
	v_mfma_f32_16x16x32_bf16 v[12:15], v[162:165], v[208:211], v[12:15]
	v_mfma_f32_16x16x32_bf16 v[8:11], v[184:187], v[208:211], v[8:11]
	v_mfma_f32_16x16x32_bf16 v[4:7], v[162:165], v[216:219], v[4:7]
	v_mfma_f32_16x16x32_bf16 v[0:3], v[184:187], v[216:219], v[0:3]
	v_mfma_f32_16x16x32_bf16 v[28:31], v[180:183], v[196:199], v[28:31]
	v_mfma_f32_16x16x32_bf16 v[24:27], v[188:191], v[196:199], v[24:27]
	v_mfma_f32_16x16x32_bf16 v[20:23], v[180:183], v[204:207], v[20:23]
	v_mfma_f32_16x16x32_bf16 v[16:19], v[188:191], v[204:207], v[16:19]
	v_mfma_f32_16x16x32_bf16 v[12:15], v[180:183], v[212:215], v[12:15]
	v_mfma_f32_16x16x32_bf16 v[8:11], v[188:191], v[212:215], v[8:11]
	s_setprio 2
	s_barrier
	v_mfma_f32_16x16x32_bf16 v[4:7], v[180:183], v[220:223], v[4:7]
	v_mfma_f32_16x16x32_bf16 v[0:3], v[188:191], v[220:223], v[0:3]
	s_setprio 0
	s_add_i32 s54, 0, 0x18000
	s_add_i32 s55, 0, 0x1c000
	v_add_u32_e32 v158, s54, v168
	v_add_u32_e32 v173, s55, v168
	ds_read_b128 v[108:111], v158
	ds_read_b128 v[112:115], v158 offset:1024
	ds_read_b128 v[154:157], v158 offset:2048
	ds_read_b128 v[158:161], v158 offset:3072
	ds_read_b128 v[162:165], v173
	ds_read_b128 v[180:183], v173 offset:1024
	ds_read_b128 v[184:187], v173 offset:2048
	ds_read_b128 v[188:191], v173 offset:3072
	s_add_u32 s28, s28, 0x80000
	s_addc_u32 s29, s29, 0
	s_mov_b32 m0, s39
	v_lshl_add_u64 v[230:231], s[28:29], 0, v[136:137]
	ds_read_b128 v[192:195], v172 offset:32768
	ds_read_b128 v[196:199], v172 offset:33792
	ds_read_b128 v[200:203], v172 offset:34816
	ds_read_b128 v[204:207], v172 offset:35840
	ds_read_b128 v[208:211], v172 offset:36864
	ds_read_b128 v[212:215], v172 offset:37888
	ds_read_b128 v[216:219], v172 offset:38912
	ds_read_b128 v[220:223], v172 offset:39936
	global_load_lds_dwordx4 v[230:231], off
	v_lshl_add_u64 v[230:231], s[28:29], 0, v[140:141]
	s_mov_b32 m0, s40
	s_nop 0
	global_load_lds_dwordx4 v[230:231], off
	s_waitcnt vmcnt(8)
	s_waitcnt lgkmcnt(0)
	s_barrier
	s_setprio 1
	s_waitcnt lgkmcnt(0)
	v_mfma_f32_16x16x32_bf16 v[132:135], v[108:111], v[192:195], v[132:135]
	v_mfma_f32_16x16x32_bf16 v[128:131], v[154:157], v[192:195], v[128:131]
	v_mfma_f32_16x16x32_bf16 v[124:127], v[108:111], v[200:203], v[124:127]
	v_mfma_f32_16x16x32_bf16 v[120:123], v[154:157], v[200:203], v[120:123]
	v_mfma_f32_16x16x32_bf16 v[116:119], v[108:111], v[208:211], v[116:119]
	v_mfma_f32_16x16x32_bf16 v[104:107], v[154:157], v[208:211], v[104:107]
	v_mfma_f32_16x16x32_bf16 v[100:103], v[108:111], v[216:219], v[100:103]
	v_mfma_f32_16x16x32_bf16 v[96:99], v[154:157], v[216:219], v[96:99]
	v_mfma_f32_16x16x32_bf16 v[132:135], v[112:115], v[196:199], v[132:135]
	v_mfma_f32_16x16x32_bf16 v[128:131], v[158:161], v[196:199], v[128:131]
	v_mfma_f32_16x16x32_bf16 v[124:127], v[112:115], v[204:207], v[124:127]
	v_mfma_f32_16x16x32_bf16 v[120:123], v[158:161], v[204:207], v[120:123]
	v_mfma_f32_16x16x32_bf16 v[116:119], v[112:115], v[212:215], v[116:119]
	v_mfma_f32_16x16x32_bf16 v[104:107], v[158:161], v[212:215], v[104:107]
	v_mfma_f32_16x16x32_bf16 v[100:103], v[112:115], v[220:223], v[100:103]
	v_mfma_f32_16x16x32_bf16 v[96:99], v[158:161], v[220:223], v[96:99]
	s_setprio 0
	s_setprio 1
	v_mfma_f32_16x16x32_bf16 v[60:63], v[162:165], v[192:195], v[60:63]
	v_mfma_f32_16x16x32_bf16 v[56:59], v[184:187], v[192:195], v[56:59]
	v_mfma_f32_16x16x32_bf16 v[52:55], v[162:165], v[200:203], v[52:55]
	v_mfma_f32_16x16x32_bf16 v[48:51], v[184:187], v[200:203], v[48:51]
	v_mfma_f32_16x16x32_bf16 v[44:47], v[162:165], v[208:211], v[44:47]
	v_mfma_f32_16x16x32_bf16 v[40:43], v[184:187], v[208:211], v[40:43]
	v_mfma_f32_16x16x32_bf16 v[36:39], v[162:165], v[216:219], v[36:39]
	v_mfma_f32_16x16x32_bf16 v[32:35], v[184:187], v[216:219], v[32:35]
	v_mfma_f32_16x16x32_bf16 v[60:63], v[180:183], v[196:199], v[60:63]
	v_mfma_f32_16x16x32_bf16 v[56:59], v[188:191], v[196:199], v[56:59]
	v_mfma_f32_16x16x32_bf16 v[52:55], v[180:183], v[204:207], v[52:55]
	v_mfma_f32_16x16x32_bf16 v[48:51], v[188:191], v[204:207], v[48:51]
	v_mfma_f32_16x16x32_bf16 v[44:47], v[180:183], v[212:215], v[44:47]
	v_mfma_f32_16x16x32_bf16 v[40:43], v[188:191], v[212:215], v[40:43]
	s_setprio 2
	s_barrier
; #define PG8_STAGE(bufoff, gbase, voff) do { _Pragma("unroll") for (int _i = 0; _i < 2; ++_i) \
;         __builtin_amdgcn_global_load_lds((const unsigned*)((const char*)(gbase) + (voff)[_i]), (LAS unsigned*)(lds + (bufoff) + ldsw + _i * 8192), 16, 0, 0); } while (0)
; #define PG8_LDA(dst, b, h) do { _Pragma("unroll") for (int m = 0; m < 4; ++m) _Pragma("unroll") for (int k = 0; k < 2; ++k) dst[m][k] = *(const LAS bf16x8*)(lds + PG8_SA(b, h) + aoff + m * 2048 + k * 1024); } while (0)
; #define PG8_MMA(ai, bj, At, Bt) do { __builtin_amdgcn_s_setprio(1); _Pragma("unroll") for (int m = 0; m < 4; ++m) _Pragma("unroll") for (int n = 0; n < 2; ++n) _Pragma("unroll") for (int k = 0; k < 2; ++k) \
;         acc[ai][bj][m][n] = __builtin_amdgcn_mfma_f32_16x16x32_bf16(Bt[n][k], At[m][k], acc[ai][bj][m][n], 0, 0, 0); __builtin_amdgcn_s_setprio(0); } while (0)
; #define PG8_WAIT_V(n) asm volatile("s_waitcnt vmcnt(" #n ")" ::: "memory")
; #define PG8_WAIT_L(n) asm volatile("s_waitcnt lgkmcnt(" #n ")" ::: "memory")
; #define PG8_BAR __builtin_amdgcn_s_barrier()
; #define PG8_SCHED __builtin_amdgcn_sched_barrier(0)
; template <class Epi, class Sched, bool ALIGN_EPI = true, bool SP2 = true>
; __device__ __forceinline__ void gemm_phase(LAS unsigned char* lds, const bf16_t* Ag, const bf16_t* Btg, const int K, const int lda, const int ldb, const Sched& S, const Epi& E) {
;     ...
;         for (int t = 0; t < nt; t += 2) {
;     ...
;             PG8_WAIT_V(8); PG8_WAIT_L(0); PG8_BAR; PG8_MMA(0, 0, At, B0); PG8_MMA(0, 1, At, B1); PG8_BAR; PG8_SCHED;
;             PG8_LDA(At, 1, 1); PG8_STAGE(PG8_SB(1, 0), b3, voffB); PG8_STAGE(PG8_SB(1, 1), b3 + hstepB, voffB); PG8_STAGE(PG8_SA(1, 0), a3, voffA);
;             PG8_WAIT_V(8); PG8_WAIT_L(0); PG8_BAR; PG8_MMA(1, 0, At, B0); PG8_MMA(1, 1, At, B1); PG8_BAR; PG8_SCHED;
	v_mfma_f32_16x16x32_bf16 v[36:39], v[180:183], v[220:223], v[36:39]
	v_mfma_f32_16x16x32_bf16 v[32:35], v[188:191], v[220:223], v[32:35]
	s_setprio 0
	s_add_i32 s28, s54, s35
	v_lshl_add_u64 v[174:175], v[174:175], 0, s[6:7]
	s_mov_b32 m0, s28
	ds_read_b128 v[192:195], v172 offset:49152
	ds_read_b128 v[196:199], v172 offset:50176
	ds_read_b128 v[200:203], v172 offset:51200
	ds_read_b128 v[204:207], v172 offset:52224
	ds_read_b128 v[208:211], v172 offset:53248
	ds_read_b128 v[212:215], v172 offset:54272
	ds_read_b128 v[216:219], v172 offset:55296
	ds_read_b128 v[220:223], v172 offset:56320
	global_load_lds_dwordx4 v[174:175], off
	s_add_i32 m0, s28, 0x2000
	s_add_u32 s26, s26, 0x80080
	v_lshl_add_u64 v[174:175], v[224:225], 0, s[6:7]
	s_addc_u32 s27, s27, 0
	s_add_i32 s28, s55, s35
	global_load_lds_dwordx4 v[174:175], off
	v_lshl_add_u64 v[174:175], s[26:27], 0, v[138:139]
	s_mov_b32 m0, s28
	s_nop 0
	global_load_lds_dwordx4 v[174:175], off
	v_lshl_add_u64 v[174:175], s[26:27], 0, v[142:143]
	s_add_i32 m0, s28, 0x2000
	s_nop 0
	global_load_lds_dwordx4 v[174:175], off
	v_lshl_add_u64 v[174:175], v[226:227], 0, s[6:7]
	s_mov_b32 m0, s42
	s_nop 0
	global_load_lds_dwordx4 v[174:175], off
	v_lshl_add_u64 v[174:175], v[228:229], 0, s[6:7]
	s_mov_b32 m0, s43
	s_nop 0
	global_load_lds_dwordx4 v[174:175], off
	s_waitcnt vmcnt(8)
	s_waitcnt lgkmcnt(0)
	s_barrier
	s_setprio 1
	s_waitcnt lgkmcnt(0)
	v_mfma_f32_16x16x32_bf16 v[92:95], v[108:111], v[192:195], v[92:95]
	s_add_i32 s53, s53, 2
	s_add_u32 s24, s24, 0x100
	s_addc_u32 s25, s25, 0
	s_add_u32 s51, s51, 0x100
	s_addc_u32 s52, s52, 0
	s_cmp_gt_u32 s53, 29
	v_mfma_f32_16x16x32_bf16 v[88:91], v[154:157], v[192:195], v[88:91]
	v_mfma_f32_16x16x32_bf16 v[84:87], v[108:111], v[200:203], v[84:87]
	v_mfma_f32_16x16x32_bf16 v[80:83], v[154:157], v[200:203], v[80:83]
	v_mfma_f32_16x16x32_bf16 v[76:79], v[108:111], v[208:211], v[76:79]
	v_mfma_f32_16x16x32_bf16 v[72:75], v[154:157], v[208:211], v[72:75]
	v_mfma_f32_16x16x32_bf16 v[68:71], v[108:111], v[216:219], v[68:71]
	v_mfma_f32_16x16x32_bf16 v[64:67], v[154:157], v[216:219], v[64:67]
	v_mfma_f32_16x16x32_bf16 v[92:95], v[112:115], v[196:199], v[92:95]
	v_mfma_f32_16x16x32_bf16 v[88:91], v[158:161], v[196:199], v[88:91]
	v_mfma_f32_16x16x32_bf16 v[84:87], v[112:115], v[204:207], v[84:87]
	v_mfma_f32_16x16x32_bf16 v[80:83], v[158:161], v[204:207], v[80:83]
	v_mfma_f32_16x16x32_bf16 v[76:79], v[112:115], v[212:215], v[76:79]
	v_mfma_f32_16x16x32_bf16 v[72:75], v[158:161], v[212:215], v[72:75]
	v_mfma_f32_16x16x32_bf16 v[68:71], v[112:115], v[220:223], v[68:71]
	v_mfma_f32_16x16x32_bf16 v[64:67], v[158:161], v[220:223], v[64:67]
	s_setprio 0
	s_setprio 1
	v_mfma_f32_16x16x32_bf16 v[28:31], v[162:165], v[192:195], v[28:31]
	v_mfma_f32_16x16x32_bf16 v[24:27], v[184:187], v[192:195], v[24:27]
	v_mfma_f32_16x16x32_bf16 v[20:23], v[162:165], v[200:203], v[20:23]
	v_mfma_f32_16x16x32_bf16 v[16:19], v[184:187], v[200:203], v[16:19]
	v_mfma_f32_16x16x32_bf16 v[12:15], v[162:165], v[208:211], v[12:15]
	v_mfma_f32_16x16x32_bf16 v[8:11], v[184:187], v[208:211], v[8:11]
	v_mfma_f32_16x16x32_bf16 v[4:7], v[162:165], v[216:219], v[4:7]
	v_mfma_f32_16x16x32_bf16 v[0:3], v[184:187], v[216:219], v[0:3]
	v_mfma_f32_16x16x32_bf16 v[28:31], v[180:183], v[196:199], v[28:31]
	v_mfma_f32_16x16x32_bf16 v[24:27], v[188:191], v[196:199], v[24:27]
	v_mfma_f32_16x16x32_bf16 v[20:23], v[180:183], v[204:207], v[20:23]
	v_mfma_f32_16x16x32_bf16 v[16:19], v[188:191], v[204:207], v[16:19]
	v_mfma_f32_16x16x32_bf16 v[12:15], v[180:183], v[212:215], v[12:15]
	v_mfma_f32_16x16x32_bf16 v[8:11], v[188:191], v[212:215], v[8:11]
	s_setprio 2
	s_barrier
	v_mfma_f32_16x16x32_bf16 v[4:7], v[180:183], v[220:223], v[4:7]
	v_mfma_f32_16x16x32_bf16 v[0:3], v[188:191], v[220:223], v[0:3]
	s_setprio 0
	s_cbranch_scc0 .LBB0_787
	s_and_b64 vcc, exec, s[8:9]
	s_cbranch_vccz .LBB0_790
	s_barrier

; #define PG8_STAGE(bufoff, gbase, voff) do { _Pragma("unroll") for (int _i = 0; _i < 2; ++_i) \
;         __builtin_amdgcn_global_load_lds((const unsigned*)((const char*)(gbase) + (voff)[_i]), (LAS unsigned*)(lds + (bufoff) + ldsw + _i * 8192), 16, 0, 0); } while (0)
; #define PG8_LDA(dst, b, h) do { _Pragma("unroll") for (int m = 0; m < 4; ++m) _Pragma("unroll") for (int k = 0; k < 2; ++k) dst[m][k] = *(const LAS bf16x8*)(lds + PG8_SA(b, h) + aoff + m * 2048 + k * 1024); } while (0)
; #define PG8_LDB(dst, b, h) do { _Pragma("unroll") for (int n = 0; n < 2; ++n) _Pragma("unroll") for (int k = 0; k < 2; ++k) dst[n][k] = *(const LAS bf16x8*)(lds + PG8_SB(b, h) + boff + n * 2048 + k * 1024); } while (0)
; #define PG8_MMA(ai, bj, At, Bt) do { __builtin_amdgcn_s_setprio(1); _Pragma("unroll") for (int m = 0; m < 4; ++m) _Pragma("unroll") for (int n = 0; n < 2; ++n) _Pragma("unroll") for (int k = 0; k < 2; ++k) \
;         acc[ai][bj][m][n] = __builtin_amdgcn_mfma_f32_16x16x32_bf16(Bt[n][k], At[m][k], acc[ai][bj][m][n], 0, 0, 0); __builtin_amdgcn_s_setprio(0); } while (0)
; #define PG8_WAIT_V(n) asm volatile("s_waitcnt vmcnt(" #n ")" ::: "memory")
; #define PG8_BAR __builtin_amdgcn_s_barrier()
; template <class Epi, class Sched, bool ALIGN_EPI = true, bool SP2 = true>
; __device__ __forceinline__ void gemm_phase(LAS unsigned char* lds, const bf16_t* Ag, const bf16_t* Btg, const int K, const int lda, const int ldb, const Sched& S, const Epi& E) {
;     ...
;         for (int t = 0; t < nt; t += 2) {
;             const bool last = (t == nt - 2);
;             const char* a1 = cA + (size_t)(t + 1) * kstep;
;             const char* a2 = last ? nA : cA + (size_t)(t + 2) * kstep; const char* b2 = last ? nB : cB + (size_t)(t + 2) * kstep;
;             const char* a3 = a2 + kstep; const char* b3 = b2 + kstep;
;             if constexpr (SP2) {
;             PG8_LDB(B0, 0, 0); PG8_LDB(B1, 0, 1); PG8_SCHED; PG8_LDA(At, 0, 0); PG8_STAGE(PG8_SA(1, 1), a1 + hstepA, voffA);
;             PG8_WAIT_V(8); PG8_WAIT_L(0); PG8_BAR; PG8_MMA(0, 0, At, B0); PG8_MMA(0, 1, At, B1); PG8_BAR; PG8_SCHED;
;             PG8_LDA(At, 0, 1); PG8_STAGE(PG8_SB(0, 0), b2, voffB); PG8_STAGE(PG8_SB(0, 1), b2 + hstepB, voffB); PG8_STAGE(PG8_SA(0, 0), a2, voffA);
;             PG8_WAIT_V(8); PG8_WAIT_L(0); PG8_BAR; PG8_MMA(1, 0, At, B0); PG8_MMA(1, 1, At, B1); PG8_BAR; PG8_SCHED;
.LBB0_866:
	ds_read_b128 v[146:149], v159
	ds_read_b128 v[162:165], v159 offset:1024
	ds_read_b128 v[168:171], v159 offset:2048
	ds_read_b128 v[172:175], v159 offset:3072
	ds_read_b128 v[180:183], v160
	ds_read_b128 v[184:187], v160 offset:1024
	ds_read_b128 v[188:191], v160 offset:2048
	ds_read_b128 v[192:195], v160 offset:3072
	s_add_u32 s28, s26, 0xfff80080
	s_addc_u32 s29, s27, -1
	s_cmp_eq_u32 s53, 12
	s_cselect_b32 s31, s13, s29
	s_cselect_b32 s30, s15, s28
	s_cselect_b32 s29, s47, s52
	s_cselect_b32 s28, s50, s51
	v_lshl_add_u64 v[228:229], s[26:27], 0, v[138:139]
	s_add_i32 m0, s35, 0xc000
	ds_read_b128 v[196:199], v161
	ds_read_b128 v[200:203], v161 offset:1024
	ds_read_b128 v[204:207], v161 offset:2048
	ds_read_b128 v[208:211], v161 offset:3072
	ds_read_b128 v[212:215], v161 offset:4096
	ds_read_b128 v[216:219], v161 offset:5120
	ds_read_b128 v[220:223], v161 offset:6144
	ds_read_b128 v[224:227], v161 offset:7168
	global_load_lds_dwordx4 v[228:229], off
	v_lshl_add_u64 v[228:229], s[26:27], 0, v[140:141]
	s_add_i32 m0, s35, 0xe000
	s_nop 0
	global_load_lds_dwordx4 v[228:229], off
	s_waitcnt vmcnt(8)
	s_waitcnt lgkmcnt(0)
	s_barrier
	s_setprio 1
	s_waitcnt lgkmcnt(0)
	v_mfma_f32_16x16x32_bf16 v[124:127], v[146:149], v[196:199], v[124:127]
	v_mfma_f32_16x16x32_bf16 v[120:123], v[168:171], v[196:199], v[120:123]
	v_mfma_f32_16x16x32_bf16 v[108:111], v[146:149], v[204:207], v[108:111]
	v_mfma_f32_16x16x32_bf16 v[104:107], v[168:171], v[204:207], v[104:107]
	v_mfma_f32_16x16x32_bf16 v[92:95], v[146:149], v[212:215], v[92:95]
	v_mfma_f32_16x16x32_bf16 v[88:91], v[168:171], v[212:215], v[88:91]
	v_mfma_f32_16x16x32_bf16 v[76:79], v[146:149], v[220:223], v[76:79]
	v_mfma_f32_16x16x32_bf16 v[72:75], v[168:171], v[220:223], v[72:75]
	v_mfma_f32_16x16x32_bf16 v[124:127], v[162:165], v[200:203], v[124:127]
	v_mfma_f32_16x16x32_bf16 v[120:123], v[172:175], v[200:203], v[120:123]
	v_mfma_f32_16x16x32_bf16 v[108:111], v[162:165], v[208:211], v[108:111]
	v_mfma_f32_16x16x32_bf16 v[104:107], v[172:175], v[208:211], v[104:107]
	v_mfma_f32_16x16x32_bf16 v[92:95], v[162:165], v[216:219], v[92:95]
	v_mfma_f32_16x16x32_bf16 v[88:91], v[172:175], v[216:219], v[88:91]
	v_mfma_f32_16x16x32_bf16 v[76:79], v[162:165], v[224:227], v[76:79]
	v_mfma_f32_16x16x32_bf16 v[72:75], v[172:175], v[224:227], v[72:75]
	s_setprio 0
	s_setprio 1
	v_mfma_f32_16x16x32_bf16 v[116:119], v[180:183], v[196:199], v[116:119]
	v_mfma_f32_16x16x32_bf16 v[112:115], v[188:191], v[196:199], v[112:115]
	v_mfma_f32_16x16x32_bf16 v[100:103], v[180:183], v[204:207], v[100:103]
	v_mfma_f32_16x16x32_bf16 v[96:99], v[188:191], v[204:207], v[96:99]
	v_mfma_f32_16x16x32_bf16 v[84:87], v[180:183], v[212:215], v[84:87]
	v_mfma_f32_16x16x32_bf16 v[80:83], v[188:191], v[212:215], v[80:83]
	v_mfma_f32_16x16x32_bf16 v[68:71], v[180:183], v[220:223], v[68:71]
	v_mfma_f32_16x16x32_bf16 v[64:67], v[188:191], v[220:223], v[64:67]
	v_mfma_f32_16x16x32_bf16 v[116:119], v[184:187], v[200:203], v[116:119]
	v_mfma_f32_16x16x32_bf16 v[112:115], v[192:195], v[200:203], v[112:115]
	v_mfma_f32_16x16x32_bf16 v[100:103], v[184:187], v[208:211], v[100:103]
	v_mfma_f32_16x16x32_bf16 v[96:99], v[192:195], v[208:211], v[96:99]
	v_mfma_f32_16x16x32_bf16 v[84:87], v[184:187], v[216:219], v[84:87]
	v_mfma_f32_16x16x32_bf16 v[80:83], v[192:195], v[216:219], v[80:83]
	s_setprio 2
	s_barrier
	v_mfma_f32_16x16x32_bf16 v[68:71], v[184:187], v[224:227], v[68:71]
	v_mfma_f32_16x16x32_bf16 v[64:67], v[192:195], v[224:227], v[64:67]
	s_setprio 0
	s_add_i32 s54, s45, s34
	v_lshl_add_u64 v[228:229], s[28:29], 0, v[130:131]
	s_mov_b32 m0, s54
	ds_read_b128 v[196:199], v161 offset:16384
	ds_read_b128 v[200:203], v161 offset:17408
	ds_read_b128 v[204:207], v161 offset:18432
	ds_read_b128 v[208:211], v161 offset:19456
	ds_read_b128 v[212:215], v161 offset:20480
	ds_read_b128 v[216:219], v161 offset:21504
	ds_read_b128 v[220:223], v161 offset:22528
	ds_read_b128 v[224:227], v161 offset:23552
	global_load_lds_dwordx4 v[228:229], off
	s_add_i32 m0, s54, 0x2000
	s_add_u32 s54, s28, 0x80000
	v_lshl_add_u64 v[230:231], s[28:29], 0, v[134:135]
	s_addc_u32 s55, s29, 0
	s_add_i32 s58, s46, s34
	global_load_lds_dwordx4 v[230:231], off
	v_lshl_add_u64 v[232:233], s[54:55], 0, v[130:131]
	s_mov_b32 m0, s58
	v_lshl_add_u64 v[234:235], s[30:31], 0, v[132:133]
	global_load_lds_dwordx4 v[232:233], off
	v_lshl_add_u64 v[232:233], s[54:55], 0, v[134:135]
	s_add_i32 m0, s58, 0x2000
	s_nop 0
	global_load_lds_dwordx4 v[232:233], off
	v_lshl_add_u64 v[232:233], s[30:31], 0, v[128:129]
	s_mov_b32 m0, s35
	s_nop 0
	global_load_lds_dwordx4 v[232:233], off
	s_mov_b32 m0, s37
	s_nop 0
	global_load_lds_dwordx4 v[234:235], off
	s_waitcnt vmcnt(8)
	s_waitcnt lgkmcnt(0)
	s_barrier
; #define PG8_STAGE(bufoff, gbase, voff) do { _Pragma("unroll") for (int _i = 0; _i < 2; ++_i) \
;         __builtin_amdgcn_global_load_lds((const unsigned*)((const char*)(gbase) + (voff)[_i]), (LAS unsigned*)(lds + (bufoff) + ldsw + _i * 8192), 16, 0, 0); } while (0)
; #define PG8_LDA(dst, b, h) do { _Pragma("unroll") for (int m = 0; m < 4; ++m) _Pragma("unroll") for (int k = 0; k < 2; ++k) dst[m][k] = *(const LAS bf16x8*)(lds + PG8_SA(b, h) + aoff + m * 2048 + k * 1024); } while (0)
; #define PG8_LDB(dst, b, h) do { _Pragma("unroll") for (int n = 0; n < 2; ++n) _Pragma("unroll") for (int k = 0; k < 2; ++k) dst[n][k] = *(const LAS bf16x8*)(lds + PG8_SB(b, h) + boff + n * 2048 + k * 1024); } while (0)
; #define PG8_MMA(ai, bj, At, Bt) do { __builtin_amdgcn_s_setprio(1); _Pragma("unroll") for (int m = 0; m < 4; ++m) _Pragma("unroll") for (int n = 0; n < 2; ++n) _Pragma("unroll") for (int k = 0; k < 2; ++k) \
;         acc[ai][bj][m][n] = __builtin_amdgcn_mfma_f32_16x16x32_bf16(Bt[n][k], At[m][k], acc[ai][bj][m][n], 0, 0, 0); __builtin_amdgcn_s_setprio(0); } while (0)
; #define PG8_WAIT_V(n) asm volatile("s_waitcnt vmcnt(" #n ")" ::: "memory")
; #define PG8_WAIT_L(n) asm volatile("s_waitcnt lgkmcnt(" #n ")" ::: "memory")
; #define PG8_BAR __builtin_amdgcn_s_barrier()
; #define PG8_SCHED __builtin_amdgcn_sched_barrier(0)
; template <class Epi, class Sched, bool ALIGN_EPI = true, bool SP2 = true>
; __device__ __forceinline__ void gemm_phase(LAS unsigned char* lds, const bf16_t* Ag, const bf16_t* Btg, const int K, const int lda, const int ldb, const Sched& S, const Epi& E) {
;     ...
;             PG8_WAIT_V(8); PG8_WAIT_L(0); PG8_BAR; PG8_MMA(1, 0, At, B0); PG8_MMA(1, 1, At, B1); PG8_BAR; PG8_SCHED;
;             PG8_LDB(B0, 1, 0); PG8_LDB(B1, 1, 1); PG8_SCHED; PG8_LDA(At, 1, 0); PG8_STAGE(PG8_SA(0, 1), a2 + hstepA, voffA);
;             PG8_WAIT_V(8); PG8_WAIT_L(0); PG8_BAR; PG8_MMA(0, 0, At, B0); PG8_MMA(0, 1, At, B1); PG8_BAR; PG8_SCHED;
	s_setprio 1
	s_waitcnt lgkmcnt(0)
	v_mfma_f32_16x16x32_bf16 v[60:63], v[146:149], v[196:199], v[60:63]
	v_mfma_f32_16x16x32_bf16 v[56:59], v[168:171], v[196:199], v[56:59]
	v_mfma_f32_16x16x32_bf16 v[44:47], v[146:149], v[204:207], v[44:47]
	v_mfma_f32_16x16x32_bf16 v[40:43], v[168:171], v[204:207], v[40:43]
	v_mfma_f32_16x16x32_bf16 v[28:31], v[146:149], v[212:215], v[28:31]
	v_mfma_f32_16x16x32_bf16 v[24:27], v[168:171], v[212:215], v[24:27]
	v_mfma_f32_16x16x32_bf16 v[12:15], v[146:149], v[220:223], v[12:15]
	v_mfma_f32_16x16x32_bf16 v[8:11], v[168:171], v[220:223], v[8:11]
	v_mfma_f32_16x16x32_bf16 v[60:63], v[162:165], v[200:203], v[60:63]
	v_mfma_f32_16x16x32_bf16 v[56:59], v[172:175], v[200:203], v[56:59]
	v_mfma_f32_16x16x32_bf16 v[44:47], v[162:165], v[208:211], v[44:47]
	v_mfma_f32_16x16x32_bf16 v[40:43], v[172:175], v[208:211], v[40:43]
	v_mfma_f32_16x16x32_bf16 v[28:31], v[162:165], v[216:219], v[28:31]
	v_mfma_f32_16x16x32_bf16 v[24:27], v[172:175], v[216:219], v[24:27]
	v_mfma_f32_16x16x32_bf16 v[12:15], v[162:165], v[224:227], v[12:15]
	v_mfma_f32_16x16x32_bf16 v[8:11], v[172:175], v[224:227], v[8:11]
	s_setprio 0
	s_setprio 1
	v_mfma_f32_16x16x32_bf16 v[52:55], v[180:183], v[196:199], v[52:55]
	v_mfma_f32_16x16x32_bf16 v[48:51], v[188:191], v[196:199], v[48:51]
	v_mfma_f32_16x16x32_bf16 v[36:39], v[180:183], v[204:207], v[36:39]
	v_mfma_f32_16x16x32_bf16 v[32:35], v[188:191], v[204:207], v[32:35]
	v_mfma_f32_16x16x32_bf16 v[20:23], v[180:183], v[212:215], v[20:23]
	v_mfma_f32_16x16x32_bf16 v[16:19], v[188:191], v[212:215], v[16:19]
	v_mfma_f32_16x16x32_bf16 v[4:7], v[180:183], v[220:223], v[4:7]
	v_mfma_f32_16x16x32_bf16 v[0:3], v[188:191], v[220:223], v[0:3]
	v_mfma_f32_16x16x32_bf16 v[52:55], v[184:187], v[200:203], v[52:55]
	v_mfma_f32_16x16x32_bf16 v[48:51], v[192:195], v[200:203], v[48:51]
	v_mfma_f32_16x16x32_bf16 v[36:39], v[184:187], v[208:211], v[36:39]
	v_mfma_f32_16x16x32_bf16 v[32:35], v[192:195], v[208:211], v[32:35]
	v_mfma_f32_16x16x32_bf16 v[20:23], v[184:187], v[216:219], v[20:23]
	v_mfma_f32_16x16x32_bf16 v[16:19], v[192:195], v[216:219], v[16:19]
	s_setprio 2
	s_barrier
	v_mfma_f32_16x16x32_bf16 v[4:7], v[184:187], v[224:227], v[4:7]
	v_mfma_f32_16x16x32_bf16 v[0:3], v[192:195], v[224:227], v[0:3]
	s_setprio 0
	s_add_i32 s54, 0, 0x18000
	s_add_i32 s55, 0, 0x1c000
	v_add_u32_e32 v172, s54, v157
	v_add_u32_e32 v192, s55, v157
	ds_read_b128 v[146:149], v172
	ds_read_b128 v[162:165], v172 offset:1024
	ds_read_b128 v[168:171], v172 offset:2048
	ds_read_b128 v[172:175], v172 offset:3072
	ds_read_b128 v[180:183], v192
	ds_read_b128 v[184:187], v192 offset:1024
	ds_read_b128 v[188:191], v192 offset:2048
	ds_read_b128 v[192:195], v192 offset:3072
	s_add_u32 s30, s30, 0x80000
	s_addc_u32 s31, s31, 0
	s_mov_b32 m0, s38
	v_lshl_add_u64 v[236:237], s[30:31], 0, v[128:129]
	ds_read_b128 v[196:199], v161 offset:32768
	ds_read_b128 v[200:203], v161 offset:33792
	ds_read_b128 v[204:207], v161 offset:34816
	ds_read_b128 v[208:211], v161 offset:35840
	ds_read_b128 v[212:215], v161 offset:36864
	ds_read_b128 v[216:219], v161 offset:37888
	ds_read_b128 v[220:223], v161 offset:38912
	ds_read_b128 v[224:227], v161 offset:39936
	global_load_lds_dwordx4 v[236:237], off
	v_lshl_add_u64 v[236:237], s[30:31], 0, v[132:133]
	s_mov_b32 m0, s39
	s_nop 0
	global_load_lds_dwordx4 v[236:237], off
	s_waitcnt vmcnt(8)
	s_waitcnt lgkmcnt(0)
	s_barrier
	s_setprio 1
	s_waitcnt lgkmcnt(0)
	v_mfma_f32_16x16x32_bf16 v[124:127], v[146:149], v[196:199], v[124:127]
	v_mfma_f32_16x16x32_bf16 v[120:123], v[168:171], v[196:199], v[120:123]
	v_mfma_f32_16x16x32_bf16 v[108:111], v[146:149], v[204:207], v[108:111]
	v_mfma_f32_16x16x32_bf16 v[104:107], v[168:171], v[204:207], v[104:107]
	v_mfma_f32_16x16x32_bf16 v[92:95], v[146:149], v[212:215], v[92:95]
	v_mfma_f32_16x16x32_bf16 v[88:91], v[168:171], v[212:215], v[88:91]
	v_mfma_f32_16x16x32_bf16 v[76:79], v[146:149], v[220:223], v[76:79]
	v_mfma_f32_16x16x32_bf16 v[72:75], v[168:171], v[220:223], v[72:75]
	v_mfma_f32_16x16x32_bf16 v[124:127], v[162:165], v[200:203], v[124:127]
	v_mfma_f32_16x16x32_bf16 v[120:123], v[172:175], v[200:203], v[120:123]
	v_mfma_f32_16x16x32_bf16 v[108:111], v[162:165], v[208:211], v[108:111]
	v_mfma_f32_16x16x32_bf16 v[104:107], v[172:175], v[208:211], v[104:107]
	v_mfma_f32_16x16x32_bf16 v[92:95], v[162:165], v[216:219], v[92:95]
	v_mfma_f32_16x16x32_bf16 v[88:91], v[172:175], v[216:219], v[88:91]
	v_mfma_f32_16x16x32_bf16 v[76:79], v[162:165], v[224:227], v[76:79]
	v_mfma_f32_16x16x32_bf16 v[72:75], v[172:175], v[224:227], v[72:75]
	s_setprio 0
	s_setprio 1
	v_mfma_f32_16x16x32_bf16 v[116:119], v[180:183], v[196:199], v[116:119]
	v_mfma_f32_16x16x32_bf16 v[112:115], v[188:191], v[196:199], v[112:115]
	v_mfma_f32_16x16x32_bf16 v[100:103], v[180:183], v[204:207], v[100:103]
	v_mfma_f32_16x16x32_bf16 v[96:99], v[188:191], v[204:207], v[96:99]
	v_mfma_f32_16x16x32_bf16 v[84:87], v[180:183], v[212:215], v[84:87]
	v_mfma_f32_16x16x32_bf16 v[80:83], v[188:191], v[212:215], v[80:83]
	v_mfma_f32_16x16x32_bf16 v[68:71], v[180:183], v[220:223], v[68:71]
	v_mfma_f32_16x16x32_bf16 v[64:67], v[188:191], v[220:223], v[64:67]
	v_mfma_f32_16x16x32_bf16 v[116:119], v[184:187], v[200:203], v[116:119]
	v_mfma_f32_16x16x32_bf16 v[112:115], v[192:195], v[200:203], v[112:115]
	v_mfma_f32_16x16x32_bf16 v[100:103], v[184:187], v[208:211], v[100:103]
	v_mfma_f32_16x16x32_bf16 v[96:99], v[192:195], v[208:211], v[96:99]
	v_mfma_f32_16x16x32_bf16 v[84:87], v[184:187], v[216:219], v[84:87]
	v_mfma_f32_16x16x32_bf16 v[80:83], v[192:195], v[216:219], v[80:83]
	s_setprio 2
	s_barrier
; #define PG8_STAGE(bufoff, gbase, voff) do { _Pragma("unroll") for (int _i = 0; _i < 2; ++_i) \
;         __builtin_amdgcn_global_load_lds((const unsigned*)((const char*)(gbase) + (voff)[_i]), (LAS unsigned*)(lds + (bufoff) + ldsw + _i * 8192), 16, 0, 0); } while (0)
; #define PG8_LDA(dst, b, h) do { _Pragma("unroll") for (int m = 0; m < 4; ++m) _Pragma("unroll") for (int k = 0; k < 2; ++k) dst[m][k] = *(const LAS bf16x8*)(lds + PG8_SA(b, h) + aoff + m * 2048 + k * 1024); } while (0)
; #define PG8_MMA(ai, bj, At, Bt) do { __builtin_amdgcn_s_setprio(1); _Pragma("unroll") for (int m = 0; m < 4; ++m) _Pragma("unroll") for (int n = 0; n < 2; ++n) _Pragma("unroll") for (int k = 0; k < 2; ++k) \
;         acc[ai][bj][m][n] = __builtin_amdgcn_mfma_f32_16x16x32_bf16(Bt[n][k], At[m][k], acc[ai][bj][m][n], 0, 0, 0); __builtin_amdgcn_s_setprio(0); } while (0)
; #define PG8_WAIT_V(n) asm volatile("s_waitcnt vmcnt(" #n ")" ::: "memory")
; #define PG8_WAIT_L(n) asm volatile("s_waitcnt lgkmcnt(" #n ")" ::: "memory")
; #define PG8_BAR __builtin_amdgcn_s_barrier()
; #define PG8_SCHED __builtin_amdgcn_sched_barrier(0)
; template <class Epi, class Sched, bool ALIGN_EPI = true, bool SP2 = true>
; __device__ __forceinline__ void gemm_phase(LAS unsigned char* lds, const bf16_t* Ag, const bf16_t* Btg, const int K, const int lda, const int ldb, const Sched& S, const Epi& E) {
;     ...
;         for (int t = 0; t < nt; t += 2) {
;     ...
;             PG8_WAIT_V(8); PG8_WAIT_L(0); PG8_BAR; PG8_MMA(0, 0, At, B0); PG8_MMA(0, 1, At, B1); PG8_BAR; PG8_SCHED;
;             PG8_LDA(At, 1, 1); PG8_STAGE(PG8_SB(1, 0), b3, voffB); PG8_STAGE(PG8_SB(1, 1), b3 + hstepB, voffB); PG8_STAGE(PG8_SA(1, 0), a3, voffA);
;             PG8_WAIT_V(8); PG8_WAIT_L(0); PG8_BAR; PG8_MMA(1, 0, At, B0); PG8_MMA(1, 1, At, B1); PG8_BAR; PG8_SCHED;
	v_mfma_f32_16x16x32_bf16 v[68:71], v[184:187], v[224:227], v[68:71]
	v_mfma_f32_16x16x32_bf16 v[64:67], v[192:195], v[224:227], v[64:67]
	s_setprio 0
	s_add_i32 s30, s54, s34
	v_lshl_add_u64 v[228:229], v[228:229], 0, s[8:9]
	s_mov_b32 m0, s30
	ds_read_b128 v[196:199], v161 offset:49152
	ds_read_b128 v[200:203], v161 offset:50176
	ds_read_b128 v[204:207], v161 offset:51200
	ds_read_b128 v[208:211], v161 offset:52224
	ds_read_b128 v[212:215], v161 offset:53248
	ds_read_b128 v[216:219], v161 offset:54272
	ds_read_b128 v[220:223], v161 offset:55296
	ds_read_b128 v[224:227], v161 offset:56320
	global_load_lds_dwordx4 v[228:229], off
	s_add_i32 m0, s30, 0x2000
	s_add_u32 s28, s28, 0x80080
	v_lshl_add_u64 v[228:229], v[230:231], 0, s[8:9]
	s_addc_u32 s29, s29, 0
	s_add_i32 s30, s55, s34
	global_load_lds_dwordx4 v[228:229], off
	v_lshl_add_u64 v[228:229], s[28:29], 0, v[130:131]
	s_mov_b32 m0, s30
	s_nop 0
	global_load_lds_dwordx4 v[228:229], off
	v_lshl_add_u64 v[228:229], s[28:29], 0, v[134:135]
	s_add_i32 m0, s30, 0x2000
	s_nop 0
	global_load_lds_dwordx4 v[228:229], off
	v_lshl_add_u64 v[228:229], v[232:233], 0, s[8:9]
	s_mov_b32 m0, s41
	s_nop 0
	global_load_lds_dwordx4 v[228:229], off
	v_lshl_add_u64 v[228:229], v[234:235], 0, s[8:9]
	s_mov_b32 m0, s42
	s_nop 0
	global_load_lds_dwordx4 v[228:229], off
	s_waitcnt vmcnt(8)
	s_waitcnt lgkmcnt(0)
	s_barrier
	s_setprio 1
	s_waitcnt lgkmcnt(0)
	v_mfma_f32_16x16x32_bf16 v[60:63], v[146:149], v[196:199], v[60:63]
	s_add_i32 s53, s53, 2
	s_add_u32 s26, s26, 0x100
	s_addc_u32 s27, s27, 0
	s_add_u32 s51, s51, 0x100
	s_addc_u32 s52, s52, 0
	s_cmp_gt_u32 s53, 13
	v_mfma_f32_16x16x32_bf16 v[56:59], v[168:171], v[196:199], v[56:59]
	v_mfma_f32_16x16x32_bf16 v[44:47], v[146:149], v[204:207], v[44:47]
	v_mfma_f32_16x16x32_bf16 v[40:43], v[168:171], v[204:207], v[40:43]
	v_mfma_f32_16x16x32_bf16 v[28:31], v[146:149], v[212:215], v[28:31]
	v_mfma_f32_16x16x32_bf16 v[24:27], v[168:171], v[212:215], v[24:27]
	v_mfma_f32_16x16x32_bf16 v[12:15], v[146:149], v[220:223], v[12:15]
	v_mfma_f32_16x16x32_bf16 v[8:11], v[168:171], v[220:223], v[8:11]
	v_mfma_f32_16x16x32_bf16 v[60:63], v[162:165], v[200:203], v[60:63]
	v_mfma_f32_16x16x32_bf16 v[56:59], v[172:175], v[200:203], v[56:59]
	v_mfma_f32_16x16x32_bf16 v[44:47], v[162:165], v[208:211], v[44:47]
	v_mfma_f32_16x16x32_bf16 v[40:43], v[172:175], v[208:211], v[40:43]
	v_mfma_f32_16x16x32_bf16 v[28:31], v[162:165], v[216:219], v[28:31]
	v_mfma_f32_16x16x32_bf16 v[24:27], v[172:175], v[216:219], v[24:27]
	v_mfma_f32_16x16x32_bf16 v[12:15], v[162:165], v[224:227], v[12:15]
	v_mfma_f32_16x16x32_bf16 v[8:11], v[172:175], v[224:227], v[8:11]
	s_setprio 0
	s_setprio 1
	v_mfma_f32_16x16x32_bf16 v[52:55], v[180:183], v[196:199], v[52:55]
	v_mfma_f32_16x16x32_bf16 v[48:51], v[188:191], v[196:199], v[48:51]
	v_mfma_f32_16x16x32_bf16 v[36:39], v[180:183], v[204:207], v[36:39]
	v_mfma_f32_16x16x32_bf16 v[32:35], v[188:191], v[204:207], v[32:35]
	v_mfma_f32_16x16x32_bf16 v[20:23], v[180:183], v[212:215], v[20:23]
	v_mfma_f32_16x16x32_bf16 v[16:19], v[188:191], v[212:215], v[16:19]
	v_mfma_f32_16x16x32_bf16 v[4:7], v[180:183], v[220:223], v[4:7]
	v_mfma_f32_16x16x32_bf16 v[0:3], v[188:191], v[220:223], v[0:3]
	v_mfma_f32_16x16x32_bf16 v[52:55], v[184:187], v[200:203], v[52:55]
	v_mfma_f32_16x16x32_bf16 v[48:51], v[192:195], v[200:203], v[48:51]
	v_mfma_f32_16x16x32_bf16 v[36:39], v[184:187], v[208:211], v[36:39]
	v_mfma_f32_16x16x32_bf16 v[32:35], v[192:195], v[208:211], v[32:35]
	v_mfma_f32_16x16x32_bf16 v[20:23], v[184:187], v[216:219], v[20:23]
	v_mfma_f32_16x16x32_bf16 v[16:19], v[192:195], v[216:219], v[16:19]
	s_setprio 2
	s_barrier
	v_mfma_f32_16x16x32_bf16 v[4:7], v[184:187], v[224:227], v[4:7]
	v_mfma_f32_16x16x32_bf16 v[0:3], v[192:195], v[224:227], v[0:3]
	s_setprio 0
	s_cbranch_scc0 .LBB0_866
	s_and_b64 vcc, exec, s[10:11]
	s_cbranch_vccz .LBB0_869
	s_barrier

; #define PG8_STAGE(bufoff, gbase, voff) do { _Pragma("unroll") for (int _i = 0; _i < 2; ++_i) \
;         __builtin_amdgcn_global_load_lds((const unsigned*)((const char*)(gbase) + (voff)[_i]), (LAS unsigned*)(lds + (bufoff) + ldsw + _i * 8192), 16, 0, 0); } while (0)
; #define PG8_LDA(dst, b, h) do { _Pragma("unroll") for (int m = 0; m < 4; ++m) _Pragma("unroll") for (int k = 0; k < 2; ++k) dst[m][k] = *(const LAS bf16x8*)(lds + PG8_SA(b, h) + aoff + m * 2048 + k * 1024); } while (0)
; #define PG8_LDB(dst, b, h) do { _Pragma("unroll") for (int n = 0; n < 2; ++n) _Pragma("unroll") for (int k = 0; k < 2; ++k) dst[n][k] = *(const LAS bf16x8*)(lds + PG8_SB(b, h) + boff + n * 2048 + k * 1024); } while (0)
; #define PG8_MMA(ai, bj, At, Bt) do { __builtin_amdgcn_s_setprio(1); _Pragma("unroll") for (int m = 0; m < 4; ++m) _Pragma("unroll") for (int n = 0; n < 2; ++n) _Pragma("unroll") for (int k = 0; k < 2; ++k) \
;         acc[ai][bj][m][n] = __builtin_amdgcn_mfma_f32_16x16x32_bf16(Bt[n][k], At[m][k], acc[ai][bj][m][n], 0, 0, 0); __builtin_amdgcn_s_setprio(0); } while (0)
; #define PG8_WAIT_V(n) asm volatile("s_waitcnt vmcnt(" #n ")" ::: "memory")
; #define PG8_BAR __builtin_amdgcn_s_barrier()
; template <class Epi, class Sched, bool ALIGN_EPI = true, bool SP2 = true>
; __device__ __forceinline__ void gemm_phase(LAS unsigned char* lds, const bf16_t* Ag, const bf16_t* Btg, const int K, const int lda, const int ldb, const Sched& S, const Epi& E) {
;     ...
;         for (int t = 0; t < nt; t += 2) {
;             const bool last = (t == nt - 2);
;             const char* a1 = cA + (size_t)(t + 1) * kstep;
;             const char* a2 = last ? nA : cA + (size_t)(t + 2) * kstep; const char* b2 = last ? nB : cB + (size_t)(t + 2) * kstep;
;             const char* a3 = a2 + kstep; const char* b3 = b2 + kstep;
;             if constexpr (SP2) {
;             PG8_LDB(B0, 0, 0); PG8_LDB(B1, 0, 1); PG8_SCHED; PG8_LDA(At, 0, 0); PG8_STAGE(PG8_SA(1, 1), a1 + hstepA, voffA);
;             PG8_WAIT_V(8); PG8_WAIT_L(0); PG8_BAR; PG8_MMA(0, 0, At, B0); PG8_MMA(0, 1, At, B1); PG8_BAR; PG8_SCHED;
;             PG8_LDA(At, 0, 1); PG8_STAGE(PG8_SB(0, 0), b2, voffB); PG8_STAGE(PG8_SB(0, 1), b2 + hstepB, voffB); PG8_STAGE(PG8_SA(0, 0), a2, voffA);
;             PG8_WAIT_V(8); PG8_WAIT_L(0); PG8_BAR; PG8_MMA(1, 0, At, B0); PG8_MMA(1, 1, At, B1); PG8_BAR; PG8_SCHED;
.LBB0_890:
	ds_read_b128 v[146:149], v156
	ds_read_b128 v[150:153], v156 offset:1024
	ds_read_b128 v[160:163], v156 offset:2048
	ds_read_b128 v[168:171], v156 offset:3072
	ds_read_b128 v[172:175], v157
	ds_read_b128 v[180:183], v157 offset:1024
	ds_read_b128 v[184:187], v157 offset:2048
	ds_read_b128 v[188:191], v157 offset:3072
	s_add_u32 s28, s26, 0xfff80080
	s_addc_u32 s29, s27, -1
	s_cmp_eq_u32 s59, 12
	s_cselect_b32 s31, s13, s29
	s_cselect_b32 s30, s15, s28
	s_cselect_b32 s29, s33, s58
	s_cselect_b32 s28, s54, s55
	v_lshl_add_u64 v[164:165], s[26:27], 0, v[138:139]
	s_add_i32 m0, s41, 0xc000
	ds_read_b128 v[192:195], v158
	ds_read_b128 v[196:199], v158 offset:1024
	ds_read_b128 v[200:203], v158 offset:2048
	ds_read_b128 v[204:207], v158 offset:3072
	ds_read_b128 v[208:211], v158 offset:4096
	ds_read_b128 v[212:215], v158 offset:5120
	ds_read_b128 v[216:219], v158 offset:6144
	ds_read_b128 v[220:223], v158 offset:7168
	global_load_lds_dwordx4 v[164:165], off
	v_lshl_add_u64 v[164:165], s[26:27], 0, v[140:141]
	s_add_i32 m0, s41, 0xe000
	s_nop 0
	global_load_lds_dwordx4 v[164:165], off
	s_waitcnt vmcnt(8)
	s_waitcnt lgkmcnt(0)
	s_barrier
	s_setprio 1
	s_waitcnt lgkmcnt(0)
	v_mfma_f32_16x16x32_bf16 v[124:127], v[146:149], v[192:195], v[124:127]
	v_mfma_f32_16x16x32_bf16 v[120:123], v[160:163], v[192:195], v[120:123]
	v_mfma_f32_16x16x32_bf16 v[108:111], v[146:149], v[200:203], v[108:111]
	v_mfma_f32_16x16x32_bf16 v[104:107], v[160:163], v[200:203], v[104:107]
	v_mfma_f32_16x16x32_bf16 v[92:95], v[146:149], v[208:211], v[92:95]
	v_mfma_f32_16x16x32_bf16 v[88:91], v[160:163], v[208:211], v[88:91]
	v_mfma_f32_16x16x32_bf16 v[76:79], v[146:149], v[216:219], v[76:79]
	v_mfma_f32_16x16x32_bf16 v[72:75], v[160:163], v[216:219], v[72:75]
	v_mfma_f32_16x16x32_bf16 v[124:127], v[150:153], v[196:199], v[124:127]
	v_mfma_f32_16x16x32_bf16 v[120:123], v[168:171], v[196:199], v[120:123]
	v_mfma_f32_16x16x32_bf16 v[108:111], v[150:153], v[204:207], v[108:111]
	v_mfma_f32_16x16x32_bf16 v[104:107], v[168:171], v[204:207], v[104:107]
	v_mfma_f32_16x16x32_bf16 v[92:95], v[150:153], v[212:215], v[92:95]
	v_mfma_f32_16x16x32_bf16 v[88:91], v[168:171], v[212:215], v[88:91]
	v_mfma_f32_16x16x32_bf16 v[76:79], v[150:153], v[220:223], v[76:79]
	v_mfma_f32_16x16x32_bf16 v[72:75], v[168:171], v[220:223], v[72:75]
	s_setprio 0
	s_setprio 1
	v_mfma_f32_16x16x32_bf16 v[116:119], v[172:175], v[192:195], v[116:119]
	v_mfma_f32_16x16x32_bf16 v[112:115], v[184:187], v[192:195], v[112:115]
	v_mfma_f32_16x16x32_bf16 v[100:103], v[172:175], v[200:203], v[100:103]
	v_mfma_f32_16x16x32_bf16 v[96:99], v[184:187], v[200:203], v[96:99]
	v_mfma_f32_16x16x32_bf16 v[84:87], v[172:175], v[208:211], v[84:87]
	v_mfma_f32_16x16x32_bf16 v[80:83], v[184:187], v[208:211], v[80:83]
	v_mfma_f32_16x16x32_bf16 v[68:71], v[172:175], v[216:219], v[68:71]
	v_mfma_f32_16x16x32_bf16 v[64:67], v[184:187], v[216:219], v[64:67]
	v_mfma_f32_16x16x32_bf16 v[116:119], v[180:183], v[196:199], v[116:119]
	v_mfma_f32_16x16x32_bf16 v[112:115], v[188:191], v[196:199], v[112:115]
	v_mfma_f32_16x16x32_bf16 v[100:103], v[180:183], v[204:207], v[100:103]
	v_mfma_f32_16x16x32_bf16 v[96:99], v[188:191], v[204:207], v[96:99]
	v_mfma_f32_16x16x32_bf16 v[84:87], v[180:183], v[212:215], v[84:87]
	v_mfma_f32_16x16x32_bf16 v[80:83], v[188:191], v[212:215], v[80:83]
	s_setprio 2
	s_barrier
	v_mfma_f32_16x16x32_bf16 v[68:71], v[180:183], v[220:223], v[68:71]
	v_mfma_f32_16x16x32_bf16 v[64:67], v[188:191], v[220:223], v[64:67]
	s_setprio 0
	s_add_i32 s60, s52, s40
	v_lshl_add_u64 v[164:165], s[28:29], 0, v[130:131]
	s_mov_b32 m0, s60
	ds_read_b128 v[192:195], v158 offset:16384
	ds_read_b128 v[196:199], v158 offset:17408
	ds_read_b128 v[200:203], v158 offset:18432
	ds_read_b128 v[204:207], v158 offset:19456
	ds_read_b128 v[208:211], v158 offset:20480
	ds_read_b128 v[212:215], v158 offset:21504
	ds_read_b128 v[216:219], v158 offset:22528
	ds_read_b128 v[220:223], v158 offset:23552
	global_load_lds_dwordx4 v[164:165], off
	s_add_i32 m0, s60, 0x2000
	s_add_u32 s60, s28, 0x80000
	v_lshl_add_u64 v[224:225], s[28:29], 0, v[134:135]
	s_addc_u32 s61, s29, 0
	s_add_i32 s64, s53, s40
	global_load_lds_dwordx4 v[224:225], off
	v_lshl_add_u64 v[226:227], s[60:61], 0, v[130:131]
	s_mov_b32 m0, s64
	v_lshl_add_u64 v[228:229], s[30:31], 0, v[132:133]
	global_load_lds_dwordx4 v[226:227], off
	v_lshl_add_u64 v[226:227], s[60:61], 0, v[134:135]
	s_add_i32 m0, s64, 0x2000
	s_nop 0
	global_load_lds_dwordx4 v[226:227], off
	v_lshl_add_u64 v[226:227], s[30:31], 0, v[128:129]
	s_mov_b32 m0, s41
	s_nop 0
	global_load_lds_dwordx4 v[226:227], off
	s_mov_b32 m0, s42
	s_nop 0
	global_load_lds_dwordx4 v[228:229], off
	s_waitcnt vmcnt(8)
	s_waitcnt lgkmcnt(0)
	s_barrier
; #define PG8_STAGE(bufoff, gbase, voff) do { _Pragma("unroll") for (int _i = 0; _i < 2; ++_i) \
;         __builtin_amdgcn_global_load_lds((const unsigned*)((const char*)(gbase) + (voff)[_i]), (LAS unsigned*)(lds + (bufoff) + ldsw + _i * 8192), 16, 0, 0); } while (0)
; #define PG8_LDA(dst, b, h) do { _Pragma("unroll") for (int m = 0; m < 4; ++m) _Pragma("unroll") for (int k = 0; k < 2; ++k) dst[m][k] = *(const LAS bf16x8*)(lds + PG8_SA(b, h) + aoff + m * 2048 + k * 1024); } while (0)
; #define PG8_LDB(dst, b, h) do { _Pragma("unroll") for (int n = 0; n < 2; ++n) _Pragma("unroll") for (int k = 0; k < 2; ++k) dst[n][k] = *(const LAS bf16x8*)(lds + PG8_SB(b, h) + boff + n * 2048 + k * 1024); } while (0)
; #define PG8_MMA(ai, bj, At, Bt) do { __builtin_amdgcn_s_setprio(1); _Pragma("unroll") for (int m = 0; m < 4; ++m) _Pragma("unroll") for (int n = 0; n < 2; ++n) _Pragma("unroll") for (int k = 0; k < 2; ++k) \
;         acc[ai][bj][m][n] = __builtin_amdgcn_mfma_f32_16x16x32_bf16(Bt[n][k], At[m][k], acc[ai][bj][m][n], 0, 0, 0); __builtin_amdgcn_s_setprio(0); } while (0)
; #define PG8_WAIT_V(n) asm volatile("s_waitcnt vmcnt(" #n ")" ::: "memory")
; #define PG8_WAIT_L(n) asm volatile("s_waitcnt lgkmcnt(" #n ")" ::: "memory")
; #define PG8_BAR __builtin_amdgcn_s_barrier()
; #define PG8_SCHED __builtin_amdgcn_sched_barrier(0)
; template <class Epi, class Sched, bool ALIGN_EPI = true, bool SP2 = true>
; __device__ __forceinline__ void gemm_phase(LAS unsigned char* lds, const bf16_t* Ag, const bf16_t* Btg, const int K, const int lda, const int ldb, const Sched& S, const Epi& E) {
;     ...
;             PG8_WAIT_V(8); PG8_WAIT_L(0); PG8_BAR; PG8_MMA(1, 0, At, B0); PG8_MMA(1, 1, At, B1); PG8_BAR; PG8_SCHED;
;             PG8_LDB(B0, 1, 0); PG8_LDB(B1, 1, 1); PG8_SCHED; PG8_LDA(At, 1, 0); PG8_STAGE(PG8_SA(0, 1), a2 + hstepA, voffA);
;             PG8_WAIT_V(8); PG8_WAIT_L(0); PG8_BAR; PG8_MMA(0, 0, At, B0); PG8_MMA(0, 1, At, B1); PG8_BAR; PG8_SCHED;
	s_setprio 1
	s_waitcnt lgkmcnt(0)
	v_mfma_f32_16x16x32_bf16 v[60:63], v[146:149], v[192:195], v[60:63]
	v_mfma_f32_16x16x32_bf16 v[56:59], v[160:163], v[192:195], v[56:59]
	v_mfma_f32_16x16x32_bf16 v[44:47], v[146:149], v[200:203], v[44:47]
	v_mfma_f32_16x16x32_bf16 v[40:43], v[160:163], v[200:203], v[40:43]
	v_mfma_f32_16x16x32_bf16 v[28:31], v[146:149], v[208:211], v[28:31]
	v_mfma_f32_16x16x32_bf16 v[24:27], v[160:163], v[208:211], v[24:27]
	v_mfma_f32_16x16x32_bf16 v[12:15], v[146:149], v[216:219], v[12:15]
	v_mfma_f32_16x16x32_bf16 v[8:11], v[160:163], v[216:219], v[8:11]
	v_mfma_f32_16x16x32_bf16 v[60:63], v[150:153], v[196:199], v[60:63]
	v_mfma_f32_16x16x32_bf16 v[56:59], v[168:171], v[196:199], v[56:59]
	v_mfma_f32_16x16x32_bf16 v[44:47], v[150:153], v[204:207], v[44:47]
	v_mfma_f32_16x16x32_bf16 v[40:43], v[168:171], v[204:207], v[40:43]
	v_mfma_f32_16x16x32_bf16 v[28:31], v[150:153], v[212:215], v[28:31]
	v_mfma_f32_16x16x32_bf16 v[24:27], v[168:171], v[212:215], v[24:27]
	v_mfma_f32_16x16x32_bf16 v[12:15], v[150:153], v[220:223], v[12:15]
	v_mfma_f32_16x16x32_bf16 v[8:11], v[168:171], v[220:223], v[8:11]
	s_setprio 0
	s_setprio 1
	v_mfma_f32_16x16x32_bf16 v[52:55], v[172:175], v[192:195], v[52:55]
	v_mfma_f32_16x16x32_bf16 v[48:51], v[184:187], v[192:195], v[48:51]
	v_mfma_f32_16x16x32_bf16 v[36:39], v[172:175], v[200:203], v[36:39]
	v_mfma_f32_16x16x32_bf16 v[32:35], v[184:187], v[200:203], v[32:35]
	v_mfma_f32_16x16x32_bf16 v[20:23], v[172:175], v[208:211], v[20:23]
	v_mfma_f32_16x16x32_bf16 v[16:19], v[184:187], v[208:211], v[16:19]
	v_mfma_f32_16x16x32_bf16 v[4:7], v[172:175], v[216:219], v[4:7]
	v_mfma_f32_16x16x32_bf16 v[0:3], v[184:187], v[216:219], v[0:3]
	v_mfma_f32_16x16x32_bf16 v[52:55], v[180:183], v[196:199], v[52:55]
	v_mfma_f32_16x16x32_bf16 v[48:51], v[188:191], v[196:199], v[48:51]
	v_mfma_f32_16x16x32_bf16 v[36:39], v[180:183], v[204:207], v[36:39]
	v_mfma_f32_16x16x32_bf16 v[32:35], v[188:191], v[204:207], v[32:35]
	v_mfma_f32_16x16x32_bf16 v[20:23], v[180:183], v[212:215], v[20:23]
	v_mfma_f32_16x16x32_bf16 v[16:19], v[188:191], v[212:215], v[16:19]
	s_setprio 2
	s_barrier
	v_mfma_f32_16x16x32_bf16 v[4:7], v[180:183], v[220:223], v[4:7]
	v_mfma_f32_16x16x32_bf16 v[0:3], v[188:191], v[220:223], v[0:3]
	s_setprio 0
	s_add_i32 s60, 0, 0x18000
	v_add_u32_e32 v159, s60, v154
	s_add_i32 s61, 0, 0x1c000
	ds_read_b128 v[146:149], v159
	ds_read_b128 v[150:153], v159 offset:1024
	ds_read_b128 v[160:163], v159 offset:2048
	ds_read_b128 v[168:171], v159 offset:3072
	v_add_u32_e32 v159, s61, v154
	ds_read_b128 v[172:175], v159
	ds_read_b128 v[180:183], v159 offset:1024
	ds_read_b128 v[184:187], v159 offset:2048
	ds_read_b128 v[188:191], v159 offset:3072
	s_add_u32 s30, s30, 0x80000
	s_addc_u32 s31, s31, 0
	s_mov_b32 m0, s43
	v_lshl_add_u64 v[230:231], s[30:31], 0, v[128:129]
	ds_read_b128 v[192:195], v158 offset:32768
	ds_read_b128 v[196:199], v158 offset:33792
	ds_read_b128 v[200:203], v158 offset:34816
	ds_read_b128 v[204:207], v158 offset:35840
	ds_read_b128 v[208:211], v158 offset:36864
	ds_read_b128 v[212:215], v158 offset:37888
	ds_read_b128 v[216:219], v158 offset:38912
	ds_read_b128 v[220:223], v158 offset:39936
	global_load_lds_dwordx4 v[230:231], off
	v_lshl_add_u64 v[230:231], s[30:31], 0, v[132:133]
	s_mov_b32 m0, s44
	s_nop 0
	global_load_lds_dwordx4 v[230:231], off
	s_waitcnt vmcnt(8)
	s_waitcnt lgkmcnt(0)
	s_barrier
	s_setprio 1
	s_waitcnt lgkmcnt(0)
	v_mfma_f32_16x16x32_bf16 v[124:127], v[146:149], v[192:195], v[124:127]
	v_mfma_f32_16x16x32_bf16 v[120:123], v[160:163], v[192:195], v[120:123]
	v_mfma_f32_16x16x32_bf16 v[108:111], v[146:149], v[200:203], v[108:111]
	v_mfma_f32_16x16x32_bf16 v[104:107], v[160:163], v[200:203], v[104:107]
	v_mfma_f32_16x16x32_bf16 v[92:95], v[146:149], v[208:211], v[92:95]
	v_mfma_f32_16x16x32_bf16 v[88:91], v[160:163], v[208:211], v[88:91]
	v_mfma_f32_16x16x32_bf16 v[76:79], v[146:149], v[216:219], v[76:79]
	v_mfma_f32_16x16x32_bf16 v[72:75], v[160:163], v[216:219], v[72:75]
	v_mfma_f32_16x16x32_bf16 v[124:127], v[150:153], v[196:199], v[124:127]
	v_mfma_f32_16x16x32_bf16 v[120:123], v[168:171], v[196:199], v[120:123]
	v_mfma_f32_16x16x32_bf16 v[108:111], v[150:153], v[204:207], v[108:111]
	v_mfma_f32_16x16x32_bf16 v[104:107], v[168:171], v[204:207], v[104:107]
	v_mfma_f32_16x16x32_bf16 v[92:95], v[150:153], v[212:215], v[92:95]
	v_mfma_f32_16x16x32_bf16 v[88:91], v[168:171], v[212:215], v[88:91]
	v_mfma_f32_16x16x32_bf16 v[76:79], v[150:153], v[220:223], v[76:79]
	v_mfma_f32_16x16x32_bf16 v[72:75], v[168:171], v[220:223], v[72:75]
	s_setprio 0
	s_setprio 1
	v_mfma_f32_16x16x32_bf16 v[116:119], v[172:175], v[192:195], v[116:119]
	v_mfma_f32_16x16x32_bf16 v[112:115], v[184:187], v[192:195], v[112:115]
	v_mfma_f32_16x16x32_bf16 v[100:103], v[172:175], v[200:203], v[100:103]
	v_mfma_f32_16x16x32_bf16 v[96:99], v[184:187], v[200:203], v[96:99]
	v_mfma_f32_16x16x32_bf16 v[84:87], v[172:175], v[208:211], v[84:87]
	v_mfma_f32_16x16x32_bf16 v[80:83], v[184:187], v[208:211], v[80:83]
	v_mfma_f32_16x16x32_bf16 v[68:71], v[172:175], v[216:219], v[68:71]
	v_mfma_f32_16x16x32_bf16 v[64:67], v[184:187], v[216:219], v[64:67]
	v_mfma_f32_16x16x32_bf16 v[116:119], v[180:183], v[196:199], v[116:119]
	v_mfma_f32_16x16x32_bf16 v[112:115], v[188:191], v[196:199], v[112:115]
	v_mfma_f32_16x16x32_bf16 v[100:103], v[180:183], v[204:207], v[100:103]
	v_mfma_f32_16x16x32_bf16 v[96:99], v[188:191], v[204:207], v[96:99]
	v_mfma_f32_16x16x32_bf16 v[84:87], v[180:183], v[212:215], v[84:87]
	v_mfma_f32_16x16x32_bf16 v[80:83], v[188:191], v[212:215], v[80:83]
	s_setprio 2
	s_barrier
; #define PG8_STAGE(bufoff, gbase, voff) do { _Pragma("unroll") for (int _i = 0; _i < 2; ++_i) \
;         __builtin_amdgcn_global_load_lds((const unsigned*)((const char*)(gbase) + (voff)[_i]), (LAS unsigned*)(lds + (bufoff) + ldsw + _i * 8192), 16, 0, 0); } while (0)
; #define PG8_LDA(dst, b, h) do { _Pragma("unroll") for (int m = 0; m < 4; ++m) _Pragma("unroll") for (int k = 0; k < 2; ++k) dst[m][k] = *(const LAS bf16x8*)(lds + PG8_SA(b, h) + aoff + m * 2048 + k * 1024); } while (0)
; #define PG8_MMA(ai, bj, At, Bt) do { __builtin_amdgcn_s_setprio(1); _Pragma("unroll") for (int m = 0; m < 4; ++m) _Pragma("unroll") for (int n = 0; n < 2; ++n) _Pragma("unroll") for (int k = 0; k < 2; ++k) \
;         acc[ai][bj][m][n] = __builtin_amdgcn_mfma_f32_16x16x32_bf16(Bt[n][k], At[m][k], acc[ai][bj][m][n], 0, 0, 0); __builtin_amdgcn_s_setprio(0); } while (0)
; #define PG8_WAIT_V(n) asm volatile("s_waitcnt vmcnt(" #n ")" ::: "memory")
; #define PG8_WAIT_L(n) asm volatile("s_waitcnt lgkmcnt(" #n ")" ::: "memory")
; #define PG8_BAR __builtin_amdgcn_s_barrier()
; #define PG8_SCHED __builtin_amdgcn_sched_barrier(0)
; template <class Epi, class Sched, bool ALIGN_EPI = true, bool SP2 = true>
; __device__ __forceinline__ void gemm_phase(LAS unsigned char* lds, const bf16_t* Ag, const bf16_t* Btg, const int K, const int lda, const int ldb, const Sched& S, const Epi& E) {
;     ...
;         for (int t = 0; t < nt; t += 2) {
;     ...
;             PG8_WAIT_V(8); PG8_WAIT_L(0); PG8_BAR; PG8_MMA(0, 0, At, B0); PG8_MMA(0, 1, At, B1); PG8_BAR; PG8_SCHED;
;             PG8_LDA(At, 1, 1); PG8_STAGE(PG8_SB(1, 0), b3, voffB); PG8_STAGE(PG8_SB(1, 1), b3 + hstepB, voffB); PG8_STAGE(PG8_SA(1, 0), a3, voffA);
;             PG8_WAIT_V(8); PG8_WAIT_L(0); PG8_BAR; PG8_MMA(1, 0, At, B0); PG8_MMA(1, 1, At, B1); PG8_BAR; PG8_SCHED;
	v_mfma_f32_16x16x32_bf16 v[68:71], v[180:183], v[220:223], v[68:71]
	v_mfma_f32_16x16x32_bf16 v[64:67], v[188:191], v[220:223], v[64:67]
	s_setprio 0
	s_add_i32 s30, s60, s40
	v_lshl_add_u64 v[164:165], v[164:165], 0, s[6:7]
	s_mov_b32 m0, s30
	ds_read_b128 v[192:195], v158 offset:49152
	ds_read_b128 v[196:199], v158 offset:50176
	ds_read_b128 v[200:203], v158 offset:51200
	ds_read_b128 v[204:207], v158 offset:52224
	ds_read_b128 v[208:211], v158 offset:53248
	ds_read_b128 v[212:215], v158 offset:54272
	ds_read_b128 v[216:219], v158 offset:55296
	ds_read_b128 v[220:223], v158 offset:56320
	global_load_lds_dwordx4 v[164:165], off
	s_add_i32 m0, s30, 0x2000
	s_add_u32 s28, s28, 0x80080
	v_lshl_add_u64 v[164:165], v[224:225], 0, s[6:7]
	s_addc_u32 s29, s29, 0
	s_add_i32 s30, s61, s40
	global_load_lds_dwordx4 v[164:165], off
	v_lshl_add_u64 v[164:165], s[28:29], 0, v[130:131]
	s_mov_b32 m0, s30
	s_nop 0
	global_load_lds_dwordx4 v[164:165], off
	v_lshl_add_u64 v[164:165], s[28:29], 0, v[134:135]
	s_add_i32 m0, s30, 0x2000
	s_nop 0
	global_load_lds_dwordx4 v[164:165], off
	v_lshl_add_u64 v[164:165], v[226:227], 0, s[6:7]
	s_mov_b32 m0, s46
	s_nop 0
	global_load_lds_dwordx4 v[164:165], off
	v_lshl_add_u64 v[164:165], v[228:229], 0, s[6:7]
	s_mov_b32 m0, s47
	s_nop 0
	global_load_lds_dwordx4 v[164:165], off
	s_waitcnt vmcnt(8)
	s_waitcnt lgkmcnt(0)
	s_barrier
	s_setprio 1
	s_waitcnt lgkmcnt(0)
	v_mfma_f32_16x16x32_bf16 v[60:63], v[146:149], v[192:195], v[60:63]
	s_add_i32 s59, s59, 2
	s_add_u32 s26, s26, 0x100
	s_addc_u32 s27, s27, 0
	s_add_u32 s55, s55, 0x100
	s_addc_u32 s58, s58, 0
	s_cmp_gt_u32 s59, 13
	v_mfma_f32_16x16x32_bf16 v[56:59], v[160:163], v[192:195], v[56:59]
	v_mfma_f32_16x16x32_bf16 v[44:47], v[146:149], v[200:203], v[44:47]
	v_mfma_f32_16x16x32_bf16 v[40:43], v[160:163], v[200:203], v[40:43]
	v_mfma_f32_16x16x32_bf16 v[28:31], v[146:149], v[208:211], v[28:31]
	v_mfma_f32_16x16x32_bf16 v[24:27], v[160:163], v[208:211], v[24:27]
	v_mfma_f32_16x16x32_bf16 v[12:15], v[146:149], v[216:219], v[12:15]
	v_mfma_f32_16x16x32_bf16 v[8:11], v[160:163], v[216:219], v[8:11]
	v_mfma_f32_16x16x32_bf16 v[60:63], v[150:153], v[196:199], v[60:63]
	v_mfma_f32_16x16x32_bf16 v[56:59], v[168:171], v[196:199], v[56:59]
	v_mfma_f32_16x16x32_bf16 v[44:47], v[150:153], v[204:207], v[44:47]
	v_mfma_f32_16x16x32_bf16 v[40:43], v[168:171], v[204:207], v[40:43]
	v_mfma_f32_16x16x32_bf16 v[28:31], v[150:153], v[212:215], v[28:31]
	v_mfma_f32_16x16x32_bf16 v[24:27], v[168:171], v[212:215], v[24:27]
	v_mfma_f32_16x16x32_bf16 v[12:15], v[150:153], v[220:223], v[12:15]
	v_mfma_f32_16x16x32_bf16 v[8:11], v[168:171], v[220:223], v[8:11]
	s_setprio 0
	s_setprio 1
	v_mfma_f32_16x16x32_bf16 v[52:55], v[172:175], v[192:195], v[52:55]
	v_mfma_f32_16x16x32_bf16 v[48:51], v[184:187], v[192:195], v[48:51]
	v_mfma_f32_16x16x32_bf16 v[36:39], v[172:175], v[200:203], v[36:39]
	v_mfma_f32_16x16x32_bf16 v[32:35], v[184:187], v[200:203], v[32:35]
	v_mfma_f32_16x16x32_bf16 v[20:23], v[172:175], v[208:211], v[20:23]
	v_mfma_f32_16x16x32_bf16 v[16:19], v[184:187], v[208:211], v[16:19]
	v_mfma_f32_16x16x32_bf16 v[4:7], v[172:175], v[216:219], v[4:7]
	v_mfma_f32_16x16x32_bf16 v[0:3], v[184:187], v[216:219], v[0:3]
	v_mfma_f32_16x16x32_bf16 v[52:55], v[180:183], v[196:199], v[52:55]
	v_mfma_f32_16x16x32_bf16 v[48:51], v[188:191], v[196:199], v[48:51]
	v_mfma_f32_16x16x32_bf16 v[36:39], v[180:183], v[204:207], v[36:39]
	v_mfma_f32_16x16x32_bf16 v[32:35], v[188:191], v[204:207], v[32:35]
	v_mfma_f32_16x16x32_bf16 v[20:23], v[180:183], v[212:215], v[20:23]
	v_mfma_f32_16x16x32_bf16 v[16:19], v[188:191], v[212:215], v[16:19]
	s_setprio 2
	s_barrier
	v_mfma_f32_16x16x32_bf16 v[4:7], v[180:183], v[220:223], v[4:7]
	v_mfma_f32_16x16x32_bf16 v[0:3], v[188:191], v[220:223], v[0:3]
	s_setprio 0
	s_cbranch_scc0 .LBB0_890
	s_and_b64 vcc, exec, s[8:9]
	s_cbranch_vccz .LBB0_893
	s_barrier

; #define PG8_STAGE(bufoff, gbase, voff) do { _Pragma("unroll") for (int _i = 0; _i < 2; ++_i) \
;         __builtin_amdgcn_global_load_lds((const unsigned*)((const char*)(gbase) + (voff)[_i]), (LAS unsigned*)(lds + (bufoff) + ldsw + _i * 8192), 16, 0, 0); } while (0)
; #define PG8_LDA(dst, b, h) do { _Pragma("unroll") for (int m = 0; m < 4; ++m) _Pragma("unroll") for (int k = 0; k < 2; ++k) dst[m][k] = *(const LAS bf16x8*)(lds + PG8_SA(b, h) + aoff + m * 2048 + k * 1024); } while (0)
; #define PG8_LDB(dst, b, h) do { _Pragma("unroll") for (int n = 0; n < 2; ++n) _Pragma("unroll") for (int k = 0; k < 2; ++k) dst[n][k] = *(const LAS bf16x8*)(lds + PG8_SB(b, h) + boff + n * 2048 + k * 1024); } while (0)
; #define PG8_MMA(ai, bj, At, Bt) do { __builtin_amdgcn_s_setprio(1); _Pragma("unroll") for (int m = 0; m < 4; ++m) _Pragma("unroll") for (int n = 0; n < 2; ++n) _Pragma("unroll") for (int k = 0; k < 2; ++k) \
;         acc[ai][bj][m][n] = __builtin_amdgcn_mfma_f32_16x16x32_bf16(Bt[n][k], At[m][k], acc[ai][bj][m][n], 0, 0, 0); __builtin_amdgcn_s_setprio(0); } while (0)
; #define PG8_WAIT_V(n) asm volatile("s_waitcnt vmcnt(" #n ")" ::: "memory")
; #define PG8_WAIT_L(n) asm volatile("s_waitcnt lgkmcnt(" #n ")" ::: "memory")
; #define PG8_BAR __builtin_amdgcn_s_barrier()
; #define PG8_SCHED __builtin_amdgcn_sched_barrier(0)
; template <class Epi, class Sched, bool ALIGN_EPI = true, bool SP2 = true>
; __device__ __forceinline__ void gemm_phase(LAS unsigned char* lds, const bf16_t* Ag, const bf16_t* Btg, const int K, const int lda, const int ldb, const Sched& S, const Epi& E) {
;     ...
;             const bool last = (t == nt - 2);
;             const char* a1 = cA + (size_t)(t + 1) * kstep;
;             const char* a2 = last ? nA : cA + (size_t)(t + 2) * kstep; const char* b2 = last ? nB : cB + (size_t)(t + 2) * kstep;
;             const char* a3 = a2 + kstep; const char* b3 = b2 + kstep;
;             if constexpr (SP2) {
;             PG8_LDB(B0, 0, 0); PG8_LDB(B1, 0, 1); PG8_SCHED; PG8_LDA(At, 0, 0); PG8_STAGE(PG8_SA(1, 1), a1 + hstepA, voffA);
;             PG8_WAIT_V(8); PG8_WAIT_L(0); PG8_BAR; PG8_MMA(0, 0, At, B0); PG8_MMA(0, 1, At, B1); PG8_BAR; PG8_SCHED;
;             PG8_LDA(At, 0, 1); PG8_STAGE(PG8_SB(0, 0), b2, voffB); PG8_STAGE(PG8_SB(0, 1), b2 + hstepB, voffB); PG8_STAGE(PG8_SA(0, 0), a2, voffA);
.LBB0_969:
	ds_read_b128 v[152:155], v149
	ds_read_b128 v[156:159], v149 offset:1024
	ds_read_b128 v[160:163], v149 offset:2048
	ds_read_b128 v[168:171], v149 offset:3072
	ds_read_b128 v[172:175], v150
	ds_read_b128 v[180:183], v150 offset:1024
	ds_read_b128 v[184:187], v150 offset:2048
	ds_read_b128 v[188:191], v150 offset:3072
	s_add_u32 s26, s24, 0xfff80080
	s_addc_u32 s27, s25, -1
	s_cmp_eq_u32 s54, 28
	s_cselect_b32 s29, s33, s27
	s_cselect_b32 s28, s47, s26
	s_cselect_b32 s27, s50, s53
	s_cselect_b32 s26, s51, s52
	v_lshl_add_u64 v[146:147], s[24:25], 0, v[138:139]
	s_add_i32 m0, s34, 0xc000
	ds_read_b128 v[192:195], v151
	ds_read_b128 v[196:199], v151 offset:1024
	ds_read_b128 v[200:203], v151 offset:2048
	ds_read_b128 v[204:207], v151 offset:3072
	ds_read_b128 v[208:211], v151 offset:4096
	ds_read_b128 v[212:215], v151 offset:5120
	ds_read_b128 v[216:219], v151 offset:6144
	ds_read_b128 v[220:223], v151 offset:7168
	global_load_lds_dwordx4 v[146:147], off
	v_lshl_add_u64 v[146:147], s[24:25], 0, v[140:141]
	s_add_i32 m0, s34, 0xe000
	s_nop 0
	global_load_lds_dwordx4 v[146:147], off
	s_waitcnt vmcnt(8)
	s_waitcnt lgkmcnt(0)
	s_barrier
	s_setprio 1
	s_waitcnt lgkmcnt(0)
	v_mfma_f32_16x16x32_bf16 v[124:127], v[152:155], v[192:195], v[124:127]
	v_mfma_f32_16x16x32_bf16 v[120:123], v[160:163], v[192:195], v[120:123]
	v_mfma_f32_16x16x32_bf16 v[116:119], v[152:155], v[200:203], v[116:119]
	v_mfma_f32_16x16x32_bf16 v[108:111], v[160:163], v[200:203], v[108:111]
	v_mfma_f32_16x16x32_bf16 v[92:95], v[152:155], v[208:211], v[92:95]
	v_mfma_f32_16x16x32_bf16 v[88:91], v[160:163], v[208:211], v[88:91]
	v_mfma_f32_16x16x32_bf16 v[76:79], v[152:155], v[216:219], v[76:79]
	v_mfma_f32_16x16x32_bf16 v[72:75], v[160:163], v[216:219], v[72:75]
	v_mfma_f32_16x16x32_bf16 v[124:127], v[156:159], v[196:199], v[124:127]
	v_mfma_f32_16x16x32_bf16 v[120:123], v[168:171], v[196:199], v[120:123]
	v_mfma_f32_16x16x32_bf16 v[116:119], v[156:159], v[204:207], v[116:119]
	v_mfma_f32_16x16x32_bf16 v[108:111], v[168:171], v[204:207], v[108:111]
	v_mfma_f32_16x16x32_bf16 v[92:95], v[156:159], v[212:215], v[92:95]
	v_mfma_f32_16x16x32_bf16 v[88:91], v[168:171], v[212:215], v[88:91]
	v_mfma_f32_16x16x32_bf16 v[76:79], v[156:159], v[220:223], v[76:79]
	v_mfma_f32_16x16x32_bf16 v[72:75], v[168:171], v[220:223], v[72:75]
	s_setprio 0
	s_setprio 1
	v_mfma_f32_16x16x32_bf16 v[112:115], v[172:175], v[192:195], v[112:115]
	v_mfma_f32_16x16x32_bf16 v[104:107], v[184:187], v[192:195], v[104:107]
	v_mfma_f32_16x16x32_bf16 v[100:103], v[172:175], v[200:203], v[100:103]
	v_mfma_f32_16x16x32_bf16 v[96:99], v[184:187], v[200:203], v[96:99]
	v_mfma_f32_16x16x32_bf16 v[84:87], v[172:175], v[208:211], v[84:87]
	v_mfma_f32_16x16x32_bf16 v[80:83], v[184:187], v[208:211], v[80:83]
	v_mfma_f32_16x16x32_bf16 v[68:71], v[172:175], v[216:219], v[68:71]
	v_mfma_f32_16x16x32_bf16 v[64:67], v[184:187], v[216:219], v[64:67]
	v_mfma_f32_16x16x32_bf16 v[112:115], v[180:183], v[196:199], v[112:115]
	v_mfma_f32_16x16x32_bf16 v[104:107], v[188:191], v[196:199], v[104:107]
	v_mfma_f32_16x16x32_bf16 v[100:103], v[180:183], v[204:207], v[100:103]
	v_mfma_f32_16x16x32_bf16 v[96:99], v[188:191], v[204:207], v[96:99]
	v_mfma_f32_16x16x32_bf16 v[84:87], v[180:183], v[212:215], v[84:87]
	v_mfma_f32_16x16x32_bf16 v[80:83], v[188:191], v[212:215], v[80:83]
	s_setprio 2
	s_barrier
	v_mfma_f32_16x16x32_bf16 v[68:71], v[180:183], v[220:223], v[68:71]
	v_mfma_f32_16x16x32_bf16 v[64:67], v[188:191], v[220:223], v[64:67]
	s_setprio 0
	s_add_i32 s55, s44, s31
	v_lshl_add_u64 v[146:147], s[26:27], 0, v[130:131]
	s_mov_b32 m0, s55
	ds_read_b128 v[192:195], v151 offset:16384
	ds_read_b128 v[196:199], v151 offset:17408
	ds_read_b128 v[200:203], v151 offset:18432
	ds_read_b128 v[204:207], v151 offset:19456
	ds_read_b128 v[208:211], v151 offset:20480
	ds_read_b128 v[212:215], v151 offset:21504
	ds_read_b128 v[216:219], v151 offset:22528
	ds_read_b128 v[220:223], v151 offset:23552
	global_load_lds_dwordx4 v[146:147], off
	s_add_i32 m0, s55, 0x2000
	s_add_u32 s58, s26, 0x80000
	v_lshl_add_u64 v[164:165], s[26:27], 0, v[134:135]
	s_addc_u32 s59, s27, 0
	s_add_i32 s55, s45, s31
	global_load_lds_dwordx4 v[164:165], off
	v_lshl_add_u64 v[224:225], s[58:59], 0, v[130:131]
	s_mov_b32 m0, s55
	v_lshl_add_u64 v[226:227], s[28:29], 0, v[132:133]
	global_load_lds_dwordx4 v[224:225], off
	v_lshl_add_u64 v[224:225], s[58:59], 0, v[134:135]
	s_add_i32 m0, s55, 0x2000
	s_nop 0
	global_load_lds_dwordx4 v[224:225], off
	v_lshl_add_u64 v[224:225], s[28:29], 0, v[128:129]
	s_mov_b32 m0, s34
	s_nop 0
	global_load_lds_dwordx4 v[224:225], off
	s_mov_b32 m0, s35
	s_nop 0
	global_load_lds_dwordx4 v[226:227], off
	s_waitcnt vmcnt(8)
	s_waitcnt lgkmcnt(0)
	s_barrier
; #define PG8_STAGE(bufoff, gbase, voff) do { _Pragma("unroll") for (int _i = 0; _i < 2; ++_i) \
;         __builtin_amdgcn_global_load_lds((const unsigned*)((const char*)(gbase) + (voff)[_i]), (LAS unsigned*)(lds + (bufoff) + ldsw + _i * 8192), 16, 0, 0); } while (0)
; #define PG8_LDA(dst, b, h) do { _Pragma("unroll") for (int m = 0; m < 4; ++m) _Pragma("unroll") for (int k = 0; k < 2; ++k) dst[m][k] = *(const LAS bf16x8*)(lds + PG8_SA(b, h) + aoff + m * 2048 + k * 1024); } while (0)
; #define PG8_LDB(dst, b, h) do { _Pragma("unroll") for (int n = 0; n < 2; ++n) _Pragma("unroll") for (int k = 0; k < 2; ++k) dst[n][k] = *(const LAS bf16x8*)(lds + PG8_SB(b, h) + boff + n * 2048 + k * 1024); } while (0)
; #define PG8_MMA(ai, bj, At, Bt) do { __builtin_amdgcn_s_setprio(1); _Pragma("unroll") for (int m = 0; m < 4; ++m) _Pragma("unroll") for (int n = 0; n < 2; ++n) _Pragma("unroll") for (int k = 0; k < 2; ++k) \
;         acc[ai][bj][m][n] = __builtin_amdgcn_mfma_f32_16x16x32_bf16(Bt[n][k], At[m][k], acc[ai][bj][m][n], 0, 0, 0); __builtin_amdgcn_s_setprio(0); } while (0)
; #define PG8_WAIT_V(n) asm volatile("s_waitcnt vmcnt(" #n ")" ::: "memory")
; #define PG8_WAIT_L(n) asm volatile("s_waitcnt lgkmcnt(" #n ")" ::: "memory")
; #define PG8_BAR __builtin_amdgcn_s_barrier()
; #define PG8_SCHED __builtin_amdgcn_sched_barrier(0)
; template <class Epi, class Sched, bool ALIGN_EPI = true, bool SP2 = true>
; __device__ __forceinline__ void gemm_phase(LAS unsigned char* lds, const bf16_t* Ag, const bf16_t* Btg, const int K, const int lda, const int ldb, const Sched& S, const Epi& E) {
;     ...
;             PG8_WAIT_V(8); PG8_WAIT_L(0); PG8_BAR; PG8_MMA(1, 0, At, B0); PG8_MMA(1, 1, At, B1); PG8_BAR; PG8_SCHED;
;             PG8_LDB(B0, 1, 0); PG8_LDB(B1, 1, 1); PG8_SCHED; PG8_LDA(At, 1, 0); PG8_STAGE(PG8_SA(0, 1), a2 + hstepA, voffA);
;             PG8_WAIT_V(8); PG8_WAIT_L(0); PG8_BAR; PG8_MMA(0, 0, At, B0); PG8_MMA(0, 1, At, B1); PG8_BAR; PG8_SCHED;
	s_setprio 1
	s_waitcnt lgkmcnt(0)
	v_mfma_f32_16x16x32_bf16 v[60:63], v[152:155], v[192:195], v[60:63]
	v_mfma_f32_16x16x32_bf16 v[56:59], v[160:163], v[192:195], v[56:59]
	v_mfma_f32_16x16x32_bf16 v[44:47], v[152:155], v[200:203], v[44:47]
	v_mfma_f32_16x16x32_bf16 v[40:43], v[160:163], v[200:203], v[40:43]
	v_mfma_f32_16x16x32_bf16 v[28:31], v[152:155], v[208:211], v[28:31]
	v_mfma_f32_16x16x32_bf16 v[24:27], v[160:163], v[208:211], v[24:27]
	v_mfma_f32_16x16x32_bf16 v[12:15], v[152:155], v[216:219], v[12:15]
	v_mfma_f32_16x16x32_bf16 v[8:11], v[160:163], v[216:219], v[8:11]
	v_mfma_f32_16x16x32_bf16 v[60:63], v[156:159], v[196:199], v[60:63]
	v_mfma_f32_16x16x32_bf16 v[56:59], v[168:171], v[196:199], v[56:59]
	v_mfma_f32_16x16x32_bf16 v[44:47], v[156:159], v[204:207], v[44:47]
	v_mfma_f32_16x16x32_bf16 v[40:43], v[168:171], v[204:207], v[40:43]
	v_mfma_f32_16x16x32_bf16 v[28:31], v[156:159], v[212:215], v[28:31]
	v_mfma_f32_16x16x32_bf16 v[24:27], v[168:171], v[212:215], v[24:27]
	v_mfma_f32_16x16x32_bf16 v[12:15], v[156:159], v[220:223], v[12:15]
	v_mfma_f32_16x16x32_bf16 v[8:11], v[168:171], v[220:223], v[8:11]
	s_setprio 0
	s_setprio 1
	v_mfma_f32_16x16x32_bf16 v[52:55], v[172:175], v[192:195], v[52:55]
	v_mfma_f32_16x16x32_bf16 v[48:51], v[184:187], v[192:195], v[48:51]
	v_mfma_f32_16x16x32_bf16 v[36:39], v[172:175], v[200:203], v[36:39]
	v_mfma_f32_16x16x32_bf16 v[32:35], v[184:187], v[200:203], v[32:35]
	v_mfma_f32_16x16x32_bf16 v[20:23], v[172:175], v[208:211], v[20:23]
	v_mfma_f32_16x16x32_bf16 v[16:19], v[184:187], v[208:211], v[16:19]
	v_mfma_f32_16x16x32_bf16 v[4:7], v[172:175], v[216:219], v[4:7]
	v_mfma_f32_16x16x32_bf16 v[0:3], v[184:187], v[216:219], v[0:3]
	v_mfma_f32_16x16x32_bf16 v[52:55], v[180:183], v[196:199], v[52:55]
	v_mfma_f32_16x16x32_bf16 v[48:51], v[188:191], v[196:199], v[48:51]
	v_mfma_f32_16x16x32_bf16 v[36:39], v[180:183], v[204:207], v[36:39]
	v_mfma_f32_16x16x32_bf16 v[32:35], v[188:191], v[204:207], v[32:35]
	v_mfma_f32_16x16x32_bf16 v[20:23], v[180:183], v[212:215], v[20:23]
	v_mfma_f32_16x16x32_bf16 v[16:19], v[188:191], v[212:215], v[16:19]
	s_setprio 2
	s_barrier
	v_mfma_f32_16x16x32_bf16 v[4:7], v[180:183], v[220:223], v[4:7]
	v_mfma_f32_16x16x32_bf16 v[0:3], v[188:191], v[220:223], v[0:3]
	s_setprio 0
	s_add_i32 s55, 0, 0x18000
	s_add_i32 s58, 0, 0x1c000
	v_add_u32_e32 v168, s55, v148
	v_add_u32_e32 v188, s58, v148
	ds_read_b128 v[152:155], v168
	ds_read_b128 v[156:159], v168 offset:1024
	ds_read_b128 v[160:163], v168 offset:2048
	ds_read_b128 v[168:171], v168 offset:3072
	ds_read_b128 v[172:175], v188
	ds_read_b128 v[180:183], v188 offset:1024
	ds_read_b128 v[184:187], v188 offset:2048
	ds_read_b128 v[188:191], v188 offset:3072
	s_add_u32 s28, s28, 0x80000
	s_addc_u32 s29, s29, 0
	s_mov_b32 m0, s37
	v_lshl_add_u64 v[228:229], s[28:29], 0, v[128:129]
	ds_read_b128 v[192:195], v151 offset:32768
	ds_read_b128 v[196:199], v151 offset:33792
	ds_read_b128 v[200:203], v151 offset:34816
	ds_read_b128 v[204:207], v151 offset:35840
	ds_read_b128 v[208:211], v151 offset:36864
	ds_read_b128 v[212:215], v151 offset:37888
	ds_read_b128 v[216:219], v151 offset:38912
	ds_read_b128 v[220:223], v151 offset:39936
	global_load_lds_dwordx4 v[228:229], off
	v_lshl_add_u64 v[228:229], s[28:29], 0, v[132:133]
	s_mov_b32 m0, s38
	s_nop 0
	global_load_lds_dwordx4 v[228:229], off
	s_waitcnt vmcnt(8)
	s_waitcnt lgkmcnt(0)
	s_barrier
	s_setprio 1
	s_waitcnt lgkmcnt(0)
	v_mfma_f32_16x16x32_bf16 v[124:127], v[152:155], v[192:195], v[124:127]
	v_mfma_f32_16x16x32_bf16 v[120:123], v[160:163], v[192:195], v[120:123]
	v_mfma_f32_16x16x32_bf16 v[116:119], v[152:155], v[200:203], v[116:119]
	v_mfma_f32_16x16x32_bf16 v[108:111], v[160:163], v[200:203], v[108:111]
	v_mfma_f32_16x16x32_bf16 v[92:95], v[152:155], v[208:211], v[92:95]
	v_mfma_f32_16x16x32_bf16 v[88:91], v[160:163], v[208:211], v[88:91]
	v_mfma_f32_16x16x32_bf16 v[76:79], v[152:155], v[216:219], v[76:79]
	v_mfma_f32_16x16x32_bf16 v[72:75], v[160:163], v[216:219], v[72:75]
	v_mfma_f32_16x16x32_bf16 v[124:127], v[156:159], v[196:199], v[124:127]
	v_mfma_f32_16x16x32_bf16 v[120:123], v[168:171], v[196:199], v[120:123]
	v_mfma_f32_16x16x32_bf16 v[116:119], v[156:159], v[204:207], v[116:119]
	v_mfma_f32_16x16x32_bf16 v[108:111], v[168:171], v[204:207], v[108:111]
	v_mfma_f32_16x16x32_bf16 v[92:95], v[156:159], v[212:215], v[92:95]
	v_mfma_f32_16x16x32_bf16 v[88:91], v[168:171], v[212:215], v[88:91]
	v_mfma_f32_16x16x32_bf16 v[76:79], v[156:159], v[220:223], v[76:79]
	v_mfma_f32_16x16x32_bf16 v[72:75], v[168:171], v[220:223], v[72:75]
	s_setprio 0
	s_setprio 1
	v_mfma_f32_16x16x32_bf16 v[112:115], v[172:175], v[192:195], v[112:115]
	v_mfma_f32_16x16x32_bf16 v[104:107], v[184:187], v[192:195], v[104:107]
	v_mfma_f32_16x16x32_bf16 v[100:103], v[172:175], v[200:203], v[100:103]
	v_mfma_f32_16x16x32_bf16 v[96:99], v[184:187], v[200:203], v[96:99]
	v_mfma_f32_16x16x32_bf16 v[84:87], v[172:175], v[208:211], v[84:87]
	v_mfma_f32_16x16x32_bf16 v[80:83], v[184:187], v[208:211], v[80:83]
	v_mfma_f32_16x16x32_bf16 v[68:71], v[172:175], v[216:219], v[68:71]
	v_mfma_f32_16x16x32_bf16 v[64:67], v[184:187], v[216:219], v[64:67]
	v_mfma_f32_16x16x32_bf16 v[112:115], v[180:183], v[196:199], v[112:115]
	v_mfma_f32_16x16x32_bf16 v[104:107], v[188:191], v[196:199], v[104:107]
	v_mfma_f32_16x16x32_bf16 v[100:103], v[180:183], v[204:207], v[100:103]
	v_mfma_f32_16x16x32_bf16 v[96:99], v[188:191], v[204:207], v[96:99]
	v_mfma_f32_16x16x32_bf16 v[84:87], v[180:183], v[212:215], v[84:87]
	v_mfma_f32_16x16x32_bf16 v[80:83], v[188:191], v[212:215], v[80:83]
	s_setprio 2
	s_barrier
; #define PG8_STAGE(bufoff, gbase, voff) do { _Pragma("unroll") for (int _i = 0; _i < 2; ++_i) \
;         __builtin_amdgcn_global_load_lds((const unsigned*)((const char*)(gbase) + (voff)[_i]), (LAS unsigned*)(lds + (bufoff) + ldsw + _i * 8192), 16, 0, 0); } while (0)
; #define PG8_LDA(dst, b, h) do { _Pragma("unroll") for (int m = 0; m < 4; ++m) _Pragma("unroll") for (int k = 0; k < 2; ++k) dst[m][k] = *(const LAS bf16x8*)(lds + PG8_SA(b, h) + aoff + m * 2048 + k * 1024); } while (0)
; #define PG8_MMA(ai, bj, At, Bt) do { __builtin_amdgcn_s_setprio(1); _Pragma("unroll") for (int m = 0; m < 4; ++m) _Pragma("unroll") for (int n = 0; n < 2; ++n) _Pragma("unroll") for (int k = 0; k < 2; ++k) \
;         acc[ai][bj][m][n] = __builtin_amdgcn_mfma_f32_16x16x32_bf16(Bt[n][k], At[m][k], acc[ai][bj][m][n], 0, 0, 0); __builtin_amdgcn_s_setprio(0); } while (0)
; #define PG8_WAIT_V(n) asm volatile("s_waitcnt vmcnt(" #n ")" ::: "memory")
; #define PG8_WAIT_L(n) asm volatile("s_waitcnt lgkmcnt(" #n ")" ::: "memory")
; #define PG8_BAR __builtin_amdgcn_s_barrier()
; #define PG8_SCHED __builtin_amdgcn_sched_barrier(0)
; template <class Epi, class Sched, bool ALIGN_EPI = true, bool SP2 = true>
; __device__ __forceinline__ void gemm_phase(LAS unsigned char* lds, const bf16_t* Ag, const bf16_t* Btg, const int K, const int lda, const int ldb, const Sched& S, const Epi& E) {
;     ...
;         for (int t = 0; t < nt; t += 2) {
;             const bool last = (t == nt - 2);
;     ...
;             PG8_LDA(At, 1, 1); PG8_STAGE(PG8_SB(1, 0), b3, voffB); PG8_STAGE(PG8_SB(1, 1), b3 + hstepB, voffB); PG8_STAGE(PG8_SA(1, 0), a3, voffA);
;             PG8_WAIT_V(8); PG8_WAIT_L(0); PG8_BAR; PG8_MMA(1, 0, At, B0); PG8_MMA(1, 1, At, B1); PG8_BAR; PG8_SCHED;
	v_mfma_f32_16x16x32_bf16 v[68:71], v[180:183], v[220:223], v[68:71]
	v_mfma_f32_16x16x32_bf16 v[64:67], v[188:191], v[220:223], v[64:67]
	s_setprio 0
	s_add_i32 s28, s55, s31
	v_lshl_add_u64 v[146:147], v[146:147], 0, s[6:7]
	s_mov_b32 m0, s28
	ds_read_b128 v[192:195], v151 offset:49152
	ds_read_b128 v[196:199], v151 offset:50176
	ds_read_b128 v[200:203], v151 offset:51200
	ds_read_b128 v[204:207], v151 offset:52224
	ds_read_b128 v[208:211], v151 offset:53248
	ds_read_b128 v[212:215], v151 offset:54272
	ds_read_b128 v[216:219], v151 offset:55296
	ds_read_b128 v[220:223], v151 offset:56320
	global_load_lds_dwordx4 v[146:147], off
	s_add_i32 m0, s28, 0x2000
	s_add_u32 s26, s26, 0x80080
	v_lshl_add_u64 v[146:147], v[164:165], 0, s[6:7]
	s_addc_u32 s27, s27, 0
	s_add_i32 s28, s58, s31
	global_load_lds_dwordx4 v[146:147], off
	v_lshl_add_u64 v[146:147], s[26:27], 0, v[130:131]
	s_mov_b32 m0, s28
	s_nop 0
	global_load_lds_dwordx4 v[146:147], off
	v_lshl_add_u64 v[146:147], s[26:27], 0, v[134:135]
	s_add_i32 m0, s28, 0x2000
	s_nop 0
	global_load_lds_dwordx4 v[146:147], off
	v_lshl_add_u64 v[146:147], v[224:225], 0, s[6:7]
	s_mov_b32 m0, s40
	s_nop 0
	global_load_lds_dwordx4 v[146:147], off
	v_lshl_add_u64 v[146:147], v[226:227], 0, s[6:7]
	s_mov_b32 m0, s41
	s_nop 0
	global_load_lds_dwordx4 v[146:147], off
	s_waitcnt vmcnt(8)
	s_waitcnt lgkmcnt(0)
	s_barrier
	s_setprio 1
	s_waitcnt lgkmcnt(0)
	v_mfma_f32_16x16x32_bf16 v[60:63], v[152:155], v[192:195], v[60:63]
	s_add_i32 s54, s54, 2
	s_add_u32 s24, s24, 0x100
	s_addc_u32 s25, s25, 0
	s_add_u32 s52, s52, 0x100
	s_addc_u32 s53, s53, 0
	s_cmp_gt_u32 s54, 29
	v_mfma_f32_16x16x32_bf16 v[56:59], v[160:163], v[192:195], v[56:59]
	v_mfma_f32_16x16x32_bf16 v[44:47], v[152:155], v[200:203], v[44:47]
	v_mfma_f32_16x16x32_bf16 v[40:43], v[160:163], v[200:203], v[40:43]
	v_mfma_f32_16x16x32_bf16 v[28:31], v[152:155], v[208:211], v[28:31]
	v_mfma_f32_16x16x32_bf16 v[24:27], v[160:163], v[208:211], v[24:27]
	v_mfma_f32_16x16x32_bf16 v[12:15], v[152:155], v[216:219], v[12:15]
	v_mfma_f32_16x16x32_bf16 v[8:11], v[160:163], v[216:219], v[8:11]
	v_mfma_f32_16x16x32_bf16 v[60:63], v[156:159], v[196:199], v[60:63]
	v_mfma_f32_16x16x32_bf16 v[56:59], v[168:171], v[196:199], v[56:59]
	v_mfma_f32_16x16x32_bf16 v[44:47], v[156:159], v[204:207], v[44:47]
	v_mfma_f32_16x16x32_bf16 v[40:43], v[168:171], v[204:207], v[40:43]
	v_mfma_f32_16x16x32_bf16 v[28:31], v[156:159], v[212:215], v[28:31]
	v_mfma_f32_16x16x32_bf16 v[24:27], v[168:171], v[212:215], v[24:27]
	v_mfma_f32_16x16x32_bf16 v[12:15], v[156:159], v[220:223], v[12:15]
	v_mfma_f32_16x16x32_bf16 v[8:11], v[168:171], v[220:223], v[8:11]
	s_setprio 0
	s_setprio 1
	v_mfma_f32_16x16x32_bf16 v[52:55], v[172:175], v[192:195], v[52:55]
	v_mfma_f32_16x16x32_bf16 v[48:51], v[184:187], v[192:195], v[48:51]
	v_mfma_f32_16x16x32_bf16 v[36:39], v[172:175], v[200:203], v[36:39]
	v_mfma_f32_16x16x32_bf16 v[32:35], v[184:187], v[200:203], v[32:35]
	v_mfma_f32_16x16x32_bf16 v[20:23], v[172:175], v[208:211], v[20:23]
	v_mfma_f32_16x16x32_bf16 v[16:19], v[184:187], v[208:211], v[16:19]
	v_mfma_f32_16x16x32_bf16 v[4:7], v[172:175], v[216:219], v[4:7]
	v_mfma_f32_16x16x32_bf16 v[0:3], v[184:187], v[216:219], v[0:3]
	v_mfma_f32_16x16x32_bf16 v[52:55], v[180:183], v[196:199], v[52:55]
	v_mfma_f32_16x16x32_bf16 v[48:51], v[188:191], v[196:199], v[48:51]
	v_mfma_f32_16x16x32_bf16 v[36:39], v[180:183], v[204:207], v[36:39]
	v_mfma_f32_16x16x32_bf16 v[32:35], v[188:191], v[204:207], v[32:35]
	v_mfma_f32_16x16x32_bf16 v[20:23], v[180:183], v[212:215], v[20:23]
	v_mfma_f32_16x16x32_bf16 v[16:19], v[188:191], v[212:215], v[16:19]
	s_setprio 2
	s_barrier
	v_mfma_f32_16x16x32_bf16 v[4:7], v[180:183], v[220:223], v[4:7]
	v_mfma_f32_16x16x32_bf16 v[0:3], v[188:191], v[220:223], v[0:3]
	s_setprio 0
	s_cbranch_scc0 .LBB0_969
	s_and_b64 vcc, exec, s[8:9]
	s_cbranch_vccz .LBB0_972
	s_barrier

; #define PG8_STAGE(bufoff, gbase, voff) do { _Pragma("unroll") for (int _i = 0; _i < 2; ++_i) \
;         __builtin_amdgcn_global_load_lds((const unsigned*)((const char*)(gbase) + (voff)[_i]), (LAS unsigned*)(lds + (bufoff) + ldsw + _i * 8192), 16, 0, 0); } while (0)
; #define PG8_LDA(dst, b, h) do { _Pragma("unroll") for (int m = 0; m < 4; ++m) _Pragma("unroll") for (int k = 0; k < 2; ++k) dst[m][k] = *(const LAS bf16x8*)(lds + PG8_SA(b, h) + aoff + m * 2048 + k * 1024); } while (0)
; #define PG8_LDB(dst, b, h) do { _Pragma("unroll") for (int n = 0; n < 2; ++n) _Pragma("unroll") for (int k = 0; k < 2; ++k) dst[n][k] = *(const LAS bf16x8*)(lds + PG8_SB(b, h) + boff + n * 2048 + k * 1024); } while (0)
; #define PG8_MMA(ai, bj, At, Bt) do { __builtin_amdgcn_s_setprio(1); _Pragma("unroll") for (int m = 0; m < 4; ++m) _Pragma("unroll") for (int n = 0; n < 2; ++n) _Pragma("unroll") for (int k = 0; k < 2; ++k) \
;         acc[ai][bj][m][n] = __builtin_amdgcn_mfma_f32_16x16x32_bf16(Bt[n][k], At[m][k], acc[ai][bj][m][n], 0, 0, 0); __builtin_amdgcn_s_setprio(0); } while (0)
; #define PG8_WAIT_V(n) asm volatile("s_waitcnt vmcnt(" #n ")" ::: "memory")
; #define PG8_WAIT_L(n) asm volatile("s_waitcnt lgkmcnt(" #n ")" ::: "memory")
; #define PG8_BAR __builtin_amdgcn_s_barrier()
; #define PG8_SCHED __builtin_amdgcn_sched_barrier(0)
; template <class Epi, class Sched, bool ALIGN_EPI = true, bool SP2 = true>
; __device__ __forceinline__ void gemm_phase(LAS unsigned char* lds, const bf16_t* Ag, const bf16_t* Btg, const int K, const int lda, const int ldb, const Sched& S, const Epi& E) {
;     ...
;             const bool last = (t == nt - 2);
;             const char* a1 = cA + (size_t)(t + 1) * kstep;
;             const char* a2 = last ? nA : cA + (size_t)(t + 2) * kstep; const char* b2 = last ? nB : cB + (size_t)(t + 2) * kstep;
;             const char* a3 = a2 + kstep; const char* b3 = b2 + kstep;
;             if constexpr (SP2) {
;             PG8_LDB(B0, 0, 0); PG8_LDB(B1, 0, 1); PG8_SCHED; PG8_LDA(At, 0, 0); PG8_STAGE(PG8_SA(1, 1), a1 + hstepA, voffA);
;             PG8_WAIT_V(8); PG8_WAIT_L(0); PG8_BAR; PG8_MMA(0, 0, At, B0); PG8_MMA(0, 1, At, B1); PG8_BAR; PG8_SCHED;
;             PG8_LDA(At, 0, 1); PG8_STAGE(PG8_SB(0, 0), b2, voffB); PG8_STAGE(PG8_SB(0, 1), b2 + hstepB, voffB); PG8_STAGE(PG8_SA(0, 0), a2, voffA);
.LBB0_1236:
	ds_read_b128 v[152:155], v149
	ds_read_b128 v[156:159], v149 offset:1024
	ds_read_b128 v[160:163], v149 offset:2048
	ds_read_b128 v[168:171], v149 offset:3072
	ds_read_b128 v[172:175], v150
	ds_read_b128 v[180:183], v150 offset:1024
	ds_read_b128 v[184:187], v150 offset:2048
	ds_read_b128 v[188:191], v150 offset:3072
	s_add_u32 s44, s42, 0xfffc0080
	s_addc_u32 s45, s43, -1
	s_cmp_eq_u32 s70, 12
	s_cselect_b32 s51, s33, s45
	s_cselect_b32 s50, s65, s44
	s_cselect_b32 s45, s66, s69
	s_cselect_b32 s44, s67, s68
	v_lshl_add_u64 v[146:147], s[42:43], 0, v[138:139]
	s_add_i32 m0, s41, 0xc000
	ds_read_b128 v[192:195], v151
	ds_read_b128 v[196:199], v151 offset:1024
	ds_read_b128 v[200:203], v151 offset:2048
	ds_read_b128 v[204:207], v151 offset:3072
	ds_read_b128 v[208:211], v151 offset:4096
	ds_read_b128 v[212:215], v151 offset:5120
	ds_read_b128 v[216:219], v151 offset:6144
	ds_read_b128 v[220:223], v151 offset:7168
	global_load_lds_dwordx4 v[146:147], off
	v_lshl_add_u64 v[146:147], s[42:43], 0, v[140:141]
	s_add_i32 m0, s41, 0xe000
	s_nop 0
	global_load_lds_dwordx4 v[146:147], off
	s_waitcnt vmcnt(8)
	s_waitcnt lgkmcnt(0)
	s_barrier
	s_setprio 1
	s_waitcnt lgkmcnt(0)
	v_mfma_f32_16x16x32_bf16 v[124:127], v[152:155], v[192:195], v[124:127]
	v_mfma_f32_16x16x32_bf16 v[120:123], v[160:163], v[192:195], v[120:123]
	v_mfma_f32_16x16x32_bf16 v[116:119], v[152:155], v[200:203], v[116:119]
	v_mfma_f32_16x16x32_bf16 v[108:111], v[160:163], v[200:203], v[108:111]
	v_mfma_f32_16x16x32_bf16 v[92:95], v[152:155], v[208:211], v[92:95]
	v_mfma_f32_16x16x32_bf16 v[88:91], v[160:163], v[208:211], v[88:91]
	v_mfma_f32_16x16x32_bf16 v[76:79], v[152:155], v[216:219], v[76:79]
	v_mfma_f32_16x16x32_bf16 v[72:75], v[160:163], v[216:219], v[72:75]
	v_mfma_f32_16x16x32_bf16 v[124:127], v[156:159], v[196:199], v[124:127]
	v_mfma_f32_16x16x32_bf16 v[120:123], v[168:171], v[196:199], v[120:123]
	v_mfma_f32_16x16x32_bf16 v[116:119], v[156:159], v[204:207], v[116:119]
	v_mfma_f32_16x16x32_bf16 v[108:111], v[168:171], v[204:207], v[108:111]
	v_mfma_f32_16x16x32_bf16 v[92:95], v[156:159], v[212:215], v[92:95]
	v_mfma_f32_16x16x32_bf16 v[88:91], v[168:171], v[212:215], v[88:91]
	v_mfma_f32_16x16x32_bf16 v[76:79], v[156:159], v[220:223], v[76:79]
	v_mfma_f32_16x16x32_bf16 v[72:75], v[168:171], v[220:223], v[72:75]
	s_setprio 0
	s_setprio 1
	v_mfma_f32_16x16x32_bf16 v[112:115], v[172:175], v[192:195], v[112:115]
	v_mfma_f32_16x16x32_bf16 v[104:107], v[184:187], v[192:195], v[104:107]
	v_mfma_f32_16x16x32_bf16 v[100:103], v[172:175], v[200:203], v[100:103]
	v_mfma_f32_16x16x32_bf16 v[96:99], v[184:187], v[200:203], v[96:99]
	v_mfma_f32_16x16x32_bf16 v[84:87], v[172:175], v[208:211], v[84:87]
	v_mfma_f32_16x16x32_bf16 v[80:83], v[184:187], v[208:211], v[80:83]
	v_mfma_f32_16x16x32_bf16 v[68:71], v[172:175], v[216:219], v[68:71]
	v_mfma_f32_16x16x32_bf16 v[64:67], v[184:187], v[216:219], v[64:67]
	v_mfma_f32_16x16x32_bf16 v[112:115], v[180:183], v[196:199], v[112:115]
	v_mfma_f32_16x16x32_bf16 v[104:107], v[188:191], v[196:199], v[104:107]
	v_mfma_f32_16x16x32_bf16 v[100:103], v[180:183], v[204:207], v[100:103]
	v_mfma_f32_16x16x32_bf16 v[96:99], v[188:191], v[204:207], v[96:99]
	v_mfma_f32_16x16x32_bf16 v[84:87], v[180:183], v[212:215], v[84:87]
	v_mfma_f32_16x16x32_bf16 v[80:83], v[188:191], v[212:215], v[80:83]
	s_setprio 2
	s_barrier
	v_mfma_f32_16x16x32_bf16 v[68:71], v[180:183], v[220:223], v[68:71]
	v_mfma_f32_16x16x32_bf16 v[64:67], v[188:191], v[220:223], v[64:67]
	s_setprio 0
	s_add_i32 s71, s60, s40
	v_lshl_add_u64 v[146:147], s[44:45], 0, v[130:131]
	s_mov_b32 m0, s71
	ds_read_b128 v[192:195], v151 offset:16384
	ds_read_b128 v[196:199], v151 offset:17408
	ds_read_b128 v[200:203], v151 offset:18432
	ds_read_b128 v[204:207], v151 offset:19456
	ds_read_b128 v[208:211], v151 offset:20480
	ds_read_b128 v[212:215], v151 offset:21504
	ds_read_b128 v[216:219], v151 offset:22528
	ds_read_b128 v[220:223], v151 offset:23552
	global_load_lds_dwordx4 v[146:147], off
	s_add_i32 m0, s71, 0x2000
	s_add_u32 s72, s44, 0x40000
	v_lshl_add_u64 v[164:165], s[44:45], 0, v[134:135]
	s_addc_u32 s73, s45, 0
	s_add_i32 s71, s61, s40
	global_load_lds_dwordx4 v[164:165], off
	v_lshl_add_u64 v[224:225], s[72:73], 0, v[130:131]
	s_mov_b32 m0, s71
	v_lshl_add_u64 v[226:227], s[50:51], 0, v[132:133]
	global_load_lds_dwordx4 v[224:225], off
	v_lshl_add_u64 v[224:225], s[72:73], 0, v[134:135]
	s_add_i32 m0, s71, 0x2000
	s_nop 0
	global_load_lds_dwordx4 v[224:225], off
	v_lshl_add_u64 v[224:225], s[50:51], 0, v[128:129]
	s_mov_b32 m0, s41
	s_nop 0
	global_load_lds_dwordx4 v[224:225], off
	s_mov_b32 m0, s46
	s_nop 0
	global_load_lds_dwordx4 v[226:227], off
	s_waitcnt vmcnt(8)
	s_waitcnt lgkmcnt(0)
	s_barrier
; #define PG8_STAGE(bufoff, gbase, voff) do { _Pragma("unroll") for (int _i = 0; _i < 2; ++_i) \
;         __builtin_amdgcn_global_load_lds((const unsigned*)((const char*)(gbase) + (voff)[_i]), (LAS unsigned*)(lds + (bufoff) + ldsw + _i * 8192), 16, 0, 0); } while (0)
; #define PG8_LDA(dst, b, h) do { _Pragma("unroll") for (int m = 0; m < 4; ++m) _Pragma("unroll") for (int k = 0; k < 2; ++k) dst[m][k] = *(const LAS bf16x8*)(lds + PG8_SA(b, h) + aoff + m * 2048 + k * 1024); } while (0)
; #define PG8_LDB(dst, b, h) do { _Pragma("unroll") for (int n = 0; n < 2; ++n) _Pragma("unroll") for (int k = 0; k < 2; ++k) dst[n][k] = *(const LAS bf16x8*)(lds + PG8_SB(b, h) + boff + n * 2048 + k * 1024); } while (0)
; #define PG8_MMA(ai, bj, At, Bt) do { __builtin_amdgcn_s_setprio(1); _Pragma("unroll") for (int m = 0; m < 4; ++m) _Pragma("unroll") for (int n = 0; n < 2; ++n) _Pragma("unroll") for (int k = 0; k < 2; ++k) \
;         acc[ai][bj][m][n] = __builtin_amdgcn_mfma_f32_16x16x32_bf16(Bt[n][k], At[m][k], acc[ai][bj][m][n], 0, 0, 0); __builtin_amdgcn_s_setprio(0); } while (0)
; #define PG8_WAIT_V(n) asm volatile("s_waitcnt vmcnt(" #n ")" ::: "memory")
; #define PG8_WAIT_L(n) asm volatile("s_waitcnt lgkmcnt(" #n ")" ::: "memory")
; #define PG8_BAR __builtin_amdgcn_s_barrier()
; #define PG8_SCHED __builtin_amdgcn_sched_barrier(0)
; template <class Epi, class Sched, bool ALIGN_EPI = true, bool SP2 = true>
; __device__ __forceinline__ void gemm_phase(LAS unsigned char* lds, const bf16_t* Ag, const bf16_t* Btg, const int K, const int lda, const int ldb, const Sched& S, const Epi& E) {
;     ...
;             PG8_WAIT_V(8); PG8_WAIT_L(0); PG8_BAR; PG8_MMA(1, 0, At, B0); PG8_MMA(1, 1, At, B1); PG8_BAR; PG8_SCHED;
;             PG8_LDB(B0, 1, 0); PG8_LDB(B1, 1, 1); PG8_SCHED; PG8_LDA(At, 1, 0); PG8_STAGE(PG8_SA(0, 1), a2 + hstepA, voffA);
;             PG8_WAIT_V(8); PG8_WAIT_L(0); PG8_BAR; PG8_MMA(0, 0, At, B0); PG8_MMA(0, 1, At, B1); PG8_BAR; PG8_SCHED;
	s_setprio 1
	s_waitcnt lgkmcnt(0)
	v_mfma_f32_16x16x32_bf16 v[60:63], v[152:155], v[192:195], v[60:63]
	v_mfma_f32_16x16x32_bf16 v[56:59], v[160:163], v[192:195], v[56:59]
	v_mfma_f32_16x16x32_bf16 v[44:47], v[152:155], v[200:203], v[44:47]
	v_mfma_f32_16x16x32_bf16 v[40:43], v[160:163], v[200:203], v[40:43]
	v_mfma_f32_16x16x32_bf16 v[28:31], v[152:155], v[208:211], v[28:31]
	v_mfma_f32_16x16x32_bf16 v[24:27], v[160:163], v[208:211], v[24:27]
	v_mfma_f32_16x16x32_bf16 v[12:15], v[152:155], v[216:219], v[12:15]
	v_mfma_f32_16x16x32_bf16 v[8:11], v[160:163], v[216:219], v[8:11]
	v_mfma_f32_16x16x32_bf16 v[60:63], v[156:159], v[196:199], v[60:63]
	v_mfma_f32_16x16x32_bf16 v[56:59], v[168:171], v[196:199], v[56:59]
	v_mfma_f32_16x16x32_bf16 v[44:47], v[156:159], v[204:207], v[44:47]
	v_mfma_f32_16x16x32_bf16 v[40:43], v[168:171], v[204:207], v[40:43]
	v_mfma_f32_16x16x32_bf16 v[28:31], v[156:159], v[212:215], v[28:31]
	v_mfma_f32_16x16x32_bf16 v[24:27], v[168:171], v[212:215], v[24:27]
	v_mfma_f32_16x16x32_bf16 v[12:15], v[156:159], v[220:223], v[12:15]
	v_mfma_f32_16x16x32_bf16 v[8:11], v[168:171], v[220:223], v[8:11]
	s_setprio 0
	s_setprio 1
	v_mfma_f32_16x16x32_bf16 v[52:55], v[172:175], v[192:195], v[52:55]
	v_mfma_f32_16x16x32_bf16 v[48:51], v[184:187], v[192:195], v[48:51]
	v_mfma_f32_16x16x32_bf16 v[36:39], v[172:175], v[200:203], v[36:39]
	v_mfma_f32_16x16x32_bf16 v[32:35], v[184:187], v[200:203], v[32:35]
	v_mfma_f32_16x16x32_bf16 v[20:23], v[172:175], v[208:211], v[20:23]
	v_mfma_f32_16x16x32_bf16 v[16:19], v[184:187], v[208:211], v[16:19]
	v_mfma_f32_16x16x32_bf16 v[4:7], v[172:175], v[216:219], v[4:7]
	v_mfma_f32_16x16x32_bf16 v[0:3], v[184:187], v[216:219], v[0:3]
	v_mfma_f32_16x16x32_bf16 v[52:55], v[180:183], v[196:199], v[52:55]
	v_mfma_f32_16x16x32_bf16 v[48:51], v[188:191], v[196:199], v[48:51]
	v_mfma_f32_16x16x32_bf16 v[36:39], v[180:183], v[204:207], v[36:39]
	v_mfma_f32_16x16x32_bf16 v[32:35], v[188:191], v[204:207], v[32:35]
	v_mfma_f32_16x16x32_bf16 v[20:23], v[180:183], v[212:215], v[20:23]
	v_mfma_f32_16x16x32_bf16 v[16:19], v[188:191], v[212:215], v[16:19]
	s_setprio 2
	s_barrier
	v_mfma_f32_16x16x32_bf16 v[4:7], v[180:183], v[220:223], v[4:7]
	v_mfma_f32_16x16x32_bf16 v[0:3], v[188:191], v[220:223], v[0:3]
	s_setprio 0
	s_add_i32 s71, 0, 0x18000
	s_add_i32 s72, 0, 0x1c000
	v_add_u32_e32 v168, s71, v148
	v_add_u32_e32 v188, s72, v148
	ds_read_b128 v[152:155], v168
	ds_read_b128 v[156:159], v168 offset:1024
	ds_read_b128 v[160:163], v168 offset:2048
	ds_read_b128 v[168:171], v168 offset:3072
	ds_read_b128 v[172:175], v188
	ds_read_b128 v[180:183], v188 offset:1024
	ds_read_b128 v[184:187], v188 offset:2048
	ds_read_b128 v[188:191], v188 offset:3072
	s_add_u32 s50, s50, 0x40000
	s_addc_u32 s51, s51, 0
	s_mov_b32 m0, s47
	v_lshl_add_u64 v[228:229], s[50:51], 0, v[128:129]
	ds_read_b128 v[192:195], v151 offset:32768
	ds_read_b128 v[196:199], v151 offset:33792
	ds_read_b128 v[200:203], v151 offset:34816
	ds_read_b128 v[204:207], v151 offset:35840
	ds_read_b128 v[208:211], v151 offset:36864
	ds_read_b128 v[212:215], v151 offset:37888
	ds_read_b128 v[216:219], v151 offset:38912
	ds_read_b128 v[220:223], v151 offset:39936
	global_load_lds_dwordx4 v[228:229], off
	v_lshl_add_u64 v[228:229], s[50:51], 0, v[132:133]
	s_mov_b32 m0, s52
	s_nop 0
	global_load_lds_dwordx4 v[228:229], off
	s_waitcnt vmcnt(8)
	s_waitcnt lgkmcnt(0)
	s_barrier
	s_setprio 1
	s_waitcnt lgkmcnt(0)
	v_mfma_f32_16x16x32_bf16 v[124:127], v[152:155], v[192:195], v[124:127]
	v_mfma_f32_16x16x32_bf16 v[120:123], v[160:163], v[192:195], v[120:123]
	v_mfma_f32_16x16x32_bf16 v[116:119], v[152:155], v[200:203], v[116:119]
	v_mfma_f32_16x16x32_bf16 v[108:111], v[160:163], v[200:203], v[108:111]
	v_mfma_f32_16x16x32_bf16 v[92:95], v[152:155], v[208:211], v[92:95]
	v_mfma_f32_16x16x32_bf16 v[88:91], v[160:163], v[208:211], v[88:91]
	v_mfma_f32_16x16x32_bf16 v[76:79], v[152:155], v[216:219], v[76:79]
	v_mfma_f32_16x16x32_bf16 v[72:75], v[160:163], v[216:219], v[72:75]
	v_mfma_f32_16x16x32_bf16 v[124:127], v[156:159], v[196:199], v[124:127]
	v_mfma_f32_16x16x32_bf16 v[120:123], v[168:171], v[196:199], v[120:123]
	v_mfma_f32_16x16x32_bf16 v[116:119], v[156:159], v[204:207], v[116:119]
	v_mfma_f32_16x16x32_bf16 v[108:111], v[168:171], v[204:207], v[108:111]
	v_mfma_f32_16x16x32_bf16 v[92:95], v[156:159], v[212:215], v[92:95]
	v_mfma_f32_16x16x32_bf16 v[88:91], v[168:171], v[212:215], v[88:91]
	v_mfma_f32_16x16x32_bf16 v[76:79], v[156:159], v[220:223], v[76:79]
	v_mfma_f32_16x16x32_bf16 v[72:75], v[168:171], v[220:223], v[72:75]
	s_setprio 0
	s_setprio 1
	v_mfma_f32_16x16x32_bf16 v[112:115], v[172:175], v[192:195], v[112:115]
	v_mfma_f32_16x16x32_bf16 v[104:107], v[184:187], v[192:195], v[104:107]
	v_mfma_f32_16x16x32_bf16 v[100:103], v[172:175], v[200:203], v[100:103]
	v_mfma_f32_16x16x32_bf16 v[96:99], v[184:187], v[200:203], v[96:99]
	v_mfma_f32_16x16x32_bf16 v[84:87], v[172:175], v[208:211], v[84:87]
	v_mfma_f32_16x16x32_bf16 v[80:83], v[184:187], v[208:211], v[80:83]
	v_mfma_f32_16x16x32_bf16 v[68:71], v[172:175], v[216:219], v[68:71]
	v_mfma_f32_16x16x32_bf16 v[64:67], v[184:187], v[216:219], v[64:67]
	v_mfma_f32_16x16x32_bf16 v[112:115], v[180:183], v[196:199], v[112:115]
	v_mfma_f32_16x16x32_bf16 v[104:107], v[188:191], v[196:199], v[104:107]
	v_mfma_f32_16x16x32_bf16 v[100:103], v[180:183], v[204:207], v[100:103]
	v_mfma_f32_16x16x32_bf16 v[96:99], v[188:191], v[204:207], v[96:99]
	v_mfma_f32_16x16x32_bf16 v[84:87], v[180:183], v[212:215], v[84:87]
	v_mfma_f32_16x16x32_bf16 v[80:83], v[188:191], v[212:215], v[80:83]
	s_setprio 2
	s_barrier
; #define PG8_STAGE(bufoff, gbase, voff) do { _Pragma("unroll") for (int _i = 0; _i < 2; ++_i) \
;         __builtin_amdgcn_global_load_lds((const unsigned*)((const char*)(gbase) + (voff)[_i]), (LAS unsigned*)(lds + (bufoff) + ldsw + _i * 8192), 16, 0, 0); } while (0)
; #define PG8_LDA(dst, b, h) do { _Pragma("unroll") for (int m = 0; m < 4; ++m) _Pragma("unroll") for (int k = 0; k < 2; ++k) dst[m][k] = *(const LAS bf16x8*)(lds + PG8_SA(b, h) + aoff + m * 2048 + k * 1024); } while (0)
; #define PG8_MMA(ai, bj, At, Bt) do { __builtin_amdgcn_s_setprio(1); _Pragma("unroll") for (int m = 0; m < 4; ++m) _Pragma("unroll") for (int n = 0; n < 2; ++n) _Pragma("unroll") for (int k = 0; k < 2; ++k) \
;         acc[ai][bj][m][n] = __builtin_amdgcn_mfma_f32_16x16x32_bf16(Bt[n][k], At[m][k], acc[ai][bj][m][n], 0, 0, 0); __builtin_amdgcn_s_setprio(0); } while (0)
; #define PG8_WAIT_V(n) asm volatile("s_waitcnt vmcnt(" #n ")" ::: "memory")
; #define PG8_WAIT_L(n) asm volatile("s_waitcnt lgkmcnt(" #n ")" ::: "memory")
; #define PG8_BAR __builtin_amdgcn_s_barrier()
; #define PG8_SCHED __builtin_amdgcn_sched_barrier(0)
; template <class Epi, class Sched, bool ALIGN_EPI = true, bool SP2 = true>
; __device__ __forceinline__ void gemm_phase(LAS unsigned char* lds, const bf16_t* Ag, const bf16_t* Btg, const int K, const int lda, const int ldb, const Sched& S, const Epi& E) {
;     ...
;         for (int t = 0; t < nt; t += 2) {
;             const bool last = (t == nt - 2);
;     ...
;             PG8_LDA(At, 1, 1); PG8_STAGE(PG8_SB(1, 0), b3, voffB); PG8_STAGE(PG8_SB(1, 1), b3 + hstepB, voffB); PG8_STAGE(PG8_SA(1, 0), a3, voffA);
;             PG8_WAIT_V(8); PG8_WAIT_L(0); PG8_BAR; PG8_MMA(1, 0, At, B0); PG8_MMA(1, 1, At, B1); PG8_BAR; PG8_SCHED;
	v_mfma_f32_16x16x32_bf16 v[68:71], v[180:183], v[220:223], v[68:71]
	v_mfma_f32_16x16x32_bf16 v[64:67], v[188:191], v[220:223], v[64:67]
	s_setprio 0
	s_add_i32 s50, s71, s40
	v_lshl_add_u64 v[146:147], v[146:147], 0, s[8:9]
	s_mov_b32 m0, s50
	ds_read_b128 v[192:195], v151 offset:49152
	ds_read_b128 v[196:199], v151 offset:50176
	ds_read_b128 v[200:203], v151 offset:51200
	ds_read_b128 v[204:207], v151 offset:52224
	ds_read_b128 v[208:211], v151 offset:53248
	ds_read_b128 v[212:215], v151 offset:54272
	ds_read_b128 v[216:219], v151 offset:55296
	ds_read_b128 v[220:223], v151 offset:56320
	global_load_lds_dwordx4 v[146:147], off
	s_add_i32 m0, s50, 0x2000
	s_add_u32 s44, s44, 0x40080
	v_lshl_add_u64 v[146:147], v[164:165], 0, s[8:9]
	s_addc_u32 s45, s45, 0
	s_add_i32 s50, s72, s40
	global_load_lds_dwordx4 v[146:147], off
	v_lshl_add_u64 v[146:147], s[44:45], 0, v[130:131]
	s_mov_b32 m0, s50
	s_nop 0
	global_load_lds_dwordx4 v[146:147], off
	v_lshl_add_u64 v[146:147], s[44:45], 0, v[134:135]
	s_add_i32 m0, s50, 0x2000
	s_nop 0
	global_load_lds_dwordx4 v[146:147], off
	v_lshl_add_u64 v[146:147], v[224:225], 0, s[8:9]
	s_mov_b32 m0, s54
	s_nop 0
	global_load_lds_dwordx4 v[146:147], off
	v_lshl_add_u64 v[146:147], v[226:227], 0, s[8:9]
	s_mov_b32 m0, s55
	s_nop 0
	global_load_lds_dwordx4 v[146:147], off
	s_waitcnt vmcnt(8)
	s_waitcnt lgkmcnt(0)
	s_barrier
	s_setprio 1
	s_waitcnt lgkmcnt(0)
	v_mfma_f32_16x16x32_bf16 v[60:63], v[152:155], v[192:195], v[60:63]
	s_add_i32 s70, s70, 2
	s_add_u32 s42, s42, 0x100
	s_addc_u32 s43, s43, 0
	s_add_u32 s68, s68, 0x100
	s_addc_u32 s69, s69, 0
	s_cmp_gt_u32 s70, 13
	v_mfma_f32_16x16x32_bf16 v[56:59], v[160:163], v[192:195], v[56:59]
	v_mfma_f32_16x16x32_bf16 v[44:47], v[152:155], v[200:203], v[44:47]
	v_mfma_f32_16x16x32_bf16 v[40:43], v[160:163], v[200:203], v[40:43]
	v_mfma_f32_16x16x32_bf16 v[28:31], v[152:155], v[208:211], v[28:31]
	v_mfma_f32_16x16x32_bf16 v[24:27], v[160:163], v[208:211], v[24:27]
	v_mfma_f32_16x16x32_bf16 v[12:15], v[152:155], v[216:219], v[12:15]
	v_mfma_f32_16x16x32_bf16 v[8:11], v[160:163], v[216:219], v[8:11]
	v_mfma_f32_16x16x32_bf16 v[60:63], v[156:159], v[196:199], v[60:63]
	v_mfma_f32_16x16x32_bf16 v[56:59], v[168:171], v[196:199], v[56:59]
	v_mfma_f32_16x16x32_bf16 v[44:47], v[156:159], v[204:207], v[44:47]
	v_mfma_f32_16x16x32_bf16 v[40:43], v[168:171], v[204:207], v[40:43]
	v_mfma_f32_16x16x32_bf16 v[28:31], v[156:159], v[212:215], v[28:31]
	v_mfma_f32_16x16x32_bf16 v[24:27], v[168:171], v[212:215], v[24:27]
	v_mfma_f32_16x16x32_bf16 v[12:15], v[156:159], v[220:223], v[12:15]
	v_mfma_f32_16x16x32_bf16 v[8:11], v[168:171], v[220:223], v[8:11]
	s_setprio 0
	s_setprio 1
	v_mfma_f32_16x16x32_bf16 v[52:55], v[172:175], v[192:195], v[52:55]
	v_mfma_f32_16x16x32_bf16 v[48:51], v[184:187], v[192:195], v[48:51]
	v_mfma_f32_16x16x32_bf16 v[36:39], v[172:175], v[200:203], v[36:39]
	v_mfma_f32_16x16x32_bf16 v[32:35], v[184:187], v[200:203], v[32:35]
	v_mfma_f32_16x16x32_bf16 v[20:23], v[172:175], v[208:211], v[20:23]
	v_mfma_f32_16x16x32_bf16 v[16:19], v[184:187], v[208:211], v[16:19]
	v_mfma_f32_16x16x32_bf16 v[4:7], v[172:175], v[216:219], v[4:7]
	v_mfma_f32_16x16x32_bf16 v[0:3], v[184:187], v[216:219], v[0:3]
	v_mfma_f32_16x16x32_bf16 v[52:55], v[180:183], v[196:199], v[52:55]
	v_mfma_f32_16x16x32_bf16 v[48:51], v[188:191], v[196:199], v[48:51]
	v_mfma_f32_16x16x32_bf16 v[36:39], v[180:183], v[204:207], v[36:39]
	v_mfma_f32_16x16x32_bf16 v[32:35], v[188:191], v[204:207], v[32:35]
	v_mfma_f32_16x16x32_bf16 v[20:23], v[180:183], v[212:215], v[20:23]
	v_mfma_f32_16x16x32_bf16 v[16:19], v[188:191], v[212:215], v[16:19]
	s_setprio 2
	s_barrier
	v_mfma_f32_16x16x32_bf16 v[4:7], v[180:183], v[220:223], v[4:7]
	v_mfma_f32_16x16x32_bf16 v[0:3], v[188:191], v[220:223], v[0:3]
	s_setprio 0
	s_cbranch_scc0 .LBB0_1236
	v_readlane_b32 s80, v244, 16
	s_and_b64 vcc, exec, s[10:11]
	v_readlane_b32 s81, v244, 17
	s_cbranch_vccz .LBB0_1239
	s_barrier

; #define PG8_STAGE(bufoff, gbase, voff) do { _Pragma("unroll") for (int _i = 0; _i < 2; ++_i) \
;         __builtin_amdgcn_global_load_lds((const unsigned*)((const char*)(gbase) + (voff)[_i]), (LAS unsigned*)(lds + (bufoff) + ldsw + _i * 8192), 16, 0, 0); } while (0)
; #define PG8_LDA(dst, b, h) do { _Pragma("unroll") for (int m = 0; m < 4; ++m) _Pragma("unroll") for (int k = 0; k < 2; ++k) dst[m][k] = *(const LAS bf16x8*)(lds + PG8_SA(b, h) + aoff + m * 2048 + k * 1024); } while (0)
; #define PG8_LDB(dst, b, h) do { _Pragma("unroll") for (int n = 0; n < 2; ++n) _Pragma("unroll") for (int k = 0; k < 2; ++k) dst[n][k] = *(const LAS bf16x8*)(lds + PG8_SB(b, h) + boff + n * 2048 + k * 1024); } while (0)
; #define PG8_MMA(ai, bj, At, Bt) do { __builtin_amdgcn_s_setprio(1); _Pragma("unroll") for (int m = 0; m < 4; ++m) _Pragma("unroll") for (int n = 0; n < 2; ++n) _Pragma("unroll") for (int k = 0; k < 2; ++k) \
;         acc[ai][bj][m][n] = __builtin_amdgcn_mfma_f32_16x16x32_bf16(Bt[n][k], At[m][k], acc[ai][bj][m][n], 0, 0, 0); __builtin_amdgcn_s_setprio(0); } while (0)
; #define PG8_WAIT_V(n) asm volatile("s_waitcnt vmcnt(" #n ")" ::: "memory")
; #define PG8_WAIT_L(n) asm volatile("s_waitcnt lgkmcnt(" #n ")" ::: "memory")
; #define PG8_BAR __builtin_amdgcn_s_barrier()
; #define PG8_SCHED __builtin_amdgcn_sched_barrier(0)
; template <class Epi, class Sched, bool ALIGN_EPI = true, bool SP2 = true>
; __device__ __forceinline__ void gemm_phase(LAS unsigned char* lds, const bf16_t* Ag, const bf16_t* Btg, const int K, const int lda, const int ldb, const Sched& S, const Epi& E) {
;     ...
;             const bool last = (t == nt - 2);
;             const char* a1 = cA + (size_t)(t + 1) * kstep;
;             const char* a2 = last ? nA : cA + (size_t)(t + 2) * kstep; const char* b2 = last ? nB : cB + (size_t)(t + 2) * kstep;
;             const char* a3 = a2 + kstep; const char* b3 = b2 + kstep;
;             if constexpr (SP2) {
;             PG8_LDB(B0, 0, 0); PG8_LDB(B1, 0, 1); PG8_SCHED; PG8_LDA(At, 0, 0); PG8_STAGE(PG8_SA(1, 1), a1 + hstepA, voffA);
;             PG8_WAIT_V(8); PG8_WAIT_L(0); PG8_BAR; PG8_MMA(0, 0, At, B0); PG8_MMA(0, 1, At, B1); PG8_BAR; PG8_SCHED;
;             PG8_LDA(At, 0, 1); PG8_STAGE(PG8_SB(0, 0), b2, voffB); PG8_STAGE(PG8_SB(0, 1), b2 + hstepB, voffB); PG8_STAGE(PG8_SA(0, 0), a2, voffA);
.LBB0_1369:
	ds_read_b128 v[152:155], v149
	ds_read_b128 v[156:159], v149 offset:1024
	ds_read_b128 v[160:163], v149 offset:2048
	ds_read_b128 v[168:171], v149 offset:3072
	ds_read_b128 v[172:175], v150
	ds_read_b128 v[180:183], v150 offset:1024
	ds_read_b128 v[184:187], v150 offset:2048
	ds_read_b128 v[188:191], v150 offset:3072
	s_add_u32 s26, s24, 0xfff80080
	s_addc_u32 s27, s25, -1
	s_cmp_eq_u32 s58, 28
	s_cselect_b32 s29, s52, s27
	s_cselect_b32 s28, s53, s26
	s_cselect_b32 s27, s54, s57
	s_cselect_b32 s26, s55, s56
	v_lshl_add_u64 v[146:147], s[24:25], 0, v[138:139]
	s_add_i32 m0, s34, 0xc000
	ds_read_b128 v[192:195], v151
	ds_read_b128 v[196:199], v151 offset:1024
	ds_read_b128 v[200:203], v151 offset:2048
	ds_read_b128 v[204:207], v151 offset:3072
	ds_read_b128 v[208:211], v151 offset:4096
	ds_read_b128 v[212:215], v151 offset:5120
	ds_read_b128 v[216:219], v151 offset:6144
	ds_read_b128 v[220:223], v151 offset:7168
	global_load_lds_dwordx4 v[146:147], off
	v_lshl_add_u64 v[146:147], s[24:25], 0, v[140:141]
	s_add_i32 m0, s34, 0xe000
	s_nop 0
	global_load_lds_dwordx4 v[146:147], off
	s_waitcnt vmcnt(8)
	s_waitcnt lgkmcnt(0)
	s_barrier
	s_setprio 1
	s_waitcnt lgkmcnt(0)
	v_mfma_f32_16x16x32_bf16 v[124:127], v[152:155], v[192:195], v[124:127]
	v_mfma_f32_16x16x32_bf16 v[120:123], v[160:163], v[192:195], v[120:123]
	v_mfma_f32_16x16x32_bf16 v[108:111], v[152:155], v[200:203], v[108:111]
	v_mfma_f32_16x16x32_bf16 v[104:107], v[160:163], v[200:203], v[104:107]
	v_mfma_f32_16x16x32_bf16 v[92:95], v[152:155], v[208:211], v[92:95]
	v_mfma_f32_16x16x32_bf16 v[88:91], v[160:163], v[208:211], v[88:91]
	v_mfma_f32_16x16x32_bf16 v[76:79], v[152:155], v[216:219], v[76:79]
	v_mfma_f32_16x16x32_bf16 v[72:75], v[160:163], v[216:219], v[72:75]
	v_mfma_f32_16x16x32_bf16 v[124:127], v[156:159], v[196:199], v[124:127]
	v_mfma_f32_16x16x32_bf16 v[120:123], v[168:171], v[196:199], v[120:123]
	v_mfma_f32_16x16x32_bf16 v[108:111], v[156:159], v[204:207], v[108:111]
	v_mfma_f32_16x16x32_bf16 v[104:107], v[168:171], v[204:207], v[104:107]
	v_mfma_f32_16x16x32_bf16 v[92:95], v[156:159], v[212:215], v[92:95]
	v_mfma_f32_16x16x32_bf16 v[88:91], v[168:171], v[212:215], v[88:91]
	v_mfma_f32_16x16x32_bf16 v[76:79], v[156:159], v[220:223], v[76:79]
	v_mfma_f32_16x16x32_bf16 v[72:75], v[168:171], v[220:223], v[72:75]
	s_setprio 0
	s_setprio 1
	v_mfma_f32_16x16x32_bf16 v[116:119], v[172:175], v[192:195], v[116:119]
	v_mfma_f32_16x16x32_bf16 v[112:115], v[184:187], v[192:195], v[112:115]
	v_mfma_f32_16x16x32_bf16 v[100:103], v[172:175], v[200:203], v[100:103]
	v_mfma_f32_16x16x32_bf16 v[96:99], v[184:187], v[200:203], v[96:99]
	v_mfma_f32_16x16x32_bf16 v[84:87], v[172:175], v[208:211], v[84:87]
	v_mfma_f32_16x16x32_bf16 v[80:83], v[184:187], v[208:211], v[80:83]
	v_mfma_f32_16x16x32_bf16 v[68:71], v[172:175], v[216:219], v[68:71]
	v_mfma_f32_16x16x32_bf16 v[64:67], v[184:187], v[216:219], v[64:67]
	v_mfma_f32_16x16x32_bf16 v[116:119], v[180:183], v[196:199], v[116:119]
	v_mfma_f32_16x16x32_bf16 v[112:115], v[188:191], v[196:199], v[112:115]
	v_mfma_f32_16x16x32_bf16 v[100:103], v[180:183], v[204:207], v[100:103]
	v_mfma_f32_16x16x32_bf16 v[96:99], v[188:191], v[204:207], v[96:99]
	v_mfma_f32_16x16x32_bf16 v[84:87], v[180:183], v[212:215], v[84:87]
	v_mfma_f32_16x16x32_bf16 v[80:83], v[188:191], v[212:215], v[80:83]
	s_setprio 2
	s_barrier
	v_mfma_f32_16x16x32_bf16 v[68:71], v[180:183], v[220:223], v[68:71]
	v_mfma_f32_16x16x32_bf16 v[64:67], v[188:191], v[220:223], v[64:67]
	s_setprio 0
	s_add_i32 s59, s43, s30
	v_lshl_add_u64 v[146:147], s[26:27], 0, v[132:133]
	s_mov_b32 m0, s59
	ds_read_b128 v[192:195], v151 offset:16384
	ds_read_b128 v[196:199], v151 offset:17408
	ds_read_b128 v[200:203], v151 offset:18432
	ds_read_b128 v[204:207], v151 offset:19456
	ds_read_b128 v[208:211], v151 offset:20480
	ds_read_b128 v[212:215], v151 offset:21504
	ds_read_b128 v[216:219], v151 offset:22528
	ds_read_b128 v[220:223], v151 offset:23552
	global_load_lds_dwordx4 v[146:147], off
	s_add_i32 m0, s59, 0x2000
	s_add_u32 s60, s26, 0x80000
	v_lshl_add_u64 v[164:165], s[26:27], 0, v[128:129]
	s_addc_u32 s61, s27, 0
	s_add_i32 s59, s44, s30
	global_load_lds_dwordx4 v[164:165], off
	v_lshl_add_u64 v[224:225], s[60:61], 0, v[132:133]
	s_mov_b32 m0, s59
	v_lshl_add_u64 v[226:227], s[28:29], 0, v[130:131]
	global_load_lds_dwordx4 v[224:225], off
	v_lshl_add_u64 v[224:225], s[60:61], 0, v[128:129]
	s_add_i32 m0, s59, 0x2000
	s_nop 0
	global_load_lds_dwordx4 v[224:225], off
	v_lshl_add_u64 v[224:225], s[28:29], 0, v[134:135]
	s_mov_b32 m0, s34
	s_nop 0
	global_load_lds_dwordx4 v[224:225], off
	s_mov_b32 m0, s35
	s_nop 0
	global_load_lds_dwordx4 v[226:227], off
	s_waitcnt vmcnt(8)
	s_waitcnt lgkmcnt(0)
	s_barrier
; #define PG8_STAGE(bufoff, gbase, voff) do { _Pragma("unroll") for (int _i = 0; _i < 2; ++_i) \
;         __builtin_amdgcn_global_load_lds((const unsigned*)((const char*)(gbase) + (voff)[_i]), (LAS unsigned*)(lds + (bufoff) + ldsw + _i * 8192), 16, 0, 0); } while (0)
; #define PG8_LDA(dst, b, h) do { _Pragma("unroll") for (int m = 0; m < 4; ++m) _Pragma("unroll") for (int k = 0; k < 2; ++k) dst[m][k] = *(const LAS bf16x8*)(lds + PG8_SA(b, h) + aoff + m * 2048 + k * 1024); } while (0)
; #define PG8_LDB(dst, b, h) do { _Pragma("unroll") for (int n = 0; n < 2; ++n) _Pragma("unroll") for (int k = 0; k < 2; ++k) dst[n][k] = *(const LAS bf16x8*)(lds + PG8_SB(b, h) + boff + n * 2048 + k * 1024); } while (0)
; #define PG8_MMA(ai, bj, At, Bt) do { __builtin_amdgcn_s_setprio(1); _Pragma("unroll") for (int m = 0; m < 4; ++m) _Pragma("unroll") for (int n = 0; n < 2; ++n) _Pragma("unroll") for (int k = 0; k < 2; ++k) \
;         acc[ai][bj][m][n] = __builtin_amdgcn_mfma_f32_16x16x32_bf16(Bt[n][k], At[m][k], acc[ai][bj][m][n], 0, 0, 0); __builtin_amdgcn_s_setprio(0); } while (0)
; #define PG8_WAIT_V(n) asm volatile("s_waitcnt vmcnt(" #n ")" ::: "memory")
; #define PG8_WAIT_L(n) asm volatile("s_waitcnt lgkmcnt(" #n ")" ::: "memory")
; #define PG8_BAR __builtin_amdgcn_s_barrier()
; #define PG8_SCHED __builtin_amdgcn_sched_barrier(0)
; template <class Epi, class Sched, bool ALIGN_EPI = true, bool SP2 = true>
; __device__ __forceinline__ void gemm_phase(LAS unsigned char* lds, const bf16_t* Ag, const bf16_t* Btg, const int K, const int lda, const int ldb, const Sched& S, const Epi& E) {
;     ...
;             PG8_WAIT_V(8); PG8_WAIT_L(0); PG8_BAR; PG8_MMA(1, 0, At, B0); PG8_MMA(1, 1, At, B1); PG8_BAR; PG8_SCHED;
;             PG8_LDB(B0, 1, 0); PG8_LDB(B1, 1, 1); PG8_SCHED; PG8_LDA(At, 1, 0); PG8_STAGE(PG8_SA(0, 1), a2 + hstepA, voffA);
;             PG8_WAIT_V(8); PG8_WAIT_L(0); PG8_BAR; PG8_MMA(0, 0, At, B0); PG8_MMA(0, 1, At, B1); PG8_BAR; PG8_SCHED;
	s_setprio 1
	s_waitcnt lgkmcnt(0)
	v_mfma_f32_16x16x32_bf16 v[60:63], v[152:155], v[192:195], v[60:63]
	v_mfma_f32_16x16x32_bf16 v[56:59], v[160:163], v[192:195], v[56:59]
	v_mfma_f32_16x16x32_bf16 v[44:47], v[152:155], v[200:203], v[44:47]
	v_mfma_f32_16x16x32_bf16 v[40:43], v[160:163], v[200:203], v[40:43]
	v_mfma_f32_16x16x32_bf16 v[28:31], v[152:155], v[208:211], v[28:31]
	v_mfma_f32_16x16x32_bf16 v[24:27], v[160:163], v[208:211], v[24:27]
	v_mfma_f32_16x16x32_bf16 v[12:15], v[152:155], v[216:219], v[12:15]
	v_mfma_f32_16x16x32_bf16 v[8:11], v[160:163], v[216:219], v[8:11]
	v_mfma_f32_16x16x32_bf16 v[60:63], v[156:159], v[196:199], v[60:63]
	v_mfma_f32_16x16x32_bf16 v[56:59], v[168:171], v[196:199], v[56:59]
	v_mfma_f32_16x16x32_bf16 v[44:47], v[156:159], v[204:207], v[44:47]
	v_mfma_f32_16x16x32_bf16 v[40:43], v[168:171], v[204:207], v[40:43]
	v_mfma_f32_16x16x32_bf16 v[28:31], v[156:159], v[212:215], v[28:31]
	v_mfma_f32_16x16x32_bf16 v[24:27], v[168:171], v[212:215], v[24:27]
	v_mfma_f32_16x16x32_bf16 v[12:15], v[156:159], v[220:223], v[12:15]
	v_mfma_f32_16x16x32_bf16 v[8:11], v[168:171], v[220:223], v[8:11]
	s_setprio 0
	s_setprio 1
	v_mfma_f32_16x16x32_bf16 v[52:55], v[172:175], v[192:195], v[52:55]
	v_mfma_f32_16x16x32_bf16 v[48:51], v[184:187], v[192:195], v[48:51]
	v_mfma_f32_16x16x32_bf16 v[36:39], v[172:175], v[200:203], v[36:39]
	v_mfma_f32_16x16x32_bf16 v[32:35], v[184:187], v[200:203], v[32:35]
	v_mfma_f32_16x16x32_bf16 v[20:23], v[172:175], v[208:211], v[20:23]
	v_mfma_f32_16x16x32_bf16 v[16:19], v[184:187], v[208:211], v[16:19]
	v_mfma_f32_16x16x32_bf16 v[4:7], v[172:175], v[216:219], v[4:7]
	v_mfma_f32_16x16x32_bf16 v[0:3], v[184:187], v[216:219], v[0:3]
	v_mfma_f32_16x16x32_bf16 v[52:55], v[180:183], v[196:199], v[52:55]
	v_mfma_f32_16x16x32_bf16 v[48:51], v[188:191], v[196:199], v[48:51]
	v_mfma_f32_16x16x32_bf16 v[36:39], v[180:183], v[204:207], v[36:39]
	v_mfma_f32_16x16x32_bf16 v[32:35], v[188:191], v[204:207], v[32:35]
	v_mfma_f32_16x16x32_bf16 v[20:23], v[180:183], v[212:215], v[20:23]
	v_mfma_f32_16x16x32_bf16 v[16:19], v[188:191], v[212:215], v[16:19]
	s_setprio 2
	s_barrier
	v_mfma_f32_16x16x32_bf16 v[4:7], v[180:183], v[220:223], v[4:7]
	v_mfma_f32_16x16x32_bf16 v[0:3], v[188:191], v[220:223], v[0:3]
	s_setprio 0
	s_add_i32 s59, 0, 0x18000
	v_add_u32_e32 v167, s59, v148
	s_add_i32 s60, 0, 0x1c000
	ds_read_b128 v[152:155], v167
	ds_read_b128 v[156:159], v167 offset:1024
	ds_read_b128 v[160:163], v167 offset:2048
	ds_read_b128 v[168:171], v167 offset:3072
	v_add_u32_e32 v167, s60, v148
	ds_read_b128 v[172:175], v167
	ds_read_b128 v[180:183], v167 offset:1024
	ds_read_b128 v[184:187], v167 offset:2048
	ds_read_b128 v[188:191], v167 offset:3072
	s_add_u32 s28, s28, 0x80000
	s_addc_u32 s29, s29, 0
	s_mov_b32 m0, s37
	v_lshl_add_u64 v[228:229], s[28:29], 0, v[134:135]
	ds_read_b128 v[192:195], v151 offset:32768
	ds_read_b128 v[196:199], v151 offset:33792
	ds_read_b128 v[200:203], v151 offset:34816
	ds_read_b128 v[204:207], v151 offset:35840
	ds_read_b128 v[208:211], v151 offset:36864
	ds_read_b128 v[212:215], v151 offset:37888
	ds_read_b128 v[216:219], v151 offset:38912
	ds_read_b128 v[220:223], v151 offset:39936
	global_load_lds_dwordx4 v[228:229], off
	v_lshl_add_u64 v[228:229], s[28:29], 0, v[130:131]
	s_mov_b32 m0, s38
	s_nop 0
	global_load_lds_dwordx4 v[228:229], off
	s_waitcnt vmcnt(8)
	s_waitcnt lgkmcnt(0)
	s_barrier
	s_setprio 1
	s_waitcnt lgkmcnt(0)
	v_mfma_f32_16x16x32_bf16 v[124:127], v[152:155], v[192:195], v[124:127]
	v_mfma_f32_16x16x32_bf16 v[120:123], v[160:163], v[192:195], v[120:123]
	v_mfma_f32_16x16x32_bf16 v[108:111], v[152:155], v[200:203], v[108:111]
	v_mfma_f32_16x16x32_bf16 v[104:107], v[160:163], v[200:203], v[104:107]
	v_mfma_f32_16x16x32_bf16 v[92:95], v[152:155], v[208:211], v[92:95]
	v_mfma_f32_16x16x32_bf16 v[88:91], v[160:163], v[208:211], v[88:91]
	v_mfma_f32_16x16x32_bf16 v[76:79], v[152:155], v[216:219], v[76:79]
	v_mfma_f32_16x16x32_bf16 v[72:75], v[160:163], v[216:219], v[72:75]
	v_mfma_f32_16x16x32_bf16 v[124:127], v[156:159], v[196:199], v[124:127]
	v_mfma_f32_16x16x32_bf16 v[120:123], v[168:171], v[196:199], v[120:123]
	v_mfma_f32_16x16x32_bf16 v[108:111], v[156:159], v[204:207], v[108:111]
	v_mfma_f32_16x16x32_bf16 v[104:107], v[168:171], v[204:207], v[104:107]
	v_mfma_f32_16x16x32_bf16 v[92:95], v[156:159], v[212:215], v[92:95]
	v_mfma_f32_16x16x32_bf16 v[88:91], v[168:171], v[212:215], v[88:91]
	v_mfma_f32_16x16x32_bf16 v[76:79], v[156:159], v[220:223], v[76:79]
	v_mfma_f32_16x16x32_bf16 v[72:75], v[168:171], v[220:223], v[72:75]
	s_setprio 0
	s_setprio 1
	v_mfma_f32_16x16x32_bf16 v[116:119], v[172:175], v[192:195], v[116:119]
	v_mfma_f32_16x16x32_bf16 v[112:115], v[184:187], v[192:195], v[112:115]
	v_mfma_f32_16x16x32_bf16 v[100:103], v[172:175], v[200:203], v[100:103]
	v_mfma_f32_16x16x32_bf16 v[96:99], v[184:187], v[200:203], v[96:99]
	v_mfma_f32_16x16x32_bf16 v[84:87], v[172:175], v[208:211], v[84:87]
	v_mfma_f32_16x16x32_bf16 v[80:83], v[184:187], v[208:211], v[80:83]
	v_mfma_f32_16x16x32_bf16 v[68:71], v[172:175], v[216:219], v[68:71]
	v_mfma_f32_16x16x32_bf16 v[64:67], v[184:187], v[216:219], v[64:67]
	v_mfma_f32_16x16x32_bf16 v[116:119], v[180:183], v[196:199], v[116:119]
	v_mfma_f32_16x16x32_bf16 v[112:115], v[188:191], v[196:199], v[112:115]
	v_mfma_f32_16x16x32_bf16 v[100:103], v[180:183], v[204:207], v[100:103]
	v_mfma_f32_16x16x32_bf16 v[96:99], v[188:191], v[204:207], v[96:99]
	v_mfma_f32_16x16x32_bf16 v[84:87], v[180:183], v[212:215], v[84:87]
	v_mfma_f32_16x16x32_bf16 v[80:83], v[188:191], v[212:215], v[80:83]
	s_setprio 2
	s_barrier
; #define PG8_STAGE(bufoff, gbase, voff) do { _Pragma("unroll") for (int _i = 0; _i < 2; ++_i) \
;         __builtin_amdgcn_global_load_lds((const unsigned*)((const char*)(gbase) + (voff)[_i]), (LAS unsigned*)(lds + (bufoff) + ldsw + _i * 8192), 16, 0, 0); } while (0)
; #define PG8_LDA(dst, b, h) do { _Pragma("unroll") for (int m = 0; m < 4; ++m) _Pragma("unroll") for (int k = 0; k < 2; ++k) dst[m][k] = *(const LAS bf16x8*)(lds + PG8_SA(b, h) + aoff + m * 2048 + k * 1024); } while (0)
; #define PG8_MMA(ai, bj, At, Bt) do { __builtin_amdgcn_s_setprio(1); _Pragma("unroll") for (int m = 0; m < 4; ++m) _Pragma("unroll") for (int n = 0; n < 2; ++n) _Pragma("unroll") for (int k = 0; k < 2; ++k) \
;         acc[ai][bj][m][n] = __builtin_amdgcn_mfma_f32_16x16x32_bf16(Bt[n][k], At[m][k], acc[ai][bj][m][n], 0, 0, 0); __builtin_amdgcn_s_setprio(0); } while (0)
; #define PG8_WAIT_V(n) asm volatile("s_waitcnt vmcnt(" #n ")" ::: "memory")
; #define PG8_WAIT_L(n) asm volatile("s_waitcnt lgkmcnt(" #n ")" ::: "memory")
; #define PG8_BAR __builtin_amdgcn_s_barrier()
; #define PG8_SCHED __builtin_amdgcn_sched_barrier(0)
; template <class Epi, class Sched, bool ALIGN_EPI = true, bool SP2 = true>
; __device__ __forceinline__ void gemm_phase(LAS unsigned char* lds, const bf16_t* Ag, const bf16_t* Btg, const int K, const int lda, const int ldb, const Sched& S, const Epi& E) {
;     ...
;         for (int t = 0; t < nt; t += 2) {
;             const bool last = (t == nt - 2);
;     ...
;             PG8_LDA(At, 1, 1); PG8_STAGE(PG8_SB(1, 0), b3, voffB); PG8_STAGE(PG8_SB(1, 1), b3 + hstepB, voffB); PG8_STAGE(PG8_SA(1, 0), a3, voffA);
;             PG8_WAIT_V(8); PG8_WAIT_L(0); PG8_BAR; PG8_MMA(1, 0, At, B0); PG8_MMA(1, 1, At, B1); PG8_BAR; PG8_SCHED;
	v_mfma_f32_16x16x32_bf16 v[68:71], v[180:183], v[220:223], v[68:71]
	v_mfma_f32_16x16x32_bf16 v[64:67], v[188:191], v[220:223], v[64:67]
	s_setprio 0
	s_add_i32 s28, s59, s30
	v_lshl_add_u64 v[146:147], v[146:147], 0, s[8:9]
	s_mov_b32 m0, s28
	ds_read_b128 v[192:195], v151 offset:49152
	ds_read_b128 v[196:199], v151 offset:50176
	ds_read_b128 v[200:203], v151 offset:51200
	ds_read_b128 v[204:207], v151 offset:52224
	ds_read_b128 v[208:211], v151 offset:53248
	ds_read_b128 v[212:215], v151 offset:54272
	ds_read_b128 v[216:219], v151 offset:55296
	ds_read_b128 v[220:223], v151 offset:56320
	global_load_lds_dwordx4 v[146:147], off
	s_add_i32 m0, s28, 0x2000
	s_add_u32 s26, s26, 0x80080
	v_lshl_add_u64 v[146:147], v[164:165], 0, s[8:9]
	s_addc_u32 s27, s27, 0
	s_add_i32 s28, s60, s30
	global_load_lds_dwordx4 v[146:147], off
	v_lshl_add_u64 v[146:147], s[26:27], 0, v[132:133]
	s_mov_b32 m0, s28
	s_nop 0
	global_load_lds_dwordx4 v[146:147], off
	v_lshl_add_u64 v[146:147], s[26:27], 0, v[128:129]
	s_add_i32 m0, s28, 0x2000
	s_nop 0
	global_load_lds_dwordx4 v[146:147], off
	v_lshl_add_u64 v[146:147], v[224:225], 0, s[8:9]
	s_mov_b32 m0, s39
	s_nop 0
	global_load_lds_dwordx4 v[146:147], off
	v_lshl_add_u64 v[146:147], v[226:227], 0, s[8:9]
	s_mov_b32 m0, s40
	s_nop 0
	global_load_lds_dwordx4 v[146:147], off
	s_waitcnt vmcnt(8)
	s_waitcnt lgkmcnt(0)
	s_barrier
	s_setprio 1
	s_waitcnt lgkmcnt(0)
	v_mfma_f32_16x16x32_bf16 v[60:63], v[152:155], v[192:195], v[60:63]
	s_add_i32 s58, s58, 2
	s_add_u32 s24, s24, 0x100
	s_addc_u32 s25, s25, 0
	s_add_u32 s56, s56, 0x100
	s_addc_u32 s57, s57, 0
	s_cmp_gt_u32 s58, 29
	v_mfma_f32_16x16x32_bf16 v[56:59], v[160:163], v[192:195], v[56:59]
	v_mfma_f32_16x16x32_bf16 v[44:47], v[152:155], v[200:203], v[44:47]
	v_mfma_f32_16x16x32_bf16 v[40:43], v[160:163], v[200:203], v[40:43]
	v_mfma_f32_16x16x32_bf16 v[28:31], v[152:155], v[208:211], v[28:31]
	v_mfma_f32_16x16x32_bf16 v[24:27], v[160:163], v[208:211], v[24:27]
	v_mfma_f32_16x16x32_bf16 v[12:15], v[152:155], v[216:219], v[12:15]
	v_mfma_f32_16x16x32_bf16 v[8:11], v[160:163], v[216:219], v[8:11]
	v_mfma_f32_16x16x32_bf16 v[60:63], v[156:159], v[196:199], v[60:63]
	v_mfma_f32_16x16x32_bf16 v[56:59], v[168:171], v[196:199], v[56:59]
	v_mfma_f32_16x16x32_bf16 v[44:47], v[156:159], v[204:207], v[44:47]
	v_mfma_f32_16x16x32_bf16 v[40:43], v[168:171], v[204:207], v[40:43]
	v_mfma_f32_16x16x32_bf16 v[28:31], v[156:159], v[212:215], v[28:31]
	v_mfma_f32_16x16x32_bf16 v[24:27], v[168:171], v[212:215], v[24:27]
	v_mfma_f32_16x16x32_bf16 v[12:15], v[156:159], v[220:223], v[12:15]
	v_mfma_f32_16x16x32_bf16 v[8:11], v[168:171], v[220:223], v[8:11]
	s_setprio 0
	s_setprio 1
	v_mfma_f32_16x16x32_bf16 v[52:55], v[172:175], v[192:195], v[52:55]
	v_mfma_f32_16x16x32_bf16 v[48:51], v[184:187], v[192:195], v[48:51]
	v_mfma_f32_16x16x32_bf16 v[36:39], v[172:175], v[200:203], v[36:39]
	v_mfma_f32_16x16x32_bf16 v[32:35], v[184:187], v[200:203], v[32:35]
	v_mfma_f32_16x16x32_bf16 v[20:23], v[172:175], v[208:211], v[20:23]
	v_mfma_f32_16x16x32_bf16 v[16:19], v[184:187], v[208:211], v[16:19]
	v_mfma_f32_16x16x32_bf16 v[4:7], v[172:175], v[216:219], v[4:7]
	v_mfma_f32_16x16x32_bf16 v[0:3], v[184:187], v[216:219], v[0:3]
	v_mfma_f32_16x16x32_bf16 v[52:55], v[180:183], v[196:199], v[52:55]
	v_mfma_f32_16x16x32_bf16 v[48:51], v[188:191], v[196:199], v[48:51]
	v_mfma_f32_16x16x32_bf16 v[36:39], v[180:183], v[204:207], v[36:39]
	v_mfma_f32_16x16x32_bf16 v[32:35], v[188:191], v[204:207], v[32:35]
	v_mfma_f32_16x16x32_bf16 v[20:23], v[180:183], v[212:215], v[20:23]
	v_mfma_f32_16x16x32_bf16 v[16:19], v[188:191], v[212:215], v[16:19]
	s_setprio 2
	s_barrier
	v_mfma_f32_16x16x32_bf16 v[4:7], v[180:183], v[220:223], v[4:7]
	v_mfma_f32_16x16x32_bf16 v[0:3], v[188:191], v[220:223], v[0:3]
	s_setprio 0
	s_cbranch_scc0 .LBB0_1369
	s_and_b64 vcc, exec, s[10:11]
	s_cbranch_vccz .LBB0_1372
	s_barrier

; #define PG8_STAGE(bufoff, gbase, voff) do { _Pragma("unroll") for (int _i = 0; _i < 2; ++_i) \
;         __builtin_amdgcn_global_load_lds((const unsigned*)((const char*)(gbase) + (voff)[_i]), (LAS unsigned*)(lds + (bufoff) + ldsw + _i * 8192), 16, 0, 0); } while (0)
; #define PG8_LDA(dst, b, h) do { _Pragma("unroll") for (int m = 0; m < 4; ++m) _Pragma("unroll") for (int k = 0; k < 2; ++k) dst[m][k] = *(const LAS bf16x8*)(lds + PG8_SA(b, h) + aoff + m * 2048 + k * 1024); } while (0)
; #define PG8_LDB(dst, b, h) do { _Pragma("unroll") for (int n = 0; n < 2; ++n) _Pragma("unroll") for (int k = 0; k < 2; ++k) dst[n][k] = *(const LAS bf16x8*)(lds + PG8_SB(b, h) + boff + n * 2048 + k * 1024); } while (0)
; #define PG8_MMA(ai, bj, At, Bt) do { __builtin_amdgcn_s_setprio(1); _Pragma("unroll") for (int m = 0; m < 4; ++m) _Pragma("unroll") for (int n = 0; n < 2; ++n) _Pragma("unroll") for (int k = 0; k < 2; ++k) \
;         acc[ai][bj][m][n] = __builtin_amdgcn_mfma_f32_16x16x32_bf16(Bt[n][k], At[m][k], acc[ai][bj][m][n], 0, 0, 0); __builtin_amdgcn_s_setprio(0); } while (0)
; #define PG8_WAIT_V(n) asm volatile("s_waitcnt vmcnt(" #n ")" ::: "memory")
; #define PG8_WAIT_L(n) asm volatile("s_waitcnt lgkmcnt(" #n ")" ::: "memory")
; #define PG8_BAR __builtin_amdgcn_s_barrier()
; #define PG8_SCHED __builtin_amdgcn_sched_barrier(0)
; template <class Epi, class Sched, bool ALIGN_EPI = true, bool SP2 = true>
; __device__ __forceinline__ void gemm_phase(LAS unsigned char* lds, const bf16_t* Ag, const bf16_t* Btg, const int K, const int lda, const int ldb, const Sched& S, const Epi& E) {
;     ...
;             const bool last = (t == nt - 2);
;             const char* a1 = cA + (size_t)(t + 1) * kstep;
;             const char* a2 = last ? nA : cA + (size_t)(t + 2) * kstep; const char* b2 = last ? nB : cB + (size_t)(t + 2) * kstep;
;             const char* a3 = a2 + kstep; const char* b3 = b2 + kstep;
;             if constexpr (SP2) {
;             PG8_LDB(B0, 0, 0); PG8_LDB(B1, 0, 1); PG8_SCHED; PG8_LDA(At, 0, 0); PG8_STAGE(PG8_SA(1, 1), a1 + hstepA, voffA);
;             PG8_WAIT_V(8); PG8_WAIT_L(0); PG8_BAR; PG8_MMA(0, 0, At, B0); PG8_MMA(0, 1, At, B1); PG8_BAR; PG8_SCHED;
;             PG8_LDA(At, 0, 1); PG8_STAGE(PG8_SB(0, 0), b2, voffB); PG8_STAGE(PG8_SB(0, 1), b2 + hstepB, voffB); PG8_STAGE(PG8_SA(0, 0), a2, voffA);
.LBB0_1448:
	ds_read_b128 v[152:155], v149
	ds_read_b128 v[156:159], v149 offset:1024
	ds_read_b128 v[160:163], v149 offset:2048
	ds_read_b128 v[164:167], v149 offset:3072
	ds_read_b128 v[168:171], v150
	ds_read_b128 v[172:175], v150 offset:1024
	ds_read_b128 v[178:181], v150 offset:2048
	ds_read_b128 v[182:185], v150 offset:3072
	s_add_u32 s54, s52, 0xffea0080
	s_addc_u32 s55, s53, -1
	s_cmpk_eq_i32 s79, 0x54
	s_cselect_b32 s57, s33, s55
	s_cselect_b32 s56, s74, s54
	s_cselect_b32 s55, s75, s78
	s_cselect_b32 s54, s76, s77
	v_lshl_add_u64 v[146:147], s[52:53], 0, v[138:139]
	s_add_i32 m0, s41, 0xc000
	ds_read_b128 v[186:189], v151
	ds_read_b128 v[190:193], v151 offset:1024
	ds_read_b128 v[194:197], v151 offset:2048
	ds_read_b128 v[198:201], v151 offset:3072
	ds_read_b128 v[202:205], v151 offset:4096
	ds_read_b128 v[206:209], v151 offset:5120
	ds_read_b128 v[210:213], v151 offset:6144
	ds_read_b128 v[214:217], v151 offset:7168
	global_load_lds_dwordx4 v[146:147], off
	v_lshl_add_u64 v[146:147], s[52:53], 0, v[140:141]
	s_add_i32 m0, s41, 0xe000
	s_nop 0
	global_load_lds_dwordx4 v[146:147], off
	s_waitcnt vmcnt(8)
	s_waitcnt lgkmcnt(0)
	s_barrier
	s_setprio 1
	s_waitcnt lgkmcnt(0)
	v_mfma_f32_16x16x32_bf16 v[124:127], v[152:155], v[186:189], v[124:127]
	v_mfma_f32_16x16x32_bf16 v[120:123], v[160:163], v[186:189], v[120:123]
	v_mfma_f32_16x16x32_bf16 v[108:111], v[152:155], v[194:197], v[108:111]
	v_mfma_f32_16x16x32_bf16 v[104:107], v[160:163], v[194:197], v[104:107]
	v_mfma_f32_16x16x32_bf16 v[92:95], v[152:155], v[202:205], v[92:95]
	v_mfma_f32_16x16x32_bf16 v[88:91], v[160:163], v[202:205], v[88:91]
	v_mfma_f32_16x16x32_bf16 v[76:79], v[152:155], v[210:213], v[76:79]
	v_mfma_f32_16x16x32_bf16 v[72:75], v[160:163], v[210:213], v[72:75]
	v_mfma_f32_16x16x32_bf16 v[124:127], v[156:159], v[190:193], v[124:127]
	v_mfma_f32_16x16x32_bf16 v[120:123], v[164:167], v[190:193], v[120:123]
	v_mfma_f32_16x16x32_bf16 v[108:111], v[156:159], v[198:201], v[108:111]
	v_mfma_f32_16x16x32_bf16 v[104:107], v[164:167], v[198:201], v[104:107]
	v_mfma_f32_16x16x32_bf16 v[92:95], v[156:159], v[206:209], v[92:95]
	v_mfma_f32_16x16x32_bf16 v[88:91], v[164:167], v[206:209], v[88:91]
	v_mfma_f32_16x16x32_bf16 v[76:79], v[156:159], v[214:217], v[76:79]
	v_mfma_f32_16x16x32_bf16 v[72:75], v[164:167], v[214:217], v[72:75]
	s_setprio 0
	s_setprio 1
	v_mfma_f32_16x16x32_bf16 v[116:119], v[168:171], v[186:189], v[116:119]
	v_mfma_f32_16x16x32_bf16 v[112:115], v[178:181], v[186:189], v[112:115]
	v_mfma_f32_16x16x32_bf16 v[100:103], v[168:171], v[194:197], v[100:103]
	v_mfma_f32_16x16x32_bf16 v[96:99], v[178:181], v[194:197], v[96:99]
	v_mfma_f32_16x16x32_bf16 v[84:87], v[168:171], v[202:205], v[84:87]
	v_mfma_f32_16x16x32_bf16 v[80:83], v[178:181], v[202:205], v[80:83]
	v_mfma_f32_16x16x32_bf16 v[68:71], v[168:171], v[210:213], v[68:71]
	v_mfma_f32_16x16x32_bf16 v[64:67], v[178:181], v[210:213], v[64:67]
	v_mfma_f32_16x16x32_bf16 v[116:119], v[172:175], v[190:193], v[116:119]
	v_mfma_f32_16x16x32_bf16 v[112:115], v[182:185], v[190:193], v[112:115]
	v_mfma_f32_16x16x32_bf16 v[100:103], v[172:175], v[198:201], v[100:103]
	v_mfma_f32_16x16x32_bf16 v[96:99], v[182:185], v[198:201], v[96:99]
	v_mfma_f32_16x16x32_bf16 v[84:87], v[172:175], v[206:209], v[84:87]
	v_mfma_f32_16x16x32_bf16 v[80:83], v[182:185], v[206:209], v[80:83]
	s_setprio 2
	s_barrier
	v_mfma_f32_16x16x32_bf16 v[68:71], v[172:175], v[214:217], v[68:71]
	v_mfma_f32_16x16x32_bf16 v[64:67], v[182:185], v[214:217], v[64:67]
	s_setprio 0
	s_add_i32 s80, s66, s40
	v_lshl_add_u64 v[146:147], s[54:55], 0, v[130:131]
	s_mov_b32 m0, s80
	ds_read_b128 v[186:189], v151 offset:16384
	ds_read_b128 v[190:193], v151 offset:17408
	ds_read_b128 v[194:197], v151 offset:18432
	ds_read_b128 v[198:201], v151 offset:19456
	ds_read_b128 v[202:205], v151 offset:20480
	ds_read_b128 v[206:209], v151 offset:21504
	ds_read_b128 v[210:213], v151 offset:22528
	ds_read_b128 v[214:217], v151 offset:23552
	global_load_lds_dwordx4 v[146:147], off
	s_add_i32 m0, s80, 0x2000
	s_add_u32 s80, s54, 0x160000
	v_lshl_add_u64 v[218:219], s[54:55], 0, v[134:135]
	s_addc_u32 s81, s55, 0
	s_add_i32 s82, s67, s40
	global_load_lds_dwordx4 v[218:219], off
	v_lshl_add_u64 v[220:221], s[80:81], 0, v[130:131]
	s_mov_b32 m0, s82
	v_lshl_add_u64 v[222:223], s[56:57], 0, v[132:133]
	global_load_lds_dwordx4 v[220:221], off
	v_lshl_add_u64 v[220:221], s[80:81], 0, v[134:135]
	s_add_i32 m0, s82, 0x2000
	s_nop 0
	global_load_lds_dwordx4 v[220:221], off
	v_lshl_add_u64 v[220:221], s[56:57], 0, v[128:129]
	s_mov_b32 m0, s41
	s_nop 0
	global_load_lds_dwordx4 v[220:221], off
	s_mov_b32 m0, s58
	s_nop 0
	global_load_lds_dwordx4 v[222:223], off
	s_waitcnt vmcnt(8)
	s_waitcnt lgkmcnt(0)
	s_barrier
; #define PG8_STAGE(bufoff, gbase, voff) do { _Pragma("unroll") for (int _i = 0; _i < 2; ++_i) \
;         __builtin_amdgcn_global_load_lds((const unsigned*)((const char*)(gbase) + (voff)[_i]), (LAS unsigned*)(lds + (bufoff) + ldsw + _i * 8192), 16, 0, 0); } while (0)
; #define PG8_LDA(dst, b, h) do { _Pragma("unroll") for (int m = 0; m < 4; ++m) _Pragma("unroll") for (int k = 0; k < 2; ++k) dst[m][k] = *(const LAS bf16x8*)(lds + PG8_SA(b, h) + aoff + m * 2048 + k * 1024); } while (0)
; #define PG8_LDB(dst, b, h) do { _Pragma("unroll") for (int n = 0; n < 2; ++n) _Pragma("unroll") for (int k = 0; k < 2; ++k) dst[n][k] = *(const LAS bf16x8*)(lds + PG8_SB(b, h) + boff + n * 2048 + k * 1024); } while (0)
; #define PG8_MMA(ai, bj, At, Bt) do { __builtin_amdgcn_s_setprio(1); _Pragma("unroll") for (int m = 0; m < 4; ++m) _Pragma("unroll") for (int n = 0; n < 2; ++n) _Pragma("unroll") for (int k = 0; k < 2; ++k) \
;         acc[ai][bj][m][n] = __builtin_amdgcn_mfma_f32_16x16x32_bf16(Bt[n][k], At[m][k], acc[ai][bj][m][n], 0, 0, 0); __builtin_amdgcn_s_setprio(0); } while (0)
; #define PG8_WAIT_V(n) asm volatile("s_waitcnt vmcnt(" #n ")" ::: "memory")
; #define PG8_WAIT_L(n) asm volatile("s_waitcnt lgkmcnt(" #n ")" ::: "memory")
; #define PG8_BAR __builtin_amdgcn_s_barrier()
; #define PG8_SCHED __builtin_amdgcn_sched_barrier(0)
; template <class Epi, class Sched, bool ALIGN_EPI = true, bool SP2 = true>
; __device__ __forceinline__ void gemm_phase(LAS unsigned char* lds, const bf16_t* Ag, const bf16_t* Btg, const int K, const int lda, const int ldb, const Sched& S, const Epi& E) {
;     ...
;             PG8_WAIT_V(8); PG8_WAIT_L(0); PG8_BAR; PG8_MMA(1, 0, At, B0); PG8_MMA(1, 1, At, B1); PG8_BAR; PG8_SCHED;
;             PG8_LDB(B0, 1, 0); PG8_LDB(B1, 1, 1); PG8_SCHED; PG8_LDA(At, 1, 0); PG8_STAGE(PG8_SA(0, 1), a2 + hstepA, voffA);
;             PG8_WAIT_V(8); PG8_WAIT_L(0); PG8_BAR; PG8_MMA(0, 0, At, B0); PG8_MMA(0, 1, At, B1); PG8_BAR; PG8_SCHED;
	s_setprio 1
	s_waitcnt lgkmcnt(0)
	v_mfma_f32_16x16x32_bf16 v[60:63], v[152:155], v[186:189], v[60:63]
	v_mfma_f32_16x16x32_bf16 v[56:59], v[160:163], v[186:189], v[56:59]
	v_mfma_f32_16x16x32_bf16 v[44:47], v[152:155], v[194:197], v[44:47]
	v_mfma_f32_16x16x32_bf16 v[40:43], v[160:163], v[194:197], v[40:43]
	v_mfma_f32_16x16x32_bf16 v[28:31], v[152:155], v[202:205], v[28:31]
	v_mfma_f32_16x16x32_bf16 v[24:27], v[160:163], v[202:205], v[24:27]
	v_mfma_f32_16x16x32_bf16 v[12:15], v[152:155], v[210:213], v[12:15]
	v_mfma_f32_16x16x32_bf16 v[8:11], v[160:163], v[210:213], v[8:11]
	v_mfma_f32_16x16x32_bf16 v[60:63], v[156:159], v[190:193], v[60:63]
	v_mfma_f32_16x16x32_bf16 v[56:59], v[164:167], v[190:193], v[56:59]
	v_mfma_f32_16x16x32_bf16 v[44:47], v[156:159], v[198:201], v[44:47]
	v_mfma_f32_16x16x32_bf16 v[40:43], v[164:167], v[198:201], v[40:43]
	v_mfma_f32_16x16x32_bf16 v[28:31], v[156:159], v[206:209], v[28:31]
	v_mfma_f32_16x16x32_bf16 v[24:27], v[164:167], v[206:209], v[24:27]
	v_mfma_f32_16x16x32_bf16 v[12:15], v[156:159], v[214:217], v[12:15]
	v_mfma_f32_16x16x32_bf16 v[8:11], v[164:167], v[214:217], v[8:11]
	s_setprio 0
	s_setprio 1
	v_mfma_f32_16x16x32_bf16 v[52:55], v[168:171], v[186:189], v[52:55]
	v_mfma_f32_16x16x32_bf16 v[48:51], v[178:181], v[186:189], v[48:51]
	v_mfma_f32_16x16x32_bf16 v[36:39], v[168:171], v[194:197], v[36:39]
	v_mfma_f32_16x16x32_bf16 v[32:35], v[178:181], v[194:197], v[32:35]
	v_mfma_f32_16x16x32_bf16 v[20:23], v[168:171], v[202:205], v[20:23]
	v_mfma_f32_16x16x32_bf16 v[16:19], v[178:181], v[202:205], v[16:19]
	v_mfma_f32_16x16x32_bf16 v[4:7], v[168:171], v[210:213], v[4:7]
	v_mfma_f32_16x16x32_bf16 v[0:3], v[178:181], v[210:213], v[0:3]
	v_mfma_f32_16x16x32_bf16 v[52:55], v[172:175], v[190:193], v[52:55]
	v_mfma_f32_16x16x32_bf16 v[48:51], v[182:185], v[190:193], v[48:51]
	v_mfma_f32_16x16x32_bf16 v[36:39], v[172:175], v[198:201], v[36:39]
	v_mfma_f32_16x16x32_bf16 v[32:35], v[182:185], v[198:201], v[32:35]
	v_mfma_f32_16x16x32_bf16 v[20:23], v[172:175], v[206:209], v[20:23]
	v_mfma_f32_16x16x32_bf16 v[16:19], v[182:185], v[206:209], v[16:19]
	s_setprio 2
	s_barrier
	v_mfma_f32_16x16x32_bf16 v[4:7], v[172:175], v[214:217], v[4:7]
	v_mfma_f32_16x16x32_bf16 v[0:3], v[182:185], v[214:217], v[0:3]
	s_setprio 0
	s_add_i32 s80, 0, 0x18000
	s_add_i32 s81, 0, 0x1c000
	v_add_u32_e32 v164, s80, v148
	v_add_u32_e32 v177, s81, v148
	ds_read_b128 v[152:155], v164
	ds_read_b128 v[156:159], v164 offset:1024
	ds_read_b128 v[160:163], v164 offset:2048
	ds_read_b128 v[164:167], v164 offset:3072
	ds_read_b128 v[168:171], v177
	ds_read_b128 v[172:175], v177 offset:1024
	ds_read_b128 v[178:181], v177 offset:2048
	ds_read_b128 v[182:185], v177 offset:3072
	s_add_u32 s56, s56, 0x160000
	s_addc_u32 s57, s57, 0
	s_mov_b32 m0, s59
	v_lshl_add_u64 v[224:225], s[56:57], 0, v[128:129]
	ds_read_b128 v[186:189], v151 offset:32768
	ds_read_b128 v[190:193], v151 offset:33792
	ds_read_b128 v[194:197], v151 offset:34816
	ds_read_b128 v[198:201], v151 offset:35840
	ds_read_b128 v[202:205], v151 offset:36864
	ds_read_b128 v[206:209], v151 offset:37888
	ds_read_b128 v[210:213], v151 offset:38912
	ds_read_b128 v[214:217], v151 offset:39936
	global_load_lds_dwordx4 v[224:225], off
	v_lshl_add_u64 v[224:225], s[56:57], 0, v[132:133]
	s_mov_b32 m0, s60
	s_nop 0
	global_load_lds_dwordx4 v[224:225], off
	s_waitcnt vmcnt(8)
	s_waitcnt lgkmcnt(0)
	s_barrier
	s_setprio 1
	s_waitcnt lgkmcnt(0)
	v_mfma_f32_16x16x32_bf16 v[124:127], v[152:155], v[186:189], v[124:127]
	v_mfma_f32_16x16x32_bf16 v[120:123], v[160:163], v[186:189], v[120:123]
	v_mfma_f32_16x16x32_bf16 v[108:111], v[152:155], v[194:197], v[108:111]
	v_mfma_f32_16x16x32_bf16 v[104:107], v[160:163], v[194:197], v[104:107]
	v_mfma_f32_16x16x32_bf16 v[92:95], v[152:155], v[202:205], v[92:95]
	v_mfma_f32_16x16x32_bf16 v[88:91], v[160:163], v[202:205], v[88:91]
	v_mfma_f32_16x16x32_bf16 v[76:79], v[152:155], v[210:213], v[76:79]
	v_mfma_f32_16x16x32_bf16 v[72:75], v[160:163], v[210:213], v[72:75]
	v_mfma_f32_16x16x32_bf16 v[124:127], v[156:159], v[190:193], v[124:127]
	v_mfma_f32_16x16x32_bf16 v[120:123], v[164:167], v[190:193], v[120:123]
	v_mfma_f32_16x16x32_bf16 v[108:111], v[156:159], v[198:201], v[108:111]
	v_mfma_f32_16x16x32_bf16 v[104:107], v[164:167], v[198:201], v[104:107]
	v_mfma_f32_16x16x32_bf16 v[92:95], v[156:159], v[206:209], v[92:95]
	v_mfma_f32_16x16x32_bf16 v[88:91], v[164:167], v[206:209], v[88:91]
	v_mfma_f32_16x16x32_bf16 v[76:79], v[156:159], v[214:217], v[76:79]
	v_mfma_f32_16x16x32_bf16 v[72:75], v[164:167], v[214:217], v[72:75]
	s_setprio 0
	s_setprio 1
	v_mfma_f32_16x16x32_bf16 v[116:119], v[168:171], v[186:189], v[116:119]
	v_mfma_f32_16x16x32_bf16 v[112:115], v[178:181], v[186:189], v[112:115]
	v_mfma_f32_16x16x32_bf16 v[100:103], v[168:171], v[194:197], v[100:103]
	v_mfma_f32_16x16x32_bf16 v[96:99], v[178:181], v[194:197], v[96:99]
	v_mfma_f32_16x16x32_bf16 v[84:87], v[168:171], v[202:205], v[84:87]
	v_mfma_f32_16x16x32_bf16 v[80:83], v[178:181], v[202:205], v[80:83]
	v_mfma_f32_16x16x32_bf16 v[68:71], v[168:171], v[210:213], v[68:71]
	v_mfma_f32_16x16x32_bf16 v[64:67], v[178:181], v[210:213], v[64:67]
	v_mfma_f32_16x16x32_bf16 v[116:119], v[172:175], v[190:193], v[116:119]
	v_mfma_f32_16x16x32_bf16 v[112:115], v[182:185], v[190:193], v[112:115]
	v_mfma_f32_16x16x32_bf16 v[100:103], v[172:175], v[198:201], v[100:103]
	v_mfma_f32_16x16x32_bf16 v[96:99], v[182:185], v[198:201], v[96:99]
	v_mfma_f32_16x16x32_bf16 v[84:87], v[172:175], v[206:209], v[84:87]
	v_mfma_f32_16x16x32_bf16 v[80:83], v[182:185], v[206:209], v[80:83]
	s_setprio 2
	s_barrier
; #define PG8_STAGE(bufoff, gbase, voff) do { _Pragma("unroll") for (int _i = 0; _i < 2; ++_i) \
;         __builtin_amdgcn_global_load_lds((const unsigned*)((const char*)(gbase) + (voff)[_i]), (LAS unsigned*)(lds + (bufoff) + ldsw + _i * 8192), 16, 0, 0); } while (0)
; #define PG8_LDA(dst, b, h) do { _Pragma("unroll") for (int m = 0; m < 4; ++m) _Pragma("unroll") for (int k = 0; k < 2; ++k) dst[m][k] = *(const LAS bf16x8*)(lds + PG8_SA(b, h) + aoff + m * 2048 + k * 1024); } while (0)
; #define PG8_MMA(ai, bj, At, Bt) do { __builtin_amdgcn_s_setprio(1); _Pragma("unroll") for (int m = 0; m < 4; ++m) _Pragma("unroll") for (int n = 0; n < 2; ++n) _Pragma("unroll") for (int k = 0; k < 2; ++k) \
;         acc[ai][bj][m][n] = __builtin_amdgcn_mfma_f32_16x16x32_bf16(Bt[n][k], At[m][k], acc[ai][bj][m][n], 0, 0, 0); __builtin_amdgcn_s_setprio(0); } while (0)
; #define PG8_WAIT_V(n) asm volatile("s_waitcnt vmcnt(" #n ")" ::: "memory")
; #define PG8_WAIT_L(n) asm volatile("s_waitcnt lgkmcnt(" #n ")" ::: "memory")
; #define PG8_BAR __builtin_amdgcn_s_barrier()
; #define PG8_SCHED __builtin_amdgcn_sched_barrier(0)
; template <class Epi, class Sched, bool ALIGN_EPI = true, bool SP2 = true>
; __device__ __forceinline__ void gemm_phase(LAS unsigned char* lds, const bf16_t* Ag, const bf16_t* Btg, const int K, const int lda, const int ldb, const Sched& S, const Epi& E) {
;     ...
;         for (int t = 0; t < nt; t += 2) {
;             const bool last = (t == nt - 2);
;     ...
;             PG8_LDA(At, 1, 1); PG8_STAGE(PG8_SB(1, 0), b3, voffB); PG8_STAGE(PG8_SB(1, 1), b3 + hstepB, voffB); PG8_STAGE(PG8_SA(1, 0), a3, voffA);
;             PG8_WAIT_V(8); PG8_WAIT_L(0); PG8_BAR; PG8_MMA(1, 0, At, B0); PG8_MMA(1, 1, At, B1); PG8_BAR; PG8_SCHED;
	v_mfma_f32_16x16x32_bf16 v[68:71], v[172:175], v[214:217], v[68:71]
	v_mfma_f32_16x16x32_bf16 v[64:67], v[182:185], v[214:217], v[64:67]
	s_setprio 0
	s_add_i32 s56, s80, s40
	v_lshl_add_u64 v[146:147], v[146:147], 0, s[6:7]
	s_mov_b32 m0, s56
	ds_read_b128 v[186:189], v151 offset:49152
	ds_read_b128 v[190:193], v151 offset:50176
	ds_read_b128 v[194:197], v151 offset:51200
	ds_read_b128 v[198:201], v151 offset:52224
	ds_read_b128 v[202:205], v151 offset:53248
	ds_read_b128 v[206:209], v151 offset:54272
	ds_read_b128 v[210:213], v151 offset:55296
	ds_read_b128 v[214:217], v151 offset:56320
	global_load_lds_dwordx4 v[146:147], off
	s_add_i32 m0, s56, 0x2000
	s_add_u32 s54, s54, 0x160080
	v_lshl_add_u64 v[146:147], v[218:219], 0, s[6:7]
	s_addc_u32 s55, s55, 0
	s_add_i32 s56, s81, s40
	global_load_lds_dwordx4 v[146:147], off
	v_lshl_add_u64 v[146:147], s[54:55], 0, v[130:131]
	s_mov_b32 m0, s56
	s_nop 0
	global_load_lds_dwordx4 v[146:147], off
	v_lshl_add_u64 v[146:147], s[54:55], 0, v[134:135]
	s_add_i32 m0, s56, 0x2000
	s_nop 0
	global_load_lds_dwordx4 v[146:147], off
	v_lshl_add_u64 v[146:147], v[220:221], 0, s[6:7]
	s_mov_b32 m0, s62
	s_nop 0
	global_load_lds_dwordx4 v[146:147], off
	v_lshl_add_u64 v[146:147], v[222:223], 0, s[6:7]
	s_mov_b32 m0, s63
	s_nop 0
	global_load_lds_dwordx4 v[146:147], off
	s_waitcnt vmcnt(8)
	s_waitcnt lgkmcnt(0)
	s_barrier
	s_setprio 1
	s_waitcnt lgkmcnt(0)
	v_mfma_f32_16x16x32_bf16 v[60:63], v[152:155], v[186:189], v[60:63]
	s_add_i32 s79, s79, 2
	s_add_u32 s52, s52, 0x100
	s_addc_u32 s53, s53, 0
	s_add_u32 s77, s77, 0x100
	s_addc_u32 s78, s78, 0
	s_cmpk_gt_u32 s79, 0x55
	v_mfma_f32_16x16x32_bf16 v[56:59], v[160:163], v[186:189], v[56:59]
	v_mfma_f32_16x16x32_bf16 v[44:47], v[152:155], v[194:197], v[44:47]
	v_mfma_f32_16x16x32_bf16 v[40:43], v[160:163], v[194:197], v[40:43]
	v_mfma_f32_16x16x32_bf16 v[28:31], v[152:155], v[202:205], v[28:31]
	v_mfma_f32_16x16x32_bf16 v[24:27], v[160:163], v[202:205], v[24:27]
	v_mfma_f32_16x16x32_bf16 v[12:15], v[152:155], v[210:213], v[12:15]
	v_mfma_f32_16x16x32_bf16 v[8:11], v[160:163], v[210:213], v[8:11]
	v_mfma_f32_16x16x32_bf16 v[60:63], v[156:159], v[190:193], v[60:63]
	v_mfma_f32_16x16x32_bf16 v[56:59], v[164:167], v[190:193], v[56:59]
	v_mfma_f32_16x16x32_bf16 v[44:47], v[156:159], v[198:201], v[44:47]
	v_mfma_f32_16x16x32_bf16 v[40:43], v[164:167], v[198:201], v[40:43]
	v_mfma_f32_16x16x32_bf16 v[28:31], v[156:159], v[206:209], v[28:31]
	v_mfma_f32_16x16x32_bf16 v[24:27], v[164:167], v[206:209], v[24:27]
	v_mfma_f32_16x16x32_bf16 v[12:15], v[156:159], v[214:217], v[12:15]
	v_mfma_f32_16x16x32_bf16 v[8:11], v[164:167], v[214:217], v[8:11]
	s_setprio 0
	s_setprio 1
	v_mfma_f32_16x16x32_bf16 v[52:55], v[168:171], v[186:189], v[52:55]
	v_mfma_f32_16x16x32_bf16 v[48:51], v[178:181], v[186:189], v[48:51]
	v_mfma_f32_16x16x32_bf16 v[36:39], v[168:171], v[194:197], v[36:39]
	v_mfma_f32_16x16x32_bf16 v[32:35], v[178:181], v[194:197], v[32:35]
	v_mfma_f32_16x16x32_bf16 v[20:23], v[168:171], v[202:205], v[20:23]
	v_mfma_f32_16x16x32_bf16 v[16:19], v[178:181], v[202:205], v[16:19]
	v_mfma_f32_16x16x32_bf16 v[4:7], v[168:171], v[210:213], v[4:7]
	v_mfma_f32_16x16x32_bf16 v[0:3], v[178:181], v[210:213], v[0:3]
	v_mfma_f32_16x16x32_bf16 v[52:55], v[172:175], v[190:193], v[52:55]
	v_mfma_f32_16x16x32_bf16 v[48:51], v[182:185], v[190:193], v[48:51]
	v_mfma_f32_16x16x32_bf16 v[36:39], v[172:175], v[198:201], v[36:39]
	v_mfma_f32_16x16x32_bf16 v[32:35], v[182:185], v[198:201], v[32:35]
	v_mfma_f32_16x16x32_bf16 v[20:23], v[172:175], v[206:209], v[20:23]
	v_mfma_f32_16x16x32_bf16 v[16:19], v[182:185], v[206:209], v[16:19]
	s_setprio 2
	s_barrier
	v_mfma_f32_16x16x32_bf16 v[4:7], v[172:175], v[214:217], v[4:7]
	v_mfma_f32_16x16x32_bf16 v[0:3], v[182:185], v[214:217], v[0:3]
	s_setprio 0
	s_cbranch_scc0 .LBB0_1448
	s_and_b64 vcc, exec, s[8:9]
	s_cbranch_vccz .LBB0_1451
	s_barrier
